# K-loop flips inverted (loader raised) plus leading half raised at entry and before each epilogue
# baseline (speedup 1.0000x reference)
_Z6mk_fwd6Params:
	s_load_dwordx2 s[42:43], s[0:1], 0xe8
	s_add_u32 s8, s0, 0xe8
	v_and_b32_e32 v1, 0x3ff, v0
	s_addc_u32 s9, s1, 0
	v_readfirstlane_b32 s68, v1
	s_nop 3
	s_lshr_b32 s98, s68, 6
	s_cmp_lt_u32 s98, 4
	s_cbranch_scc0 .Lprio_static_done
	s_setprio 3

.LBB0_153:
	ds_read_b128 v[0:3], v145
	ds_read_b128 v[4:7], v145 offset:1024
	ds_read_b128 v[8:11], v145 offset:2048
	ds_read_b128 v[12:15], v145 offset:3072
	ds_read_b128 v[16:19], v146
	ds_read_b128 v[20:23], v146 offset:1024
	ds_read_b128 v[24:27], v146 offset:2048
	ds_read_b128 v[28:31], v146 offset:3072
	s_ashr_i32 s37, s36, 31
	s_lshl_b64 s[46:47], s[36:37], 17
	s_add_u32 s46, s44, s46
	s_addc_u32 s47, s45, s47
	s_and_b64 s[48:49], s[4:5], exec
	s_cselect_b32 s59, s47, s53
	s_cselect_b32 s58, s46, s52
	s_ashr_i32 s35, s34, 31
	s_lshl_b64 s[48:49], s[34:35], 17
	s_add_u32 s48, s60, s48
	s_addc_u32 s49, s61, s49
	s_and_b64 s[56:57], s[4:5], exec
	s_cselect_b32 s57, s49, s55
	s_cselect_b32 s56, s48, s54
	s_add_u32 s80, s52, 0x10080
	s_addc_u32 s81, s53, 0
	s_add_i32 s83, s51, 0xc000
	v_lshl_add_u64 v[64:65], s[80:81], 0, v[128:129]
	s_mov_b32 m0, s83
	s_add_i32 s35, s51, 0xe000
	ds_read_b128 v[32:35], v147
	ds_read_b128 v[36:39], v147 offset:1024
	ds_read_b128 v[40:43], v147 offset:2048
	ds_read_b128 v[44:47], v147 offset:3072
	ds_read_b128 v[48:51], v147 offset:4096
	ds_read_b128 v[52:55], v147 offset:5120
	ds_read_b128 v[56:59], v147 offset:6144
	ds_read_b128 v[60:63], v147 offset:7168
	global_load_lds_dwordx4 v[64:65], off
	v_lshl_add_u64 v[64:65], s[80:81], 0, v[132:133]
	s_mov_b32 m0, s35
	s_nop 0
	global_load_lds_dwordx4 v[64:65], off
	s_waitcnt vmcnt(8)
	s_waitcnt lgkmcnt(0)
	s_setprio 0
	s_barrier
	v_mfma_f32_16x16x32_bf16 v[64:67], v[0:3], v[32:35], 0
	v_mfma_f32_16x16x32_bf16 v[68:71], v[8:11], v[32:35], 0
	v_mfma_f32_16x16x32_bf16 v[72:75], v[0:3], v[40:43], 0
	v_mfma_f32_16x16x32_bf16 v[76:79], v[8:11], v[40:43], 0
	v_mfma_f32_16x16x32_bf16 v[80:83], v[0:3], v[48:51], 0
	v_mfma_f32_16x16x32_bf16 v[84:87], v[8:11], v[48:51], 0
	v_mfma_f32_16x16x32_bf16 v[88:91], v[0:3], v[56:59], 0
	v_mfma_f32_16x16x32_bf16 v[92:95], v[8:11], v[56:59], 0
	v_mfma_f32_16x16x32_bf16 v[64:67], v[4:7], v[36:39], v[64:67]
	v_mfma_f32_16x16x32_bf16 v[68:71], v[12:15], v[36:39], v[68:71]
	v_mfma_f32_16x16x32_bf16 v[72:75], v[4:7], v[44:47], v[72:75]
	v_mfma_f32_16x16x32_bf16 v[76:79], v[12:15], v[44:47], v[76:79]
	v_mfma_f32_16x16x32_bf16 v[80:83], v[4:7], v[52:55], v[80:83]
	v_mfma_f32_16x16x32_bf16 v[84:87], v[12:15], v[52:55], v[84:87]
	v_mfma_f32_16x16x32_bf16 v[88:91], v[4:7], v[60:63], v[88:91]
	v_mfma_f32_16x16x32_bf16 v[92:95], v[12:15], v[60:63], v[92:95]
	v_mfma_f32_16x16x32_bf16 v[96:99], v[16:19], v[32:35], 0
	v_mfma_f32_16x16x32_bf16 v[32:35], v[24:27], v[32:35], 0
	v_mfma_f32_16x16x32_bf16 v[96:99], v[20:23], v[36:39], v[96:99]
	v_mfma_f32_16x16x32_bf16 v[32:35], v[28:31], v[36:39], v[32:35]
	v_mfma_f32_16x16x32_bf16 v[36:39], v[16:19], v[40:43], 0
	v_mfma_f32_16x16x32_bf16 v[40:43], v[24:27], v[40:43], 0
	v_mfma_f32_16x16x32_bf16 v[36:39], v[20:23], v[44:47], v[36:39]
	v_mfma_f32_16x16x32_bf16 v[40:43], v[28:31], v[44:47], v[40:43]
	v_mfma_f32_16x16x32_bf16 v[44:47], v[16:19], v[48:51], 0
	v_mfma_f32_16x16x32_bf16 v[48:51], v[24:27], v[48:51], 0
	v_mfma_f32_16x16x32_bf16 v[44:47], v[20:23], v[52:55], v[44:47]
	v_mfma_f32_16x16x32_bf16 v[48:51], v[28:31], v[52:55], v[48:51]
	v_mfma_f32_16x16x32_bf16 v[52:55], v[16:19], v[56:59], 0
	v_mfma_f32_16x16x32_bf16 v[56:59], v[24:27], v[56:59], 0
	v_mfma_f32_16x16x32_bf16 v[52:55], v[20:23], v[60:63], v[52:55]
	v_mfma_f32_16x16x32_bf16 v[56:59], v[28:31], v[60:63], v[56:59]
	s_barrier
	s_setprio 1
	s_add_i32 s81, s72, s62
	v_lshl_add_u64 v[140:141], s[54:55], 0, v[130:131]
	s_add_i32 s37, s81, 0x2000
	v_lshl_add_u64 v[148:149], v[140:141], 0, s[18:19]
	s_mov_b32 m0, s81
	v_lshl_add_u64 v[212:213], s[54:55], 0, v[134:135]
	s_add_u32 s84, s54, 0x10100
	ds_read_b128 v[60:63], v147 offset:16384
	ds_read_b128 v[100:103], v147 offset:17408
	ds_read_b128 v[104:107], v147 offset:18432
	ds_read_b128 v[108:111], v147 offset:19456
	ds_read_b128 v[112:115], v147 offset:20480
	ds_read_b128 v[116:119], v147 offset:21504
	ds_read_b128 v[120:123], v147 offset:22528
	ds_read_b128 v[124:127], v147 offset:23552
	global_load_lds_dwordx4 v[148:149], off
	v_lshl_add_u64 v[148:149], v[212:213], 0, s[18:19]
	s_mov_b32 m0, s37
	s_addc_u32 s85, s55, 0
	s_add_i32 s79, s73, s62
	global_load_lds_dwordx4 v[148:149], off
	v_lshl_add_u64 v[148:149], s[84:85], 0, v[130:131]
	s_mov_b32 m0, s79
	s_add_i32 s80, s79, 0x2000
	global_load_lds_dwordx4 v[148:149], off
	v_lshl_add_u64 v[148:149], s[84:85], 0, v[134:135]
	s_mov_b32 m0, s80
	v_lshl_add_u64 v[214:215], s[52:53], 0, v[128:129]
	global_load_lds_dwordx4 v[148:149], off
	v_lshl_add_u64 v[148:149], v[214:215], 0, s[18:19]
	s_mov_b32 m0, s51
	v_lshl_add_u64 v[216:217], s[52:53], 0, v[132:133]
	global_load_lds_dwordx4 v[148:149], off
	v_lshl_add_u64 v[148:149], v[216:217], 0, s[18:19]
	s_mov_b32 m0, s63
	s_nop 0
	global_load_lds_dwordx4 v[148:149], off
	s_waitcnt vmcnt(8)
	s_waitcnt lgkmcnt(0)
	s_setprio 0
	s_barrier
	v_mfma_f32_16x16x32_bf16 v[148:151], v[0:3], v[60:63], 0
	v_mfma_f32_16x16x32_bf16 v[156:159], v[0:3], v[104:107], 0
	v_mfma_f32_16x16x32_bf16 v[164:167], v[0:3], v[112:115], 0
	v_mfma_f32_16x16x32_bf16 v[0:3], v[0:3], v[120:123], 0
	v_mfma_f32_16x16x32_bf16 v[148:151], v[4:7], v[100:103], v[148:151]
	v_mfma_f32_16x16x32_bf16 v[156:159], v[4:7], v[108:111], v[156:159]
	v_mfma_f32_16x16x32_bf16 v[164:167], v[4:7], v[116:119], v[164:167]
	v_mfma_f32_16x16x32_bf16 v[0:3], v[4:7], v[124:127], v[0:3]
	v_mfma_f32_16x16x32_bf16 v[4:7], v[8:11], v[120:123], 0
	v_mfma_f32_16x16x32_bf16 v[152:155], v[8:11], v[60:63], 0
	v_mfma_f32_16x16x32_bf16 v[160:163], v[8:11], v[104:107], 0
	v_mfma_f32_16x16x32_bf16 v[168:171], v[8:11], v[112:115], 0
	v_mfma_f32_16x16x32_bf16 v[4:7], v[12:15], v[124:127], v[4:7]
	v_mfma_f32_16x16x32_bf16 v[152:155], v[12:15], v[100:103], v[152:155]
	v_mfma_f32_16x16x32_bf16 v[160:163], v[12:15], v[108:111], v[160:163]
	v_mfma_f32_16x16x32_bf16 v[168:171], v[12:15], v[116:119], v[168:171]
	v_mfma_f32_16x16x32_bf16 v[8:11], v[16:19], v[60:63], 0
	v_mfma_f32_16x16x32_bf16 v[12:15], v[24:27], v[60:63], 0
	v_mfma_f32_16x16x32_bf16 v[8:11], v[20:23], v[100:103], v[8:11]
	v_mfma_f32_16x16x32_bf16 v[12:15], v[28:31], v[100:103], v[12:15]
	v_mfma_f32_16x16x32_bf16 v[60:63], v[16:19], v[104:107], 0
	v_mfma_f32_16x16x32_bf16 v[100:103], v[24:27], v[104:107], 0
	v_mfma_f32_16x16x32_bf16 v[104:107], v[16:19], v[112:115], 0
	v_mfma_f32_16x16x32_bf16 v[16:19], v[16:19], v[120:123], 0
	v_mfma_f32_16x16x32_bf16 v[60:63], v[20:23], v[108:111], v[60:63]
	v_mfma_f32_16x16x32_bf16 v[100:103], v[28:31], v[108:111], v[100:103]
	v_mfma_f32_16x16x32_bf16 v[104:107], v[20:23], v[116:119], v[104:107]
	v_mfma_f32_16x16x32_bf16 v[108:111], v[24:27], v[112:115], 0
	v_mfma_f32_16x16x32_bf16 v[16:19], v[20:23], v[124:127], v[16:19]
	v_mfma_f32_16x16x32_bf16 v[20:23], v[24:27], v[120:123], 0
	v_mfma_f32_16x16x32_bf16 v[108:111], v[28:31], v[116:119], v[108:111]
	v_mfma_f32_16x16x32_bf16 v[20:23], v[28:31], v[124:127], v[20:23]
	s_barrier
	s_setprio 1
	s_add_i32 s82, 0, 0x18000
	s_add_i32 s88, 0, 0x1c000
	v_add_u32_e32 v228, s82, v143
	v_add_u32_e32 v236, s88, v143
	ds_read_b128 v[24:27], v228
	ds_read_b128 v[28:31], v228 offset:1024
	ds_read_b128 v[112:115], v228 offset:2048
	ds_read_b128 v[116:119], v228 offset:3072
	ds_read_b128 v[120:123], v236
	ds_read_b128 v[124:127], v236 offset:1024
	ds_read_b128 v[172:175], v236 offset:2048
	ds_read_b128 v[176:179], v236 offset:3072
	s_add_u32 s84, s52, 0x10100
	s_addc_u32 s85, s53, 0
	s_mov_b32 m0, s64
	v_lshl_add_u64 v[218:219], s[84:85], 0, v[128:129]
	ds_read_b128 v[180:183], v147 offset:32768
	ds_read_b128 v[184:187], v147 offset:33792
	ds_read_b128 v[188:191], v147 offset:34816
	ds_read_b128 v[192:195], v147 offset:35840
	ds_read_b128 v[196:199], v147 offset:36864
	ds_read_b128 v[200:203], v147 offset:37888
	ds_read_b128 v[204:207], v147 offset:38912
	ds_read_b128 v[208:211], v147 offset:39936
	global_load_lds_dwordx4 v[218:219], off
	v_lshl_add_u64 v[218:219], s[84:85], 0, v[132:133]
	s_mov_b32 m0, s65
	s_nop 0
	global_load_lds_dwordx4 v[218:219], off
	s_waitcnt vmcnt(8)
	s_waitcnt lgkmcnt(0)
	s_setprio 0
	s_barrier
	v_mfma_f32_16x16x32_bf16 v[64:67], v[24:27], v[180:183], v[64:67]
	v_mfma_f32_16x16x32_bf16 v[68:71], v[112:115], v[180:183], v[68:71]
	v_mfma_f32_16x16x32_bf16 v[72:75], v[24:27], v[188:191], v[72:75]
	v_mfma_f32_16x16x32_bf16 v[76:79], v[112:115], v[188:191], v[76:79]
	v_mfma_f32_16x16x32_bf16 v[80:83], v[24:27], v[196:199], v[80:83]
	v_mfma_f32_16x16x32_bf16 v[84:87], v[112:115], v[196:199], v[84:87]
	v_mfma_f32_16x16x32_bf16 v[88:91], v[24:27], v[204:207], v[88:91]
	v_mfma_f32_16x16x32_bf16 v[92:95], v[112:115], v[204:207], v[92:95]
	v_mfma_f32_16x16x32_bf16 v[64:67], v[28:31], v[184:187], v[64:67]
	v_mfma_f32_16x16x32_bf16 v[68:71], v[116:119], v[184:187], v[68:71]
	v_mfma_f32_16x16x32_bf16 v[72:75], v[28:31], v[192:195], v[72:75]
	v_mfma_f32_16x16x32_bf16 v[76:79], v[116:119], v[192:195], v[76:79]
	v_mfma_f32_16x16x32_bf16 v[80:83], v[28:31], v[200:203], v[80:83]
	v_mfma_f32_16x16x32_bf16 v[84:87], v[116:119], v[200:203], v[84:87]
	v_mfma_f32_16x16x32_bf16 v[88:91], v[28:31], v[208:211], v[88:91]
	v_mfma_f32_16x16x32_bf16 v[92:95], v[116:119], v[208:211], v[92:95]
	v_mfma_f32_16x16x32_bf16 v[96:99], v[120:123], v[180:183], v[96:99]
	v_mfma_f32_16x16x32_bf16 v[32:35], v[172:175], v[180:183], v[32:35]
	v_mfma_f32_16x16x32_bf16 v[36:39], v[120:123], v[188:191], v[36:39]
	v_mfma_f32_16x16x32_bf16 v[40:43], v[172:175], v[188:191], v[40:43]
	v_mfma_f32_16x16x32_bf16 v[44:47], v[120:123], v[196:199], v[44:47]
	v_mfma_f32_16x16x32_bf16 v[48:51], v[172:175], v[196:199], v[48:51]
	v_mfma_f32_16x16x32_bf16 v[52:55], v[120:123], v[204:207], v[52:55]
	v_mfma_f32_16x16x32_bf16 v[56:59], v[172:175], v[204:207], v[56:59]
	v_mfma_f32_16x16x32_bf16 v[96:99], v[124:127], v[184:187], v[96:99]
	v_mfma_f32_16x16x32_bf16 v[32:35], v[176:179], v[184:187], v[32:35]
	v_mfma_f32_16x16x32_bf16 v[36:39], v[124:127], v[192:195], v[36:39]
	v_mfma_f32_16x16x32_bf16 v[40:43], v[176:179], v[192:195], v[40:43]
	v_mfma_f32_16x16x32_bf16 v[44:47], v[124:127], v[200:203], v[44:47]
	v_mfma_f32_16x16x32_bf16 v[48:51], v[176:179], v[200:203], v[48:51]
	v_mfma_f32_16x16x32_bf16 v[52:55], v[124:127], v[208:211], v[52:55]
	v_mfma_f32_16x16x32_bf16 v[56:59], v[176:179], v[208:211], v[56:59]
	s_barrier
	s_setprio 1
	s_add_i32 s84, s82, s62
	s_add_i32 s82, s84, 0x2000
	v_lshl_add_u64 v[140:141], v[140:141], 0, s[20:21]
	s_mov_b32 m0, s84
	s_add_u32 s86, s54, 0x10180
	ds_read_b128 v[180:183], v147 offset:49152
	ds_read_b128 v[184:187], v147 offset:50176
	ds_read_b128 v[188:191], v147 offset:51200
	ds_read_b128 v[192:195], v147 offset:52224
	ds_read_b128 v[196:199], v147 offset:53248
	ds_read_b128 v[200:203], v147 offset:54272
	ds_read_b128 v[204:207], v147 offset:55296
	ds_read_b128 v[208:211], v147 offset:56320
	global_load_lds_dwordx4 v[140:141], off
	v_lshl_add_u64 v[140:141], v[212:213], 0, s[20:21]
	s_mov_b32 m0, s82
	s_addc_u32 s87, s55, 0
	s_add_i32 s54, s88, s62
	global_load_lds_dwordx4 v[140:141], off
	v_lshl_add_u64 v[140:141], s[86:87], 0, v[130:131]
	s_mov_b32 m0, s54
	s_add_i32 s55, s54, 0x2000
	global_load_lds_dwordx4 v[140:141], off
	v_lshl_add_u64 v[140:141], s[86:87], 0, v[134:135]
	s_mov_b32 m0, s55
	s_nop 0
	global_load_lds_dwordx4 v[140:141], off
	v_lshl_add_u64 v[140:141], v[214:215], 0, s[20:21]
	s_mov_b32 m0, s66
	s_nop 0
	global_load_lds_dwordx4 v[140:141], off
	v_lshl_add_u64 v[140:141], v[216:217], 0, s[20:21]
	s_mov_b32 m0, s67
	s_nop 0
	global_load_lds_dwordx4 v[140:141], off
	s_waitcnt vmcnt(8)
	s_waitcnt lgkmcnt(0)
	s_setprio 0
	s_barrier
	v_mfma_f32_16x16x32_bf16 v[0:3], v[24:27], v[204:207], v[0:3]
	v_mfma_f32_16x16x32_bf16 v[4:7], v[112:115], v[204:207], v[4:7]
	v_mfma_f32_16x16x32_bf16 v[148:151], v[24:27], v[180:183], v[148:151]
	v_mfma_f32_16x16x32_bf16 v[152:155], v[112:115], v[180:183], v[152:155]
	v_mfma_f32_16x16x32_bf16 v[156:159], v[24:27], v[188:191], v[156:159]
	v_mfma_f32_16x16x32_bf16 v[160:163], v[112:115], v[188:191], v[160:163]
	v_mfma_f32_16x16x32_bf16 v[164:167], v[24:27], v[196:199], v[164:167]
	v_mfma_f32_16x16x32_bf16 v[168:171], v[112:115], v[196:199], v[168:171]
	v_mfma_f32_16x16x32_bf16 v[0:3], v[28:31], v[208:211], v[0:3]
	v_mfma_f32_16x16x32_bf16 v[4:7], v[116:119], v[208:211], v[4:7]
	v_mfma_f32_16x16x32_bf16 v[148:151], v[28:31], v[184:187], v[148:151]
	v_mfma_f32_16x16x32_bf16 v[152:155], v[116:119], v[184:187], v[152:155]
	v_mfma_f32_16x16x32_bf16 v[156:159], v[28:31], v[192:195], v[156:159]
	v_mfma_f32_16x16x32_bf16 v[160:163], v[116:119], v[192:195], v[160:163]
	v_mfma_f32_16x16x32_bf16 v[164:167], v[28:31], v[200:203], v[164:167]
	v_mfma_f32_16x16x32_bf16 v[168:171], v[116:119], v[200:203], v[168:171]
	v_mfma_f32_16x16x32_bf16 v[8:11], v[120:123], v[180:183], v[8:11]
	v_mfma_f32_16x16x32_bf16 v[12:15], v[172:175], v[180:183], v[12:15]
	v_mfma_f32_16x16x32_bf16 v[24:27], v[120:123], v[188:191], v[60:63]
	v_mfma_f32_16x16x32_bf16 v[28:31], v[172:175], v[188:191], v[100:103]
	v_mfma_f32_16x16x32_bf16 v[60:63], v[120:123], v[196:199], v[104:107]
	v_mfma_f32_16x16x32_bf16 v[100:103], v[172:175], v[196:199], v[108:111]
	v_mfma_f32_16x16x32_bf16 v[16:19], v[120:123], v[204:207], v[16:19]
	v_mfma_f32_16x16x32_bf16 v[20:23], v[172:175], v[204:207], v[20:23]
	v_mfma_f32_16x16x32_bf16 v[8:11], v[124:127], v[184:187], v[8:11]
	v_mfma_f32_16x16x32_bf16 v[12:15], v[176:179], v[184:187], v[12:15]
	v_mfma_f32_16x16x32_bf16 v[24:27], v[124:127], v[192:195], v[24:27]
	v_mfma_f32_16x16x32_bf16 v[28:31], v[176:179], v[192:195], v[28:31]
	v_mfma_f32_16x16x32_bf16 v[60:63], v[124:127], v[200:203], v[60:63]
	v_mfma_f32_16x16x32_bf16 v[100:103], v[176:179], v[200:203], v[100:103]
	v_mfma_f32_16x16x32_bf16 v[16:19], v[124:127], v[208:211], v[16:19]
	v_mfma_f32_16x16x32_bf16 v[20:23], v[176:179], v[208:211], v[20:23]
	s_barrier
	s_setprio 1
	ds_read_b128 v[104:107], v145
	ds_read_b128 v[108:111], v145 offset:1024
	ds_read_b128 v[112:115], v145 offset:2048
	ds_read_b128 v[116:119], v145 offset:3072
	ds_read_b128 v[120:123], v146
	ds_read_b128 v[124:127], v146 offset:1024
	ds_read_b128 v[172:175], v146 offset:2048
	ds_read_b128 v[176:179], v146 offset:3072
	s_add_u32 s52, s52, 0x10180
	s_addc_u32 s53, s53, 0
	s_mov_b32 m0, s83
	v_lshl_add_u64 v[140:141], s[52:53], 0, v[128:129]
	ds_read_b128 v[180:183], v147
	ds_read_b128 v[184:187], v147 offset:1024
	ds_read_b128 v[188:191], v147 offset:2048
	ds_read_b128 v[192:195], v147 offset:3072
	ds_read_b128 v[196:199], v147 offset:4096
	ds_read_b128 v[200:203], v147 offset:5120
	ds_read_b128 v[204:207], v147 offset:6144
	ds_read_b128 v[208:211], v147 offset:7168
	global_load_lds_dwordx4 v[140:141], off
	v_lshl_add_u64 v[140:141], s[52:53], 0, v[132:133]
	s_mov_b32 m0, s35
	s_nop 0
	global_load_lds_dwordx4 v[140:141], off
	s_waitcnt vmcnt(8)
	s_waitcnt lgkmcnt(0)
	s_setprio 0
	s_barrier
	v_mfma_f32_16x16x32_bf16 v[88:91], v[104:107], v[204:207], v[88:91]
	v_mfma_f32_16x16x32_bf16 v[64:67], v[104:107], v[180:183], v[64:67]
	v_mfma_f32_16x16x32_bf16 v[68:71], v[112:115], v[180:183], v[68:71]
	v_mfma_f32_16x16x32_bf16 v[72:75], v[104:107], v[188:191], v[72:75]
	v_mfma_f32_16x16x32_bf16 v[76:79], v[112:115], v[188:191], v[76:79]
	v_mfma_f32_16x16x32_bf16 v[80:83], v[104:107], v[196:199], v[80:83]
	v_mfma_f32_16x16x32_bf16 v[84:87], v[112:115], v[196:199], v[84:87]
	v_mfma_f32_16x16x32_bf16 v[212:215], v[108:111], v[208:211], v[88:91]
	v_mfma_f32_16x16x32_bf16 v[88:91], v[112:115], v[204:207], v[92:95]
	v_mfma_f32_16x16x32_bf16 v[64:67], v[108:111], v[184:187], v[64:67]
	v_mfma_f32_16x16x32_bf16 v[68:71], v[116:119], v[184:187], v[68:71]
	v_mfma_f32_16x16x32_bf16 v[72:75], v[108:111], v[192:195], v[72:75]
	v_mfma_f32_16x16x32_bf16 v[76:79], v[116:119], v[192:195], v[76:79]
	v_mfma_f32_16x16x32_bf16 v[80:83], v[108:111], v[200:203], v[80:83]
	v_mfma_f32_16x16x32_bf16 v[84:87], v[116:119], v[200:203], v[84:87]
	v_mfma_f32_16x16x32_bf16 v[92:95], v[116:119], v[208:211], v[88:91]
	v_mfma_f32_16x16x32_bf16 v[48:51], v[172:175], v[196:199], v[48:51]
	v_mfma_f32_16x16x32_bf16 v[88:91], v[120:123], v[180:183], v[96:99]
	v_mfma_f32_16x16x32_bf16 v[32:35], v[172:175], v[180:183], v[32:35]
	v_mfma_f32_16x16x32_bf16 v[36:39], v[120:123], v[188:191], v[36:39]
	v_mfma_f32_16x16x32_bf16 v[40:43], v[172:175], v[188:191], v[40:43]
	v_mfma_f32_16x16x32_bf16 v[44:47], v[120:123], v[196:199], v[44:47]
	v_mfma_f32_16x16x32_bf16 v[180:183], v[176:179], v[200:203], v[48:51]
	v_mfma_f32_16x16x32_bf16 v[48:51], v[120:123], v[204:207], v[52:55]
	v_mfma_f32_16x16x32_bf16 v[32:35], v[176:179], v[184:187], v[32:35]
	v_mfma_f32_16x16x32_bf16 v[36:39], v[124:127], v[192:195], v[36:39]
	v_mfma_f32_16x16x32_bf16 v[40:43], v[176:179], v[192:195], v[40:43]
	v_mfma_f32_16x16x32_bf16 v[44:47], v[124:127], v[200:203], v[44:47]
	v_mfma_f32_16x16x32_bf16 v[52:55], v[124:127], v[208:211], v[48:51]
	v_mfma_f32_16x16x32_bf16 v[48:51], v[172:175], v[204:207], v[56:59]
	v_mfma_f32_16x16x32_bf16 v[220:223], v[124:127], v[184:187], v[88:91]
	v_mfma_f32_16x16x32_bf16 v[184:187], v[176:179], v[208:211], v[48:51]
	s_barrier
	s_setprio 1
	s_mov_b32 m0, s81
	v_lshl_add_u64 v[140:141], s[56:57], 0, v[130:131]
	s_add_u32 s52, s56, 0x10000
	s_nop 0
	ds_read_b128 v[48:51], v147 offset:16384
	ds_read_b128 v[56:59], v147 offset:17408
	ds_read_b128 v[88:91], v147 offset:18432
	ds_read_b128 v[96:99], v147 offset:19456
	ds_read_b128 v[188:191], v147 offset:20480
	ds_read_b128 v[192:195], v147 offset:21504
	ds_read_b128 v[196:199], v147 offset:22528
	ds_read_b128 v[200:203], v147 offset:23552
	global_load_lds_dwordx4 v[140:141], off
	v_lshl_add_u64 v[252:253], s[56:57], 0, v[134:135]
	s_mov_b32 m0, s37
	s_addc_u32 s53, s57, 0
	global_load_lds_dwordx4 v[252:253], off
	v_lshl_add_u64 v[204:205], s[52:53], 0, v[130:131]
	s_mov_b32 m0, s79
	v_lshl_add_u64 v[136:137], s[58:59], 0, v[128:129]
	global_load_lds_dwordx4 v[204:205], off
	v_lshl_add_u64 v[204:205], s[52:53], 0, v[134:135]
	s_mov_b32 m0, s80
	v_lshl_add_u64 v[138:139], s[58:59], 0, v[132:133]
	global_load_lds_dwordx4 v[204:205], off
	s_mov_b32 m0, s51
	s_nop 0
	global_load_lds_dwordx4 v[136:137], off
	s_mov_b32 m0, s63
	s_nop 0
	global_load_lds_dwordx4 v[138:139], off
	s_waitcnt vmcnt(8)
	s_waitcnt lgkmcnt(0)
	s_setprio 0
	s_barrier
	v_mfma_f32_16x16x32_bf16 v[0:3], v[104:107], v[196:199], v[0:3]
	v_mfma_f32_16x16x32_bf16 v[4:7], v[112:115], v[196:199], v[4:7]
	v_mfma_f32_16x16x32_bf16 v[148:151], v[104:107], v[48:51], v[148:151]
	v_mfma_f32_16x16x32_bf16 v[152:155], v[112:115], v[48:51], v[152:155]
	v_mfma_f32_16x16x32_bf16 v[156:159], v[104:107], v[88:91], v[156:159]
	v_mfma_f32_16x16x32_bf16 v[160:163], v[112:115], v[88:91], v[160:163]
	v_mfma_f32_16x16x32_bf16 v[164:167], v[104:107], v[188:191], v[164:167]
	v_mfma_f32_16x16x32_bf16 v[168:171], v[112:115], v[188:191], v[168:171]
	v_mfma_f32_16x16x32_bf16 v[0:3], v[108:111], v[200:203], v[0:3]
	v_mfma_f32_16x16x32_bf16 v[4:7], v[116:119], v[200:203], v[4:7]
	v_mfma_f32_16x16x32_bf16 v[148:151], v[108:111], v[56:59], v[148:151]
	v_mfma_f32_16x16x32_bf16 v[152:155], v[116:119], v[56:59], v[152:155]
	v_mfma_f32_16x16x32_bf16 v[156:159], v[108:111], v[96:99], v[156:159]
	v_mfma_f32_16x16x32_bf16 v[160:163], v[116:119], v[96:99], v[160:163]
	v_mfma_f32_16x16x32_bf16 v[164:167], v[108:111], v[192:195], v[164:167]
	v_mfma_f32_16x16x32_bf16 v[168:171], v[116:119], v[192:195], v[168:171]
	v_mfma_f32_16x16x32_bf16 v[12:15], v[172:175], v[48:51], v[12:15]
	v_mfma_f32_16x16x32_bf16 v[204:207], v[176:179], v[56:59], v[12:15]
	v_mfma_f32_16x16x32_bf16 v[12:15], v[120:123], v[88:91], v[24:27]
	v_mfma_f32_16x16x32_bf16 v[24:27], v[124:127], v[96:99], v[12:15]
	v_mfma_f32_16x16x32_bf16 v[12:15], v[172:175], v[88:91], v[28:31]
	v_mfma_f32_16x16x32_bf16 v[208:211], v[176:179], v[96:99], v[12:15]
	v_mfma_f32_16x16x32_bf16 v[12:15], v[120:123], v[188:191], v[60:63]
	v_mfma_f32_16x16x32_bf16 v[224:227], v[124:127], v[192:195], v[12:15]
	v_mfma_f32_16x16x32_bf16 v[12:15], v[172:175], v[188:191], v[100:103]
	v_mfma_f32_16x16x32_bf16 v[8:11], v[120:123], v[48:51], v[8:11]
	v_mfma_f32_16x16x32_bf16 v[188:191], v[176:179], v[192:195], v[12:15]
	v_mfma_f32_16x16x32_bf16 v[12:15], v[120:123], v[196:199], v[16:19]
	v_mfma_f32_16x16x32_bf16 v[8:11], v[124:127], v[56:59], v[8:11]
	v_mfma_f32_16x16x32_bf16 v[192:195], v[124:127], v[200:203], v[12:15]
	v_mfma_f32_16x16x32_bf16 v[12:15], v[172:175], v[196:199], v[20:23]
	v_mfma_f32_16x16x32_bf16 v[172:175], v[176:179], v[200:203], v[12:15]
	s_barrier
	s_setprio 1
	s_nop 4
	ds_read_b128 v[12:15], v228
	ds_read_b128 v[16:19], v228 offset:1024
	ds_read_b128 v[176:179], v228 offset:2048
	ds_read_b128 v[196:199], v228 offset:3072
	ds_read_b128 v[200:203], v236
	ds_read_b128 v[228:231], v236 offset:1024
	ds_read_b128 v[232:235], v236 offset:2048
	ds_read_b128 v[236:239], v236 offset:3072
	s_add_u32 s52, s58, 0x10000
	s_addc_u32 s53, s59, 0
	s_mov_b32 m0, s64
	v_lshl_add_u64 v[48:49], s[52:53], 0, v[128:129]
	ds_read_b128 v[20:23], v147 offset:32768
	ds_read_b128 v[28:31], v147 offset:33792
	ds_read_b128 v[60:63], v147 offset:34816
	ds_read_b128 v[100:103], v147 offset:35840
	ds_read_b128 v[240:243], v147 offset:36864
	ds_read_b128 v[244:247], v147 offset:37888
	ds_read_b128 v[248:251], v147 offset:38912
	ds_read_b128 v[216:219], v147 offset:39936
	global_load_lds_dwordx4 v[48:49], off
	v_lshl_add_u64 v[48:49], s[52:53], 0, v[132:133]
	s_mov_b32 m0, s65
	s_nop 0
	global_load_lds_dwordx4 v[48:49], off
	s_waitcnt vmcnt(8)
	s_waitcnt lgkmcnt(0)
	s_setprio 0
	s_barrier
	v_mfma_f32_16x16x32_bf16 v[48:51], v[12:15], v[20:23], v[64:67]
	v_mfma_f32_16x16x32_bf16 v[120:123], v[16:19], v[28:31], v[48:51]
	v_mfma_f32_16x16x32_bf16 v[48:51], v[176:179], v[20:23], v[68:71]
	v_mfma_f32_16x16x32_bf16 v[112:115], v[196:199], v[28:31], v[48:51]
	v_mfma_f32_16x16x32_bf16 v[48:51], v[12:15], v[60:63], v[72:75]
	v_mfma_f32_16x16x32_bf16 v[104:107], v[16:19], v[100:103], v[48:51]
	v_mfma_f32_16x16x32_bf16 v[48:51], v[176:179], v[60:63], v[76:79]
	v_mfma_f32_16x16x32_bf16 v[96:99], v[196:199], v[100:103], v[48:51]
	v_mfma_f32_16x16x32_bf16 v[48:51], v[12:15], v[240:243], v[80:83]
	v_mfma_f32_16x16x32_bf16 v[88:91], v[16:19], v[244:247], v[48:51]
	v_mfma_f32_16x16x32_bf16 v[48:51], v[176:179], v[240:243], v[84:87]
	v_mfma_f32_16x16x32_bf16 v[80:83], v[196:199], v[244:247], v[48:51]
	v_mfma_f32_16x16x32_bf16 v[48:51], v[12:15], v[248:251], v[212:215]
	v_mfma_f32_16x16x32_bf16 v[56:59], v[16:19], v[216:219], v[48:51]
	v_mfma_f32_16x16x32_bf16 v[48:51], v[176:179], v[248:251], v[92:95]
	v_mfma_f32_16x16x32_bf16 v[48:51], v[196:199], v[216:219], v[48:51]
	v_mfma_f32_16x16x32_bf16 v[64:67], v[200:203], v[20:23], v[220:223]
	v_mfma_f32_16x16x32_bf16 v[20:23], v[232:235], v[20:23], v[32:35]
	v_mfma_f32_16x16x32_bf16 v[116:119], v[236:239], v[28:31], v[20:23]
	v_mfma_f32_16x16x32_bf16 v[20:23], v[200:203], v[60:63], v[36:39]
	v_mfma_f32_16x16x32_bf16 v[108:111], v[228:231], v[100:103], v[20:23]
	v_mfma_f32_16x16x32_bf16 v[20:23], v[232:235], v[60:63], v[40:43]
	v_mfma_f32_16x16x32_bf16 v[100:103], v[236:239], v[100:103], v[20:23]
	v_mfma_f32_16x16x32_bf16 v[20:23], v[200:203], v[240:243], v[44:47]
	v_mfma_f32_16x16x32_bf16 v[92:95], v[228:231], v[244:247], v[20:23]
	v_mfma_f32_16x16x32_bf16 v[20:23], v[232:235], v[240:243], v[180:183]
	v_mfma_f32_16x16x32_bf16 v[84:87], v[236:239], v[244:247], v[20:23]
	v_mfma_f32_16x16x32_bf16 v[20:23], v[200:203], v[248:251], v[52:55]
	v_mfma_f32_16x16x32_bf16 v[60:63], v[228:231], v[216:219], v[20:23]
	v_mfma_f32_16x16x32_bf16 v[20:23], v[232:235], v[248:251], v[184:187]
	v_mfma_f32_16x16x32_bf16 v[124:127], v[228:231], v[28:31], v[64:67]
	v_mfma_f32_16x16x32_bf16 v[52:55], v[236:239], v[216:219], v[20:23]
	s_barrier
	s_setprio 1
	s_mov_b32 m0, s84
	s_nop 2
	v_lshl_add_u64 v[20:21], v[140:141], 0, s[12:13]
	s_add_u32 s52, s56, 0x10080
	ds_read_b128 v[32:35], v147 offset:49152
	ds_read_b128 v[40:43], v147 offset:50176
	ds_read_b128 v[180:183], v147 offset:51200
	ds_read_b128 v[184:187], v147 offset:52224
	ds_read_b128 v[212:215], v147 offset:53248
	ds_read_b128 v[216:219], v147 offset:54272
	ds_read_b128 v[220:223], v147 offset:55296
	ds_read_b128 v[240:243], v147 offset:56320
	global_load_lds_dwordx4 v[20:21], off
	v_lshl_add_u64 v[20:21], v[252:253], 0, s[12:13]
	s_mov_b32 m0, s82
	s_addc_u32 s53, s57, 0
	global_load_lds_dwordx4 v[20:21], off
	v_lshl_add_u64 v[20:21], s[52:53], 0, v[130:131]
	s_mov_b32 m0, s54
	s_nop 0
	global_load_lds_dwordx4 v[20:21], off
	v_lshl_add_u64 v[20:21], s[52:53], 0, v[134:135]
	s_mov_b32 m0, s55
	s_nop 0
	global_load_lds_dwordx4 v[20:21], off
	v_lshl_add_u64 v[20:21], v[136:137], 0, s[12:13]
	s_mov_b32 m0, s66
	s_nop 0
	global_load_lds_dwordx4 v[20:21], off
	v_lshl_add_u64 v[20:21], v[138:139], 0, s[12:13]
	s_mov_b32 m0, s67
	s_nop 0
	global_load_lds_dwordx4 v[20:21], off
	s_waitcnt vmcnt(8)
	s_waitcnt lgkmcnt(0)
	s_setprio 0
	s_barrier
	v_mfma_f32_16x16x32_bf16 v[20:23], v[12:15], v[32:35], v[148:151]
	v_mfma_f32_16x16x32_bf16 v[76:79], v[16:19], v[40:43], v[20:23]
	v_mfma_f32_16x16x32_bf16 v[20:23], v[176:179], v[32:35], v[152:155]
	v_mfma_f32_16x16x32_bf16 v[68:71], v[196:199], v[40:43], v[20:23]
	v_mfma_f32_16x16x32_bf16 v[20:23], v[12:15], v[180:183], v[156:159]
	v_mfma_f32_16x16x32_bf16 v[44:47], v[16:19], v[184:187], v[20:23]
	v_mfma_f32_16x16x32_bf16 v[20:23], v[176:179], v[180:183], v[160:163]
	v_mfma_f32_16x16x32_bf16 v[36:39], v[196:199], v[184:187], v[20:23]
	v_mfma_f32_16x16x32_bf16 v[20:23], v[12:15], v[212:215], v[164:167]
	v_mfma_f32_16x16x32_bf16 v[0:3], v[12:15], v[220:223], v[0:3]
	v_mfma_f32_16x16x32_bf16 v[28:31], v[16:19], v[216:219], v[20:23]
	v_mfma_f32_16x16x32_bf16 v[20:23], v[176:179], v[212:215], v[168:171]
	v_mfma_f32_16x16x32_bf16 v[12:15], v[16:19], v[240:243], v[0:3]
	v_mfma_f32_16x16x32_bf16 v[0:3], v[176:179], v[220:223], v[4:7]
	v_mfma_f32_16x16x32_bf16 v[20:23], v[196:199], v[216:219], v[20:23]
	v_mfma_f32_16x16x32_bf16 v[4:7], v[196:199], v[240:243], v[0:3]
	v_mfma_f32_16x16x32_bf16 v[0:3], v[200:203], v[32:35], v[8:11]
	v_mfma_f32_16x16x32_bf16 v[72:75], v[228:231], v[40:43], v[0:3]
	v_mfma_f32_16x16x32_bf16 v[0:3], v[232:235], v[32:35], v[204:207]
	v_mfma_f32_16x16x32_bf16 v[64:67], v[236:239], v[40:43], v[0:3]
	v_mfma_f32_16x16x32_bf16 v[0:3], v[200:203], v[180:183], v[24:27]
	v_mfma_f32_16x16x32_bf16 v[40:43], v[228:231], v[184:187], v[0:3]
	v_mfma_f32_16x16x32_bf16 v[0:3], v[232:235], v[180:183], v[208:211]
	v_mfma_f32_16x16x32_bf16 v[32:35], v[236:239], v[184:187], v[0:3]
	v_mfma_f32_16x16x32_bf16 v[0:3], v[200:203], v[212:215], v[224:227]
	v_mfma_f32_16x16x32_bf16 v[24:27], v[228:231], v[216:219], v[0:3]
	v_mfma_f32_16x16x32_bf16 v[0:3], v[232:235], v[212:215], v[188:191]
	v_mfma_f32_16x16x32_bf16 v[16:19], v[236:239], v[216:219], v[0:3]
	v_mfma_f32_16x16x32_bf16 v[0:3], v[200:203], v[220:223], v[192:195]
	v_mfma_f32_16x16x32_bf16 v[8:11], v[228:231], v[240:243], v[0:3]
	v_mfma_f32_16x16x32_bf16 v[0:3], v[232:235], v[220:223], v[172:175]
	v_mfma_f32_16x16x32_bf16 v[0:3], v[236:239], v[240:243], v[0:3]
	s_barrier
	s_setprio 1
	s_andn2_b64 vcc, exec, s[14:15]
	s_cbranch_vccnz .LBB0_155
	s_barrier
	s_setprio 3

.LBB0_178:
	ds_read_b128 v[148:151], v157
	ds_read_b128 v[162:165], v157 offset:1024
	ds_read_b128 v[166:169], v157 offset:2048
	ds_read_b128 v[170:173], v157 offset:3072
	ds_read_b128 v[174:177], v158
	ds_read_b128 v[178:181], v158 offset:1024
	ds_read_b128 v[182:185], v158 offset:2048
	ds_read_b128 v[186:189], v158 offset:3072
	s_add_u32 s48, s46, 0xfff80080
	s_addc_u32 s49, s47, -1
	s_cmp_eq_u32 s72, 28
	s_cselect_b32 s51, s31, s49
	s_cselect_b32 s50, s66, s48
	s_cselect_b32 s49, s27, s71
	s_cselect_b32 s48, s67, s70
	v_lshl_add_u64 v[152:153], s[46:47], 0, v[142:143]
	s_add_i32 m0, s13, 0xc000
	ds_read_b128 v[190:193], v159
	ds_read_b128 v[194:197], v159 offset:1024
	ds_read_b128 v[198:201], v159 offset:2048
	ds_read_b128 v[202:205], v159 offset:3072
	ds_read_b128 v[206:209], v159 offset:4096
	ds_read_b128 v[210:213], v159 offset:5120
	ds_read_b128 v[214:217], v159 offset:6144
	ds_read_b128 v[218:221], v159 offset:7168
	global_load_lds_dwordx4 v[152:153], off
	v_lshl_add_u64 v[152:153], s[46:47], 0, v[140:141]
	s_add_i32 m0, s13, 0xe000
	s_nop 0
	global_load_lds_dwordx4 v[152:153], off
	s_waitcnt vmcnt(8)
	s_waitcnt lgkmcnt(0)
	s_setprio 0
	s_barrier
	v_mfma_f32_16x16x32_bf16 v[124:127], v[148:151], v[190:193], v[124:127]
	v_mfma_f32_16x16x32_bf16 v[120:123], v[166:169], v[190:193], v[120:123]
	v_mfma_f32_16x16x32_bf16 v[108:111], v[148:151], v[198:201], v[108:111]
	v_mfma_f32_16x16x32_bf16 v[104:107], v[166:169], v[198:201], v[104:107]
	v_mfma_f32_16x16x32_bf16 v[92:95], v[148:151], v[206:209], v[92:95]
	v_mfma_f32_16x16x32_bf16 v[88:91], v[166:169], v[206:209], v[88:91]
	v_mfma_f32_16x16x32_bf16 v[76:79], v[148:151], v[214:217], v[76:79]
	v_mfma_f32_16x16x32_bf16 v[72:75], v[166:169], v[214:217], v[72:75]
	v_mfma_f32_16x16x32_bf16 v[124:127], v[162:165], v[194:197], v[124:127]
	v_mfma_f32_16x16x32_bf16 v[120:123], v[170:173], v[194:197], v[120:123]
	v_mfma_f32_16x16x32_bf16 v[108:111], v[162:165], v[202:205], v[108:111]
	v_mfma_f32_16x16x32_bf16 v[104:107], v[170:173], v[202:205], v[104:107]
	v_mfma_f32_16x16x32_bf16 v[92:95], v[162:165], v[210:213], v[92:95]
	v_mfma_f32_16x16x32_bf16 v[88:91], v[170:173], v[210:213], v[88:91]
	v_mfma_f32_16x16x32_bf16 v[76:79], v[162:165], v[218:221], v[76:79]
	v_mfma_f32_16x16x32_bf16 v[72:75], v[170:173], v[218:221], v[72:75]
	v_mfma_f32_16x16x32_bf16 v[116:119], v[174:177], v[190:193], v[116:119]
	v_mfma_f32_16x16x32_bf16 v[112:115], v[182:185], v[190:193], v[112:115]
	v_mfma_f32_16x16x32_bf16 v[100:103], v[174:177], v[198:201], v[100:103]
	v_mfma_f32_16x16x32_bf16 v[96:99], v[182:185], v[198:201], v[96:99]
	v_mfma_f32_16x16x32_bf16 v[84:87], v[174:177], v[206:209], v[84:87]
	v_mfma_f32_16x16x32_bf16 v[80:83], v[182:185], v[206:209], v[80:83]
	v_mfma_f32_16x16x32_bf16 v[68:71], v[174:177], v[214:217], v[68:71]
	v_mfma_f32_16x16x32_bf16 v[64:67], v[182:185], v[214:217], v[64:67]
	v_mfma_f32_16x16x32_bf16 v[116:119], v[178:181], v[194:197], v[116:119]
	v_mfma_f32_16x16x32_bf16 v[112:115], v[186:189], v[194:197], v[112:115]
	v_mfma_f32_16x16x32_bf16 v[100:103], v[178:181], v[202:205], v[100:103]
	v_mfma_f32_16x16x32_bf16 v[96:99], v[186:189], v[202:205], v[96:99]
	v_mfma_f32_16x16x32_bf16 v[84:87], v[178:181], v[210:213], v[84:87]
	v_mfma_f32_16x16x32_bf16 v[80:83], v[186:189], v[210:213], v[80:83]
	v_mfma_f32_16x16x32_bf16 v[68:71], v[178:181], v[218:221], v[68:71]
	v_mfma_f32_16x16x32_bf16 v[64:67], v[186:189], v[218:221], v[64:67]
	s_barrier
	s_setprio 1
	s_add_i32 s73, s62, s52
	v_lshl_add_u64 v[152:153], s[48:49], 0, v[130:131]
	s_mov_b32 m0, s73
	ds_read_b128 v[190:193], v159 offset:16384
	ds_read_b128 v[194:197], v159 offset:17408
	ds_read_b128 v[198:201], v159 offset:18432
	ds_read_b128 v[202:205], v159 offset:19456
	ds_read_b128 v[206:209], v159 offset:20480
	ds_read_b128 v[210:213], v159 offset:21504
	ds_read_b128 v[214:217], v159 offset:22528
	ds_read_b128 v[218:221], v159 offset:23552
	global_load_lds_dwordx4 v[152:153], off
	s_add_i32 m0, s73, 0x2000
	s_add_u32 s74, s48, 0x80000
	v_lshl_add_u64 v[222:223], s[48:49], 0, v[134:135]
	s_addc_u32 s75, s49, 0
	s_add_i32 s73, s63, s52
	global_load_lds_dwordx4 v[222:223], off
	v_lshl_add_u64 v[224:225], s[74:75], 0, v[130:131]
	s_mov_b32 m0, s73
	v_lshl_add_u64 v[226:227], s[50:51], 0, v[132:133]
	global_load_lds_dwordx4 v[224:225], off
	v_lshl_add_u64 v[224:225], s[74:75], 0, v[134:135]
	s_add_i32 m0, s73, 0x2000
	s_nop 0
	global_load_lds_dwordx4 v[224:225], off
	v_lshl_add_u64 v[224:225], s[50:51], 0, v[128:129]
	s_mov_b32 m0, s13
	s_nop 0
	global_load_lds_dwordx4 v[224:225], off
	s_mov_b32 m0, s53
	s_nop 0
	global_load_lds_dwordx4 v[226:227], off
	s_waitcnt vmcnt(8)
	s_waitcnt lgkmcnt(0)
	s_setprio 0
	s_barrier
	v_mfma_f32_16x16x32_bf16 v[60:63], v[148:151], v[190:193], v[60:63]
	v_mfma_f32_16x16x32_bf16 v[56:59], v[166:169], v[190:193], v[56:59]
	v_mfma_f32_16x16x32_bf16 v[44:47], v[148:151], v[198:201], v[44:47]
	v_mfma_f32_16x16x32_bf16 v[40:43], v[166:169], v[198:201], v[40:43]
	v_mfma_f32_16x16x32_bf16 v[28:31], v[148:151], v[206:209], v[28:31]
	v_mfma_f32_16x16x32_bf16 v[24:27], v[166:169], v[206:209], v[24:27]
	v_mfma_f32_16x16x32_bf16 v[12:15], v[148:151], v[214:217], v[12:15]
	v_mfma_f32_16x16x32_bf16 v[8:11], v[166:169], v[214:217], v[8:11]
	v_mfma_f32_16x16x32_bf16 v[60:63], v[162:165], v[194:197], v[60:63]
	v_mfma_f32_16x16x32_bf16 v[56:59], v[170:173], v[194:197], v[56:59]
	v_mfma_f32_16x16x32_bf16 v[44:47], v[162:165], v[202:205], v[44:47]
	v_mfma_f32_16x16x32_bf16 v[40:43], v[170:173], v[202:205], v[40:43]
	v_mfma_f32_16x16x32_bf16 v[28:31], v[162:165], v[210:213], v[28:31]
	v_mfma_f32_16x16x32_bf16 v[24:27], v[170:173], v[210:213], v[24:27]
	v_mfma_f32_16x16x32_bf16 v[12:15], v[162:165], v[218:221], v[12:15]
	v_mfma_f32_16x16x32_bf16 v[8:11], v[170:173], v[218:221], v[8:11]
	v_mfma_f32_16x16x32_bf16 v[52:55], v[174:177], v[190:193], v[52:55]
	v_mfma_f32_16x16x32_bf16 v[48:51], v[182:185], v[190:193], v[48:51]
	v_mfma_f32_16x16x32_bf16 v[36:39], v[174:177], v[198:201], v[36:39]
	v_mfma_f32_16x16x32_bf16 v[32:35], v[182:185], v[198:201], v[32:35]
	v_mfma_f32_16x16x32_bf16 v[20:23], v[174:177], v[206:209], v[20:23]
	v_mfma_f32_16x16x32_bf16 v[16:19], v[182:185], v[206:209], v[16:19]
	v_mfma_f32_16x16x32_bf16 v[4:7], v[174:177], v[214:217], v[4:7]
	v_mfma_f32_16x16x32_bf16 v[0:3], v[182:185], v[214:217], v[0:3]
	v_mfma_f32_16x16x32_bf16 v[52:55], v[178:181], v[194:197], v[52:55]
	v_mfma_f32_16x16x32_bf16 v[48:51], v[186:189], v[194:197], v[48:51]
	v_mfma_f32_16x16x32_bf16 v[36:39], v[178:181], v[202:205], v[36:39]
	v_mfma_f32_16x16x32_bf16 v[32:35], v[186:189], v[202:205], v[32:35]
	v_mfma_f32_16x16x32_bf16 v[20:23], v[178:181], v[210:213], v[20:23]
	v_mfma_f32_16x16x32_bf16 v[16:19], v[186:189], v[210:213], v[16:19]
	v_mfma_f32_16x16x32_bf16 v[4:7], v[178:181], v[218:221], v[4:7]
	v_mfma_f32_16x16x32_bf16 v[0:3], v[186:189], v[218:221], v[0:3]
	s_barrier
	s_setprio 1
	s_add_i32 s73, 0, 0x18000
	v_add_u32_e32 v137, s73, v155
	s_add_i32 s74, 0, 0x1c000
	ds_read_b128 v[148:151], v137
	ds_read_b128 v[162:165], v137 offset:1024
	ds_read_b128 v[166:169], v137 offset:2048
	ds_read_b128 v[170:173], v137 offset:3072
	v_add_u32_e32 v137, s74, v155
	ds_read_b128 v[174:177], v137
	ds_read_b128 v[178:181], v137 offset:1024
	ds_read_b128 v[182:185], v137 offset:2048
	ds_read_b128 v[186:189], v137 offset:3072
	s_add_u32 s50, s50, 0x80000
	s_addc_u32 s51, s51, 0
	s_mov_b32 m0, s54
	v_lshl_add_u64 v[228:229], s[50:51], 0, v[128:129]
	ds_read_b128 v[190:193], v159 offset:32768
	ds_read_b128 v[194:197], v159 offset:33792
	ds_read_b128 v[198:201], v159 offset:34816
	ds_read_b128 v[202:205], v159 offset:35840
	ds_read_b128 v[206:209], v159 offset:36864
	ds_read_b128 v[210:213], v159 offset:37888
	ds_read_b128 v[214:217], v159 offset:38912
	ds_read_b128 v[218:221], v159 offset:39936
	global_load_lds_dwordx4 v[228:229], off
	v_lshl_add_u64 v[228:229], s[50:51], 0, v[132:133]
	s_mov_b32 m0, s55
	s_nop 0
	global_load_lds_dwordx4 v[228:229], off
	s_waitcnt vmcnt(8)
	s_waitcnt lgkmcnt(0)
	s_setprio 0
	s_barrier
	v_mfma_f32_16x16x32_bf16 v[124:127], v[148:151], v[190:193], v[124:127]
	v_mfma_f32_16x16x32_bf16 v[120:123], v[166:169], v[190:193], v[120:123]
	v_mfma_f32_16x16x32_bf16 v[108:111], v[148:151], v[198:201], v[108:111]
	v_mfma_f32_16x16x32_bf16 v[104:107], v[166:169], v[198:201], v[104:107]
	v_mfma_f32_16x16x32_bf16 v[92:95], v[148:151], v[206:209], v[92:95]
	v_mfma_f32_16x16x32_bf16 v[88:91], v[166:169], v[206:209], v[88:91]
	v_mfma_f32_16x16x32_bf16 v[76:79], v[148:151], v[214:217], v[76:79]
	v_mfma_f32_16x16x32_bf16 v[72:75], v[166:169], v[214:217], v[72:75]
	v_mfma_f32_16x16x32_bf16 v[124:127], v[162:165], v[194:197], v[124:127]
	v_mfma_f32_16x16x32_bf16 v[120:123], v[170:173], v[194:197], v[120:123]
	v_mfma_f32_16x16x32_bf16 v[108:111], v[162:165], v[202:205], v[108:111]
	v_mfma_f32_16x16x32_bf16 v[104:107], v[170:173], v[202:205], v[104:107]
	v_mfma_f32_16x16x32_bf16 v[92:95], v[162:165], v[210:213], v[92:95]
	v_mfma_f32_16x16x32_bf16 v[88:91], v[170:173], v[210:213], v[88:91]
	v_mfma_f32_16x16x32_bf16 v[76:79], v[162:165], v[218:221], v[76:79]
	v_mfma_f32_16x16x32_bf16 v[72:75], v[170:173], v[218:221], v[72:75]
	v_mfma_f32_16x16x32_bf16 v[116:119], v[174:177], v[190:193], v[116:119]
	v_mfma_f32_16x16x32_bf16 v[112:115], v[182:185], v[190:193], v[112:115]
	v_mfma_f32_16x16x32_bf16 v[100:103], v[174:177], v[198:201], v[100:103]
	v_mfma_f32_16x16x32_bf16 v[96:99], v[182:185], v[198:201], v[96:99]
	v_mfma_f32_16x16x32_bf16 v[84:87], v[174:177], v[206:209], v[84:87]
	v_mfma_f32_16x16x32_bf16 v[80:83], v[182:185], v[206:209], v[80:83]
	v_mfma_f32_16x16x32_bf16 v[68:71], v[174:177], v[214:217], v[68:71]
	v_mfma_f32_16x16x32_bf16 v[64:67], v[182:185], v[214:217], v[64:67]
	v_mfma_f32_16x16x32_bf16 v[116:119], v[178:181], v[194:197], v[116:119]
	v_mfma_f32_16x16x32_bf16 v[112:115], v[186:189], v[194:197], v[112:115]
	v_mfma_f32_16x16x32_bf16 v[100:103], v[178:181], v[202:205], v[100:103]
	v_mfma_f32_16x16x32_bf16 v[96:99], v[186:189], v[202:205], v[96:99]
	v_mfma_f32_16x16x32_bf16 v[84:87], v[178:181], v[210:213], v[84:87]
	v_mfma_f32_16x16x32_bf16 v[80:83], v[186:189], v[210:213], v[80:83]
	v_mfma_f32_16x16x32_bf16 v[68:71], v[178:181], v[218:221], v[68:71]
	v_mfma_f32_16x16x32_bf16 v[64:67], v[186:189], v[218:221], v[64:67]
	s_barrier
	s_setprio 1
	s_add_i32 s50, s73, s52
	v_lshl_add_u64 v[152:153], v[152:153], 0, s[22:23]
	s_mov_b32 m0, s50
	ds_read_b128 v[190:193], v159 offset:49152
	ds_read_b128 v[194:197], v159 offset:50176
	ds_read_b128 v[198:201], v159 offset:51200
	ds_read_b128 v[202:205], v159 offset:52224
	ds_read_b128 v[206:209], v159 offset:53248
	ds_read_b128 v[210:213], v159 offset:54272
	ds_read_b128 v[214:217], v159 offset:55296
	ds_read_b128 v[218:221], v159 offset:56320
	global_load_lds_dwordx4 v[152:153], off
	s_add_i32 m0, s50, 0x2000
	s_add_u32 s48, s48, 0x80080
	v_lshl_add_u64 v[152:153], v[222:223], 0, s[22:23]
	s_addc_u32 s49, s49, 0
	s_add_i32 s50, s74, s52
	global_load_lds_dwordx4 v[152:153], off
	v_lshl_add_u64 v[152:153], s[48:49], 0, v[130:131]
	s_mov_b32 m0, s50
	s_nop 0
	global_load_lds_dwordx4 v[152:153], off
	v_lshl_add_u64 v[152:153], s[48:49], 0, v[134:135]
	s_add_i32 m0, s50, 0x2000
	s_nop 0
	global_load_lds_dwordx4 v[152:153], off
	v_lshl_add_u64 v[152:153], v[224:225], 0, s[22:23]
	s_mov_b32 m0, s57
	s_nop 0
	global_load_lds_dwordx4 v[152:153], off
	v_lshl_add_u64 v[152:153], v[226:227], 0, s[22:23]
	s_mov_b32 m0, s58
	s_nop 0
	global_load_lds_dwordx4 v[152:153], off
	s_waitcnt vmcnt(8)
	s_waitcnt lgkmcnt(0)
	s_setprio 0
	s_barrier
	v_mfma_f32_16x16x32_bf16 v[60:63], v[148:151], v[190:193], v[60:63]
	v_mfma_f32_16x16x32_bf16 v[56:59], v[166:169], v[190:193], v[56:59]
	v_mfma_f32_16x16x32_bf16 v[44:47], v[148:151], v[198:201], v[44:47]
	v_mfma_f32_16x16x32_bf16 v[40:43], v[166:169], v[198:201], v[40:43]
	v_mfma_f32_16x16x32_bf16 v[28:31], v[148:151], v[206:209], v[28:31]
	v_mfma_f32_16x16x32_bf16 v[24:27], v[166:169], v[206:209], v[24:27]
	v_mfma_f32_16x16x32_bf16 v[12:15], v[148:151], v[214:217], v[12:15]
	v_mfma_f32_16x16x32_bf16 v[8:11], v[166:169], v[214:217], v[8:11]
	v_mfma_f32_16x16x32_bf16 v[60:63], v[162:165], v[194:197], v[60:63]
	v_mfma_f32_16x16x32_bf16 v[56:59], v[170:173], v[194:197], v[56:59]
	v_mfma_f32_16x16x32_bf16 v[44:47], v[162:165], v[202:205], v[44:47]
	v_mfma_f32_16x16x32_bf16 v[40:43], v[170:173], v[202:205], v[40:43]
	v_mfma_f32_16x16x32_bf16 v[28:31], v[162:165], v[210:213], v[28:31]
	v_mfma_f32_16x16x32_bf16 v[24:27], v[170:173], v[210:213], v[24:27]
	v_mfma_f32_16x16x32_bf16 v[12:15], v[162:165], v[218:221], v[12:15]
	v_mfma_f32_16x16x32_bf16 v[8:11], v[170:173], v[218:221], v[8:11]
	v_mfma_f32_16x16x32_bf16 v[52:55], v[174:177], v[190:193], v[52:55]
	v_mfma_f32_16x16x32_bf16 v[48:51], v[182:185], v[190:193], v[48:51]
	v_mfma_f32_16x16x32_bf16 v[36:39], v[174:177], v[198:201], v[36:39]
	v_mfma_f32_16x16x32_bf16 v[32:35], v[182:185], v[198:201], v[32:35]
	v_mfma_f32_16x16x32_bf16 v[20:23], v[174:177], v[206:209], v[20:23]
	v_mfma_f32_16x16x32_bf16 v[16:19], v[182:185], v[206:209], v[16:19]
	v_mfma_f32_16x16x32_bf16 v[4:7], v[174:177], v[214:217], v[4:7]
	v_mfma_f32_16x16x32_bf16 v[0:3], v[182:185], v[214:217], v[0:3]
	v_mfma_f32_16x16x32_bf16 v[52:55], v[178:181], v[194:197], v[52:55]
	v_mfma_f32_16x16x32_bf16 v[48:51], v[186:189], v[194:197], v[48:51]
	v_mfma_f32_16x16x32_bf16 v[36:39], v[178:181], v[202:205], v[36:39]
	v_mfma_f32_16x16x32_bf16 v[32:35], v[186:189], v[202:205], v[32:35]
	v_mfma_f32_16x16x32_bf16 v[20:23], v[178:181], v[210:213], v[20:23]
	v_mfma_f32_16x16x32_bf16 v[16:19], v[186:189], v[210:213], v[16:19]
	v_mfma_f32_16x16x32_bf16 v[4:7], v[178:181], v[218:221], v[4:7]
	v_mfma_f32_16x16x32_bf16 v[0:3], v[186:189], v[218:221], v[0:3]
	s_barrier
	s_setprio 1
	s_add_i32 s72, s72, 2
	s_add_u32 s70, s70, 0x100
	s_addc_u32 s71, s71, 0
	s_add_u32 s46, s46, 0x100
	s_addc_u32 s47, s47, 0
	s_cmp_gt_u32 s72, 29
	s_cbranch_scc0 .LBB0_178
	s_and_b64 vcc, exec, s[24:25]
	s_cbranch_vccz .LBB0_181
	s_barrier
	s_setprio 3

.LBB0_337:
	ds_read_b128 v[144:147], v151
	ds_read_b128 v[156:159], v151 offset:1024
	ds_read_b128 v[160:163], v151 offset:2048
	ds_read_b128 v[164:167], v151 offset:3072
	ds_read_b128 v[168:171], v152
	ds_read_b128 v[172:175], v152 offset:1024
	ds_read_b128 v[176:179], v152 offset:2048
	ds_read_b128 v[180:183], v152 offset:3072
	s_add_u32 s50, s48, 0xfff80080
	s_addc_u32 s51, s49, -1
	s_cmp_eq_u32 s75, 28
	s_cselect_b32 s53, s31, s51
	s_cselect_b32 s52, s47, s50
	s_cselect_b32 s51, s27, s74
	s_cselect_b32 s50, s71, s72
	v_lshl_add_u64 v[216:217], s[48:49], 0, v[138:139]
	s_add_i32 m0, s57, 0xc000
	ds_read_b128 v[184:187], v153
	ds_read_b128 v[188:191], v153 offset:1024
	ds_read_b128 v[192:195], v153 offset:2048
	ds_read_b128 v[196:199], v153 offset:3072
	ds_read_b128 v[200:203], v153 offset:4096
	ds_read_b128 v[204:207], v153 offset:5120
	ds_read_b128 v[208:211], v153 offset:6144
	ds_read_b128 v[212:215], v153 offset:7168
	global_load_lds_dwordx4 v[216:217], off
	v_lshl_add_u64 v[216:217], s[48:49], 0, v[136:137]
	s_add_i32 m0, s57, 0xe000
	s_nop 0
	global_load_lds_dwordx4 v[216:217], off
	s_waitcnt vmcnt(8)
	s_waitcnt lgkmcnt(0)
	s_setprio 0
	s_barrier
	v_mfma_f32_16x16x32_bf16 v[124:127], v[144:147], v[184:187], v[124:127]
	v_mfma_f32_16x16x32_bf16 v[120:123], v[160:163], v[184:187], v[120:123]
	v_mfma_f32_16x16x32_bf16 v[108:111], v[144:147], v[192:195], v[108:111]
	v_mfma_f32_16x16x32_bf16 v[104:107], v[160:163], v[192:195], v[104:107]
	v_mfma_f32_16x16x32_bf16 v[92:95], v[144:147], v[200:203], v[92:95]
	v_mfma_f32_16x16x32_bf16 v[88:91], v[160:163], v[200:203], v[88:91]
	v_mfma_f32_16x16x32_bf16 v[76:79], v[144:147], v[208:211], v[76:79]
	v_mfma_f32_16x16x32_bf16 v[72:75], v[160:163], v[208:211], v[72:75]
	v_mfma_f32_16x16x32_bf16 v[124:127], v[156:159], v[188:191], v[124:127]
	v_mfma_f32_16x16x32_bf16 v[120:123], v[164:167], v[188:191], v[120:123]
	v_mfma_f32_16x16x32_bf16 v[108:111], v[156:159], v[196:199], v[108:111]
	v_mfma_f32_16x16x32_bf16 v[104:107], v[164:167], v[196:199], v[104:107]
	v_mfma_f32_16x16x32_bf16 v[92:95], v[156:159], v[204:207], v[92:95]
	v_mfma_f32_16x16x32_bf16 v[88:91], v[164:167], v[204:207], v[88:91]
	v_mfma_f32_16x16x32_bf16 v[76:79], v[156:159], v[212:215], v[76:79]
	v_mfma_f32_16x16x32_bf16 v[72:75], v[164:167], v[212:215], v[72:75]
	v_mfma_f32_16x16x32_bf16 v[116:119], v[168:171], v[184:187], v[116:119]
	v_mfma_f32_16x16x32_bf16 v[112:115], v[176:179], v[184:187], v[112:115]
	v_mfma_f32_16x16x32_bf16 v[100:103], v[168:171], v[192:195], v[100:103]
	v_mfma_f32_16x16x32_bf16 v[96:99], v[176:179], v[192:195], v[96:99]
	v_mfma_f32_16x16x32_bf16 v[84:87], v[168:171], v[200:203], v[84:87]
	v_mfma_f32_16x16x32_bf16 v[80:83], v[176:179], v[200:203], v[80:83]
	v_mfma_f32_16x16x32_bf16 v[68:71], v[168:171], v[208:211], v[68:71]
	v_mfma_f32_16x16x32_bf16 v[64:67], v[176:179], v[208:211], v[64:67]
	v_mfma_f32_16x16x32_bf16 v[116:119], v[172:175], v[188:191], v[116:119]
	v_mfma_f32_16x16x32_bf16 v[112:115], v[180:183], v[188:191], v[112:115]
	v_mfma_f32_16x16x32_bf16 v[100:103], v[172:175], v[196:199], v[100:103]
	v_mfma_f32_16x16x32_bf16 v[96:99], v[180:183], v[196:199], v[96:99]
	v_mfma_f32_16x16x32_bf16 v[84:87], v[172:175], v[204:207], v[84:87]
	v_mfma_f32_16x16x32_bf16 v[80:83], v[180:183], v[204:207], v[80:83]
	v_mfma_f32_16x16x32_bf16 v[68:71], v[172:175], v[212:215], v[68:71]
	v_mfma_f32_16x16x32_bf16 v[64:67], v[180:183], v[212:215], v[64:67]
	s_barrier
	s_setprio 1
	s_add_i32 s76, s66, s56
	v_lshl_add_u64 v[216:217], s[50:51], 0, v[130:131]
	s_mov_b32 m0, s76
	ds_read_b128 v[184:187], v153 offset:16384
	ds_read_b128 v[188:191], v153 offset:17408
	ds_read_b128 v[192:195], v153 offset:18432
	ds_read_b128 v[196:199], v153 offset:19456
	ds_read_b128 v[200:203], v153 offset:20480
	ds_read_b128 v[204:207], v153 offset:21504
	ds_read_b128 v[208:211], v153 offset:22528
	ds_read_b128 v[212:215], v153 offset:23552
	global_load_lds_dwordx4 v[216:217], off
	s_add_i32 m0, s76, 0x2000
	s_add_u32 s76, s50, 0x80000
	v_lshl_add_u64 v[218:219], s[50:51], 0, v[134:135]
	s_addc_u32 s77, s51, 0
	s_add_i32 s78, s67, s56
	global_load_lds_dwordx4 v[218:219], off
	v_lshl_add_u64 v[220:221], s[76:77], 0, v[130:131]
	s_mov_b32 m0, s78
	v_lshl_add_u64 v[222:223], s[52:53], 0, v[132:133]
	global_load_lds_dwordx4 v[220:221], off
	v_lshl_add_u64 v[220:221], s[76:77], 0, v[134:135]
	s_add_i32 m0, s78, 0x2000
	s_nop 0
	global_load_lds_dwordx4 v[220:221], off
	v_lshl_add_u64 v[220:221], s[52:53], 0, v[128:129]
	s_mov_b32 m0, s57
	s_nop 0
	global_load_lds_dwordx4 v[220:221], off
	s_mov_b32 m0, s58
	s_nop 0
	global_load_lds_dwordx4 v[222:223], off
	s_waitcnt vmcnt(8)
	s_waitcnt lgkmcnt(0)
	s_setprio 0
	s_barrier
	v_mfma_f32_16x16x32_bf16 v[60:63], v[144:147], v[184:187], v[60:63]
	v_mfma_f32_16x16x32_bf16 v[56:59], v[160:163], v[184:187], v[56:59]
	v_mfma_f32_16x16x32_bf16 v[44:47], v[144:147], v[192:195], v[44:47]
	v_mfma_f32_16x16x32_bf16 v[40:43], v[160:163], v[192:195], v[40:43]
	v_mfma_f32_16x16x32_bf16 v[28:31], v[144:147], v[200:203], v[28:31]
	v_mfma_f32_16x16x32_bf16 v[24:27], v[160:163], v[200:203], v[24:27]
	v_mfma_f32_16x16x32_bf16 v[12:15], v[144:147], v[208:211], v[12:15]
	v_mfma_f32_16x16x32_bf16 v[8:11], v[160:163], v[208:211], v[8:11]
	v_mfma_f32_16x16x32_bf16 v[60:63], v[156:159], v[188:191], v[60:63]
	v_mfma_f32_16x16x32_bf16 v[56:59], v[164:167], v[188:191], v[56:59]
	v_mfma_f32_16x16x32_bf16 v[44:47], v[156:159], v[196:199], v[44:47]
	v_mfma_f32_16x16x32_bf16 v[40:43], v[164:167], v[196:199], v[40:43]
	v_mfma_f32_16x16x32_bf16 v[28:31], v[156:159], v[204:207], v[28:31]
	v_mfma_f32_16x16x32_bf16 v[24:27], v[164:167], v[204:207], v[24:27]
	v_mfma_f32_16x16x32_bf16 v[12:15], v[156:159], v[212:215], v[12:15]
	v_mfma_f32_16x16x32_bf16 v[8:11], v[164:167], v[212:215], v[8:11]
	v_mfma_f32_16x16x32_bf16 v[52:55], v[168:171], v[184:187], v[52:55]
	v_mfma_f32_16x16x32_bf16 v[48:51], v[176:179], v[184:187], v[48:51]
	v_mfma_f32_16x16x32_bf16 v[36:39], v[168:171], v[192:195], v[36:39]
	v_mfma_f32_16x16x32_bf16 v[32:35], v[176:179], v[192:195], v[32:35]
	v_mfma_f32_16x16x32_bf16 v[20:23], v[168:171], v[200:203], v[20:23]
	v_mfma_f32_16x16x32_bf16 v[16:19], v[176:179], v[200:203], v[16:19]
	v_mfma_f32_16x16x32_bf16 v[4:7], v[168:171], v[208:211], v[4:7]
	v_mfma_f32_16x16x32_bf16 v[0:3], v[176:179], v[208:211], v[0:3]
	v_mfma_f32_16x16x32_bf16 v[52:55], v[172:175], v[188:191], v[52:55]
	v_mfma_f32_16x16x32_bf16 v[48:51], v[180:183], v[188:191], v[48:51]
	v_mfma_f32_16x16x32_bf16 v[36:39], v[172:175], v[196:199], v[36:39]
	v_mfma_f32_16x16x32_bf16 v[32:35], v[180:183], v[196:199], v[32:35]
	v_mfma_f32_16x16x32_bf16 v[20:23], v[172:175], v[204:207], v[20:23]
	v_mfma_f32_16x16x32_bf16 v[16:19], v[180:183], v[204:207], v[16:19]
	v_mfma_f32_16x16x32_bf16 v[4:7], v[172:175], v[212:215], v[4:7]
	v_mfma_f32_16x16x32_bf16 v[0:3], v[180:183], v[212:215], v[0:3]
	s_barrier
	s_setprio 1
	s_add_i32 s76, 0, 0x18000
	v_add_u32_e32 v155, s76, v149
	s_add_i32 s77, 0, 0x1c000
	ds_read_b128 v[144:147], v155
	ds_read_b128 v[156:159], v155 offset:1024
	ds_read_b128 v[160:163], v155 offset:2048
	ds_read_b128 v[164:167], v155 offset:3072
	v_add_u32_e32 v155, s77, v149
	ds_read_b128 v[168:171], v155
	ds_read_b128 v[172:175], v155 offset:1024
	ds_read_b128 v[176:179], v155 offset:2048
	ds_read_b128 v[180:183], v155 offset:3072
	s_add_u32 s52, s52, 0x80000
	s_addc_u32 s53, s53, 0
	s_mov_b32 m0, s59
	v_lshl_add_u64 v[224:225], s[52:53], 0, v[128:129]
	ds_read_b128 v[184:187], v153 offset:32768
	ds_read_b128 v[188:191], v153 offset:33792
	ds_read_b128 v[192:195], v153 offset:34816
	ds_read_b128 v[196:199], v153 offset:35840
	ds_read_b128 v[200:203], v153 offset:36864
	ds_read_b128 v[204:207], v153 offset:37888
	ds_read_b128 v[208:211], v153 offset:38912
	ds_read_b128 v[212:215], v153 offset:39936
	global_load_lds_dwordx4 v[224:225], off
	v_lshl_add_u64 v[224:225], s[52:53], 0, v[132:133]
	s_mov_b32 m0, s60
	s_nop 0
	global_load_lds_dwordx4 v[224:225], off
	s_waitcnt vmcnt(8)
	s_waitcnt lgkmcnt(0)
	s_setprio 0
	s_barrier
	v_mfma_f32_16x16x32_bf16 v[124:127], v[144:147], v[184:187], v[124:127]
	v_mfma_f32_16x16x32_bf16 v[120:123], v[160:163], v[184:187], v[120:123]
	v_mfma_f32_16x16x32_bf16 v[108:111], v[144:147], v[192:195], v[108:111]
	v_mfma_f32_16x16x32_bf16 v[104:107], v[160:163], v[192:195], v[104:107]
	v_mfma_f32_16x16x32_bf16 v[92:95], v[144:147], v[200:203], v[92:95]
	v_mfma_f32_16x16x32_bf16 v[88:91], v[160:163], v[200:203], v[88:91]
	v_mfma_f32_16x16x32_bf16 v[76:79], v[144:147], v[208:211], v[76:79]
	v_mfma_f32_16x16x32_bf16 v[72:75], v[160:163], v[208:211], v[72:75]
	v_mfma_f32_16x16x32_bf16 v[124:127], v[156:159], v[188:191], v[124:127]
	v_mfma_f32_16x16x32_bf16 v[120:123], v[164:167], v[188:191], v[120:123]
	v_mfma_f32_16x16x32_bf16 v[108:111], v[156:159], v[196:199], v[108:111]
	v_mfma_f32_16x16x32_bf16 v[104:107], v[164:167], v[196:199], v[104:107]
	v_mfma_f32_16x16x32_bf16 v[92:95], v[156:159], v[204:207], v[92:95]
	v_mfma_f32_16x16x32_bf16 v[88:91], v[164:167], v[204:207], v[88:91]
	v_mfma_f32_16x16x32_bf16 v[76:79], v[156:159], v[212:215], v[76:79]
	v_mfma_f32_16x16x32_bf16 v[72:75], v[164:167], v[212:215], v[72:75]
	v_mfma_f32_16x16x32_bf16 v[116:119], v[168:171], v[184:187], v[116:119]
	v_mfma_f32_16x16x32_bf16 v[112:115], v[176:179], v[184:187], v[112:115]
	v_mfma_f32_16x16x32_bf16 v[100:103], v[168:171], v[192:195], v[100:103]
	v_mfma_f32_16x16x32_bf16 v[96:99], v[176:179], v[192:195], v[96:99]
	v_mfma_f32_16x16x32_bf16 v[84:87], v[168:171], v[200:203], v[84:87]
	v_mfma_f32_16x16x32_bf16 v[80:83], v[176:179], v[200:203], v[80:83]
	v_mfma_f32_16x16x32_bf16 v[68:71], v[168:171], v[208:211], v[68:71]
	v_mfma_f32_16x16x32_bf16 v[64:67], v[176:179], v[208:211], v[64:67]
	v_mfma_f32_16x16x32_bf16 v[116:119], v[172:175], v[188:191], v[116:119]
	v_mfma_f32_16x16x32_bf16 v[112:115], v[180:183], v[188:191], v[112:115]
	v_mfma_f32_16x16x32_bf16 v[100:103], v[172:175], v[196:199], v[100:103]
	v_mfma_f32_16x16x32_bf16 v[96:99], v[180:183], v[196:199], v[96:99]
	v_mfma_f32_16x16x32_bf16 v[84:87], v[172:175], v[204:207], v[84:87]
	v_mfma_f32_16x16x32_bf16 v[80:83], v[180:183], v[204:207], v[80:83]
	v_mfma_f32_16x16x32_bf16 v[68:71], v[172:175], v[212:215], v[68:71]
	v_mfma_f32_16x16x32_bf16 v[64:67], v[180:183], v[212:215], v[64:67]
	s_barrier
	s_setprio 1
	s_add_i32 s52, s76, s56
	v_lshl_add_u64 v[216:217], v[216:217], 0, s[22:23]
	s_mov_b32 m0, s52
	ds_read_b128 v[184:187], v153 offset:49152
	ds_read_b128 v[188:191], v153 offset:50176
	ds_read_b128 v[192:195], v153 offset:51200
	ds_read_b128 v[196:199], v153 offset:52224
	ds_read_b128 v[200:203], v153 offset:53248
	ds_read_b128 v[204:207], v153 offset:54272
	ds_read_b128 v[208:211], v153 offset:55296
	ds_read_b128 v[212:215], v153 offset:56320
	global_load_lds_dwordx4 v[216:217], off
	s_add_i32 m0, s52, 0x2000
	s_add_u32 s50, s50, 0x80080
	v_lshl_add_u64 v[216:217], v[218:219], 0, s[22:23]
	s_addc_u32 s51, s51, 0
	s_add_i32 s52, s77, s56
	global_load_lds_dwordx4 v[216:217], off
	v_lshl_add_u64 v[216:217], s[50:51], 0, v[130:131]
	s_mov_b32 m0, s52
	s_nop 0
	global_load_lds_dwordx4 v[216:217], off
	v_lshl_add_u64 v[216:217], s[50:51], 0, v[134:135]
	s_add_i32 m0, s52, 0x2000
	s_nop 0
	global_load_lds_dwordx4 v[216:217], off
	v_lshl_add_u64 v[216:217], v[220:221], 0, s[22:23]
	s_mov_b32 m0, s62
	s_nop 0
	global_load_lds_dwordx4 v[216:217], off
	v_lshl_add_u64 v[216:217], v[222:223], 0, s[22:23]
	s_mov_b32 m0, s63
	s_nop 0
	global_load_lds_dwordx4 v[216:217], off
	s_waitcnt vmcnt(8)
	s_waitcnt lgkmcnt(0)
	s_setprio 0
	s_barrier
	v_mfma_f32_16x16x32_bf16 v[60:63], v[144:147], v[184:187], v[60:63]
	v_mfma_f32_16x16x32_bf16 v[56:59], v[160:163], v[184:187], v[56:59]
	v_mfma_f32_16x16x32_bf16 v[44:47], v[144:147], v[192:195], v[44:47]
	v_mfma_f32_16x16x32_bf16 v[40:43], v[160:163], v[192:195], v[40:43]
	v_mfma_f32_16x16x32_bf16 v[28:31], v[144:147], v[200:203], v[28:31]
	v_mfma_f32_16x16x32_bf16 v[24:27], v[160:163], v[200:203], v[24:27]
	v_mfma_f32_16x16x32_bf16 v[12:15], v[144:147], v[208:211], v[12:15]
	v_mfma_f32_16x16x32_bf16 v[8:11], v[160:163], v[208:211], v[8:11]
	v_mfma_f32_16x16x32_bf16 v[60:63], v[156:159], v[188:191], v[60:63]
	v_mfma_f32_16x16x32_bf16 v[56:59], v[164:167], v[188:191], v[56:59]
	v_mfma_f32_16x16x32_bf16 v[44:47], v[156:159], v[196:199], v[44:47]
	v_mfma_f32_16x16x32_bf16 v[40:43], v[164:167], v[196:199], v[40:43]
	v_mfma_f32_16x16x32_bf16 v[28:31], v[156:159], v[204:207], v[28:31]
	v_mfma_f32_16x16x32_bf16 v[24:27], v[164:167], v[204:207], v[24:27]
	v_mfma_f32_16x16x32_bf16 v[12:15], v[156:159], v[212:215], v[12:15]
	v_mfma_f32_16x16x32_bf16 v[8:11], v[164:167], v[212:215], v[8:11]
	v_mfma_f32_16x16x32_bf16 v[52:55], v[168:171], v[184:187], v[52:55]
	v_mfma_f32_16x16x32_bf16 v[48:51], v[176:179], v[184:187], v[48:51]
	v_mfma_f32_16x16x32_bf16 v[36:39], v[168:171], v[192:195], v[36:39]
	v_mfma_f32_16x16x32_bf16 v[32:35], v[176:179], v[192:195], v[32:35]
	v_mfma_f32_16x16x32_bf16 v[20:23], v[168:171], v[200:203], v[20:23]
	v_mfma_f32_16x16x32_bf16 v[16:19], v[176:179], v[200:203], v[16:19]
	v_mfma_f32_16x16x32_bf16 v[4:7], v[168:171], v[208:211], v[4:7]
	v_mfma_f32_16x16x32_bf16 v[0:3], v[176:179], v[208:211], v[0:3]
	v_mfma_f32_16x16x32_bf16 v[52:55], v[172:175], v[188:191], v[52:55]
	v_mfma_f32_16x16x32_bf16 v[48:51], v[180:183], v[188:191], v[48:51]
	v_mfma_f32_16x16x32_bf16 v[36:39], v[172:175], v[196:199], v[36:39]
	v_mfma_f32_16x16x32_bf16 v[32:35], v[180:183], v[196:199], v[32:35]
	v_mfma_f32_16x16x32_bf16 v[20:23], v[172:175], v[204:207], v[20:23]
	v_mfma_f32_16x16x32_bf16 v[16:19], v[180:183], v[204:207], v[16:19]
	v_mfma_f32_16x16x32_bf16 v[4:7], v[172:175], v[212:215], v[4:7]
	v_mfma_f32_16x16x32_bf16 v[0:3], v[180:183], v[212:215], v[0:3]
	s_barrier
	s_setprio 1
	s_add_i32 s75, s75, 2
	s_add_u32 s72, s72, 0x100
	s_addc_u32 s74, s74, 0
	s_add_u32 s48, s48, 0x100
	s_addc_u32 s49, s49, 0
	s_cmp_gt_u32 s75, 29
	s_cbranch_scc0 .LBB0_337
	s_and_b64 vcc, exec, s[24:25]
	s_cbranch_vccz .LBB0_340
	s_barrier
	s_setprio 3

.LBB0_439:
	s_and_b64 vcc, exec, s[18:19]
	s_cbranch_vccz .LBB0_441
	s_barrier
	s_setprio 3

.LBB0_523:
	ds_read_b128 v[144:147], v151
	ds_read_b128 v[156:159], v151 offset:1024
	ds_read_b128 v[160:163], v151 offset:2048
	ds_read_b128 v[164:167], v151 offset:3072
	ds_read_b128 v[168:171], v152
	ds_read_b128 v[172:175], v152 offset:1024
	ds_read_b128 v[176:179], v152 offset:2048
	ds_read_b128 v[180:183], v152 offset:3072
	s_add_u32 s36, s34, 0x100
	s_addc_u32 s37, s35, 0
	s_cmpk_eq_i32 s66, 0x54
	s_cselect_b32 s55, s13, s37
	s_cselect_b32 s54, s12, s36
	s_cselect_b32 s53, s31, s47
	s_cselect_b32 s52, s30, s46
	v_lshl_add_u64 v[216:217], s[34:35], 0, v[138:139]
	s_add_i32 m0, s49, 0xc000
	ds_read_b128 v[184:187], v153
	ds_read_b128 v[188:191], v153 offset:1024
	ds_read_b128 v[192:195], v153 offset:2048
	ds_read_b128 v[196:199], v153 offset:3072
	ds_read_b128 v[200:203], v153 offset:4096
	ds_read_b128 v[204:207], v153 offset:5120
	ds_read_b128 v[208:211], v153 offset:6144
	ds_read_b128 v[212:215], v153 offset:7168
	global_load_lds_dwordx4 v[216:217], off
	v_lshl_add_u64 v[216:217], s[34:35], 0, v[136:137]
	s_add_i32 m0, s49, 0xe000
	s_nop 0
	global_load_lds_dwordx4 v[216:217], off
	s_waitcnt vmcnt(8)
	s_waitcnt lgkmcnt(0)
	s_setprio 0
	s_barrier
	v_mfma_f32_16x16x32_bf16 v[124:127], v[144:147], v[184:187], v[124:127]
	v_mfma_f32_16x16x32_bf16 v[120:123], v[160:163], v[184:187], v[120:123]
	v_mfma_f32_16x16x32_bf16 v[108:111], v[144:147], v[192:195], v[108:111]
	v_mfma_f32_16x16x32_bf16 v[104:107], v[160:163], v[192:195], v[104:107]
	v_mfma_f32_16x16x32_bf16 v[92:95], v[144:147], v[200:203], v[92:95]
	v_mfma_f32_16x16x32_bf16 v[88:91], v[160:163], v[200:203], v[88:91]
	v_mfma_f32_16x16x32_bf16 v[76:79], v[144:147], v[208:211], v[76:79]
	v_mfma_f32_16x16x32_bf16 v[72:75], v[160:163], v[208:211], v[72:75]
	v_mfma_f32_16x16x32_bf16 v[124:127], v[156:159], v[188:191], v[124:127]
	v_mfma_f32_16x16x32_bf16 v[120:123], v[164:167], v[188:191], v[120:123]
	v_mfma_f32_16x16x32_bf16 v[108:111], v[156:159], v[196:199], v[108:111]
	v_mfma_f32_16x16x32_bf16 v[104:107], v[164:167], v[196:199], v[104:107]
	v_mfma_f32_16x16x32_bf16 v[92:95], v[156:159], v[204:207], v[92:95]
	v_mfma_f32_16x16x32_bf16 v[88:91], v[164:167], v[204:207], v[88:91]
	v_mfma_f32_16x16x32_bf16 v[76:79], v[156:159], v[212:215], v[76:79]
	v_mfma_f32_16x16x32_bf16 v[72:75], v[164:167], v[212:215], v[72:75]
	v_mfma_f32_16x16x32_bf16 v[116:119], v[168:171], v[184:187], v[116:119]
	v_mfma_f32_16x16x32_bf16 v[112:115], v[176:179], v[184:187], v[112:115]
	v_mfma_f32_16x16x32_bf16 v[100:103], v[168:171], v[192:195], v[100:103]
	v_mfma_f32_16x16x32_bf16 v[96:99], v[176:179], v[192:195], v[96:99]
	v_mfma_f32_16x16x32_bf16 v[84:87], v[168:171], v[200:203], v[84:87]
	v_mfma_f32_16x16x32_bf16 v[80:83], v[176:179], v[200:203], v[80:83]
	v_mfma_f32_16x16x32_bf16 v[68:71], v[168:171], v[208:211], v[68:71]
	v_mfma_f32_16x16x32_bf16 v[64:67], v[176:179], v[208:211], v[64:67]
	v_mfma_f32_16x16x32_bf16 v[116:119], v[172:175], v[188:191], v[116:119]
	v_mfma_f32_16x16x32_bf16 v[112:115], v[180:183], v[188:191], v[112:115]
	v_mfma_f32_16x16x32_bf16 v[100:103], v[172:175], v[196:199], v[100:103]
	v_mfma_f32_16x16x32_bf16 v[96:99], v[180:183], v[196:199], v[96:99]
	v_mfma_f32_16x16x32_bf16 v[84:87], v[172:175], v[204:207], v[84:87]
	v_mfma_f32_16x16x32_bf16 v[80:83], v[180:183], v[204:207], v[80:83]
	v_mfma_f32_16x16x32_bf16 v[68:71], v[172:175], v[212:215], v[68:71]
	v_mfma_f32_16x16x32_bf16 v[64:67], v[180:183], v[212:215], v[64:67]
	s_barrier
	s_setprio 1
	s_add_i32 s34, s62, s48
	v_lshl_add_u64 v[216:217], s[52:53], 0, v[130:131]
	s_mov_b32 m0, s34
	ds_read_b128 v[184:187], v153 offset:16384
	ds_read_b128 v[188:191], v153 offset:17408
	ds_read_b128 v[192:195], v153 offset:18432
	ds_read_b128 v[196:199], v153 offset:19456
	ds_read_b128 v[200:203], v153 offset:20480
	ds_read_b128 v[204:207], v153 offset:21504
	ds_read_b128 v[208:211], v153 offset:22528
	ds_read_b128 v[212:215], v153 offset:23552
	global_load_lds_dwordx4 v[216:217], off
	s_add_i32 m0, s34, 0x2000
	s_add_u32 s34, s52, 0x160000
	v_lshl_add_u64 v[218:219], s[52:53], 0, v[134:135]
	s_addc_u32 s35, s53, 0
	s_add_i32 s67, s63, s48
	global_load_lds_dwordx4 v[218:219], off
	v_lshl_add_u64 v[220:221], s[34:35], 0, v[130:131]
	s_mov_b32 m0, s67
	v_lshl_add_u64 v[222:223], s[54:55], 0, v[132:133]
	global_load_lds_dwordx4 v[220:221], off
	v_lshl_add_u64 v[220:221], s[34:35], 0, v[134:135]
	s_add_i32 m0, s67, 0x2000
	s_nop 0
	global_load_lds_dwordx4 v[220:221], off
	v_lshl_add_u64 v[220:221], s[54:55], 0, v[128:129]
	s_mov_b32 m0, s49
	s_nop 0
	global_load_lds_dwordx4 v[220:221], off
	s_mov_b32 m0, s56
	s_nop 0
	global_load_lds_dwordx4 v[222:223], off
	s_waitcnt vmcnt(8)
	s_waitcnt lgkmcnt(0)
	s_setprio 0
	s_barrier
	v_mfma_f32_16x16x32_bf16 v[60:63], v[144:147], v[184:187], v[60:63]
	v_mfma_f32_16x16x32_bf16 v[56:59], v[160:163], v[184:187], v[56:59]
	v_mfma_f32_16x16x32_bf16 v[44:47], v[144:147], v[192:195], v[44:47]
	v_mfma_f32_16x16x32_bf16 v[40:43], v[160:163], v[192:195], v[40:43]
	v_mfma_f32_16x16x32_bf16 v[28:31], v[144:147], v[200:203], v[28:31]
	v_mfma_f32_16x16x32_bf16 v[24:27], v[160:163], v[200:203], v[24:27]
	v_mfma_f32_16x16x32_bf16 v[12:15], v[144:147], v[208:211], v[12:15]
	v_mfma_f32_16x16x32_bf16 v[8:11], v[160:163], v[208:211], v[8:11]
	v_mfma_f32_16x16x32_bf16 v[60:63], v[156:159], v[188:191], v[60:63]
	v_mfma_f32_16x16x32_bf16 v[56:59], v[164:167], v[188:191], v[56:59]
	v_mfma_f32_16x16x32_bf16 v[44:47], v[156:159], v[196:199], v[44:47]
	v_mfma_f32_16x16x32_bf16 v[40:43], v[164:167], v[196:199], v[40:43]
	v_mfma_f32_16x16x32_bf16 v[28:31], v[156:159], v[204:207], v[28:31]
	v_mfma_f32_16x16x32_bf16 v[24:27], v[164:167], v[204:207], v[24:27]
	v_mfma_f32_16x16x32_bf16 v[12:15], v[156:159], v[212:215], v[12:15]
	v_mfma_f32_16x16x32_bf16 v[8:11], v[164:167], v[212:215], v[8:11]
	v_mfma_f32_16x16x32_bf16 v[52:55], v[168:171], v[184:187], v[52:55]
	v_mfma_f32_16x16x32_bf16 v[48:51], v[176:179], v[184:187], v[48:51]
	v_mfma_f32_16x16x32_bf16 v[36:39], v[168:171], v[192:195], v[36:39]
	v_mfma_f32_16x16x32_bf16 v[32:35], v[176:179], v[192:195], v[32:35]
	v_mfma_f32_16x16x32_bf16 v[20:23], v[168:171], v[200:203], v[20:23]
	v_mfma_f32_16x16x32_bf16 v[16:19], v[176:179], v[200:203], v[16:19]
	v_mfma_f32_16x16x32_bf16 v[4:7], v[168:171], v[208:211], v[4:7]
	v_mfma_f32_16x16x32_bf16 v[0:3], v[176:179], v[208:211], v[0:3]
	v_mfma_f32_16x16x32_bf16 v[52:55], v[172:175], v[188:191], v[52:55]
	v_mfma_f32_16x16x32_bf16 v[48:51], v[180:183], v[188:191], v[48:51]
	v_mfma_f32_16x16x32_bf16 v[36:39], v[172:175], v[196:199], v[36:39]
	v_mfma_f32_16x16x32_bf16 v[32:35], v[180:183], v[196:199], v[32:35]
	v_mfma_f32_16x16x32_bf16 v[20:23], v[172:175], v[204:207], v[20:23]
	v_mfma_f32_16x16x32_bf16 v[16:19], v[180:183], v[204:207], v[16:19]
	v_mfma_f32_16x16x32_bf16 v[4:7], v[172:175], v[212:215], v[4:7]
	v_mfma_f32_16x16x32_bf16 v[0:3], v[180:183], v[212:215], v[0:3]
	s_barrier
	s_setprio 1
	s_add_i32 s67, 0, 0x18000
	v_add_u32_e32 v155, s67, v149
	s_add_i32 s70, 0, 0x1c000
	ds_read_b128 v[144:147], v155
	ds_read_b128 v[156:159], v155 offset:1024
	ds_read_b128 v[160:163], v155 offset:2048
	ds_read_b128 v[164:167], v155 offset:3072
	v_add_u32_e32 v155, s70, v149
	ds_read_b128 v[168:171], v155
	ds_read_b128 v[172:175], v155 offset:1024
	ds_read_b128 v[176:179], v155 offset:2048
	ds_read_b128 v[180:183], v155 offset:3072
	s_add_u32 s34, s54, 0x160000
	s_addc_u32 s35, s55, 0
	s_mov_b32 m0, s57
	v_lshl_add_u64 v[224:225], s[34:35], 0, v[128:129]
	ds_read_b128 v[184:187], v153 offset:32768
	ds_read_b128 v[188:191], v153 offset:33792
	ds_read_b128 v[192:195], v153 offset:34816
	ds_read_b128 v[196:199], v153 offset:35840
	ds_read_b128 v[200:203], v153 offset:36864
	ds_read_b128 v[204:207], v153 offset:37888
	ds_read_b128 v[208:211], v153 offset:38912
	ds_read_b128 v[212:215], v153 offset:39936
	global_load_lds_dwordx4 v[224:225], off
	v_lshl_add_u64 v[224:225], s[34:35], 0, v[132:133]
	s_mov_b32 m0, s58
	s_nop 0
	global_load_lds_dwordx4 v[224:225], off
	s_waitcnt vmcnt(8)
	s_waitcnt lgkmcnt(0)
	s_setprio 0
	s_barrier
	v_mfma_f32_16x16x32_bf16 v[124:127], v[144:147], v[184:187], v[124:127]
	v_mfma_f32_16x16x32_bf16 v[120:123], v[160:163], v[184:187], v[120:123]
	v_mfma_f32_16x16x32_bf16 v[108:111], v[144:147], v[192:195], v[108:111]
	v_mfma_f32_16x16x32_bf16 v[104:107], v[160:163], v[192:195], v[104:107]
	v_mfma_f32_16x16x32_bf16 v[92:95], v[144:147], v[200:203], v[92:95]
	v_mfma_f32_16x16x32_bf16 v[88:91], v[160:163], v[200:203], v[88:91]
	v_mfma_f32_16x16x32_bf16 v[76:79], v[144:147], v[208:211], v[76:79]
	v_mfma_f32_16x16x32_bf16 v[72:75], v[160:163], v[208:211], v[72:75]
	v_mfma_f32_16x16x32_bf16 v[124:127], v[156:159], v[188:191], v[124:127]
	v_mfma_f32_16x16x32_bf16 v[120:123], v[164:167], v[188:191], v[120:123]
	v_mfma_f32_16x16x32_bf16 v[108:111], v[156:159], v[196:199], v[108:111]
	v_mfma_f32_16x16x32_bf16 v[104:107], v[164:167], v[196:199], v[104:107]
	v_mfma_f32_16x16x32_bf16 v[92:95], v[156:159], v[204:207], v[92:95]
	v_mfma_f32_16x16x32_bf16 v[88:91], v[164:167], v[204:207], v[88:91]
	v_mfma_f32_16x16x32_bf16 v[76:79], v[156:159], v[212:215], v[76:79]
	v_mfma_f32_16x16x32_bf16 v[72:75], v[164:167], v[212:215], v[72:75]
	v_mfma_f32_16x16x32_bf16 v[116:119], v[168:171], v[184:187], v[116:119]
	v_mfma_f32_16x16x32_bf16 v[112:115], v[176:179], v[184:187], v[112:115]
	v_mfma_f32_16x16x32_bf16 v[100:103], v[168:171], v[192:195], v[100:103]
	v_mfma_f32_16x16x32_bf16 v[96:99], v[176:179], v[192:195], v[96:99]
	v_mfma_f32_16x16x32_bf16 v[84:87], v[168:171], v[200:203], v[84:87]
	v_mfma_f32_16x16x32_bf16 v[80:83], v[176:179], v[200:203], v[80:83]
	v_mfma_f32_16x16x32_bf16 v[68:71], v[168:171], v[208:211], v[68:71]
	v_mfma_f32_16x16x32_bf16 v[64:67], v[176:179], v[208:211], v[64:67]
	v_mfma_f32_16x16x32_bf16 v[116:119], v[172:175], v[188:191], v[116:119]
	v_mfma_f32_16x16x32_bf16 v[112:115], v[180:183], v[188:191], v[112:115]
	v_mfma_f32_16x16x32_bf16 v[100:103], v[172:175], v[196:199], v[100:103]
	v_mfma_f32_16x16x32_bf16 v[96:99], v[180:183], v[196:199], v[96:99]
	v_mfma_f32_16x16x32_bf16 v[84:87], v[172:175], v[204:207], v[84:87]
	v_mfma_f32_16x16x32_bf16 v[80:83], v[180:183], v[204:207], v[80:83]
	v_mfma_f32_16x16x32_bf16 v[68:71], v[172:175], v[212:215], v[68:71]
	v_mfma_f32_16x16x32_bf16 v[64:67], v[180:183], v[212:215], v[64:67]
	s_barrier
	s_setprio 1
	s_add_i32 s34, s67, s48
	v_lshl_add_u64 v[216:217], v[216:217], 0, s[24:25]
	s_mov_b32 m0, s34
	ds_read_b128 v[184:187], v153 offset:49152
	ds_read_b128 v[188:191], v153 offset:50176
	ds_read_b128 v[192:195], v153 offset:51200
	ds_read_b128 v[196:199], v153 offset:52224
	ds_read_b128 v[200:203], v153 offset:53248
	ds_read_b128 v[204:207], v153 offset:54272
	ds_read_b128 v[208:211], v153 offset:55296
	ds_read_b128 v[212:215], v153 offset:56320
	global_load_lds_dwordx4 v[216:217], off
	s_add_i32 m0, s34, 0x2000
	s_add_u32 s34, s52, 0x160080
	v_lshl_add_u64 v[216:217], v[218:219], 0, s[24:25]
	s_addc_u32 s35, s53, 0
	s_add_i32 s52, s70, s48
	global_load_lds_dwordx4 v[216:217], off
	v_lshl_add_u64 v[216:217], s[34:35], 0, v[130:131]
	s_mov_b32 m0, s52
	s_nop 0
	global_load_lds_dwordx4 v[216:217], off
	v_lshl_add_u64 v[216:217], s[34:35], 0, v[134:135]
	s_add_i32 m0, s52, 0x2000
	s_nop 0
	global_load_lds_dwordx4 v[216:217], off
	v_lshl_add_u64 v[216:217], v[220:221], 0, s[24:25]
	s_mov_b32 m0, s60
	s_nop 0
	global_load_lds_dwordx4 v[216:217], off
	v_lshl_add_u64 v[216:217], v[222:223], 0, s[24:25]
	s_mov_b32 m0, s61
	s_nop 0
	global_load_lds_dwordx4 v[216:217], off
	s_waitcnt vmcnt(8)
	s_waitcnt lgkmcnt(0)
	s_setprio 0
	s_barrier
	v_mfma_f32_16x16x32_bf16 v[60:63], v[144:147], v[184:187], v[60:63]
	v_mfma_f32_16x16x32_bf16 v[56:59], v[160:163], v[184:187], v[56:59]
	v_mfma_f32_16x16x32_bf16 v[44:47], v[144:147], v[192:195], v[44:47]
	v_mfma_f32_16x16x32_bf16 v[40:43], v[160:163], v[192:195], v[40:43]
	v_mfma_f32_16x16x32_bf16 v[28:31], v[144:147], v[200:203], v[28:31]
	v_mfma_f32_16x16x32_bf16 v[24:27], v[160:163], v[200:203], v[24:27]
	v_mfma_f32_16x16x32_bf16 v[12:15], v[144:147], v[208:211], v[12:15]
	v_mfma_f32_16x16x32_bf16 v[8:11], v[160:163], v[208:211], v[8:11]
	v_mfma_f32_16x16x32_bf16 v[60:63], v[156:159], v[188:191], v[60:63]
	v_mfma_f32_16x16x32_bf16 v[56:59], v[164:167], v[188:191], v[56:59]
	v_mfma_f32_16x16x32_bf16 v[44:47], v[156:159], v[196:199], v[44:47]
	v_mfma_f32_16x16x32_bf16 v[40:43], v[164:167], v[196:199], v[40:43]
	v_mfma_f32_16x16x32_bf16 v[28:31], v[156:159], v[204:207], v[28:31]
	v_mfma_f32_16x16x32_bf16 v[24:27], v[164:167], v[204:207], v[24:27]
	v_mfma_f32_16x16x32_bf16 v[12:15], v[156:159], v[212:215], v[12:15]
	v_mfma_f32_16x16x32_bf16 v[8:11], v[164:167], v[212:215], v[8:11]
	v_mfma_f32_16x16x32_bf16 v[52:55], v[168:171], v[184:187], v[52:55]
	v_mfma_f32_16x16x32_bf16 v[48:51], v[176:179], v[184:187], v[48:51]
	v_mfma_f32_16x16x32_bf16 v[36:39], v[168:171], v[192:195], v[36:39]
	v_mfma_f32_16x16x32_bf16 v[32:35], v[176:179], v[192:195], v[32:35]
	v_mfma_f32_16x16x32_bf16 v[20:23], v[168:171], v[200:203], v[20:23]
	v_mfma_f32_16x16x32_bf16 v[16:19], v[176:179], v[200:203], v[16:19]
	v_mfma_f32_16x16x32_bf16 v[4:7], v[168:171], v[208:211], v[4:7]
	v_mfma_f32_16x16x32_bf16 v[0:3], v[176:179], v[208:211], v[0:3]
	v_mfma_f32_16x16x32_bf16 v[52:55], v[172:175], v[188:191], v[52:55]
	v_mfma_f32_16x16x32_bf16 v[48:51], v[180:183], v[188:191], v[48:51]
	v_mfma_f32_16x16x32_bf16 v[36:39], v[172:175], v[196:199], v[36:39]
	v_mfma_f32_16x16x32_bf16 v[32:35], v[180:183], v[196:199], v[32:35]
	v_mfma_f32_16x16x32_bf16 v[20:23], v[172:175], v[204:207], v[20:23]
	v_mfma_f32_16x16x32_bf16 v[16:19], v[180:183], v[204:207], v[16:19]
	v_mfma_f32_16x16x32_bf16 v[4:7], v[172:175], v[212:215], v[4:7]
	v_mfma_f32_16x16x32_bf16 v[0:3], v[180:183], v[212:215], v[0:3]
	s_barrier
	s_setprio 1
	s_add_i32 s66, s66, 2
	s_add_u32 s46, s46, 0x100
	s_addc_u32 s47, s47, 0
	s_cmpk_gt_u32 s66, 0x55
	s_mov_b64 s[34:35], s[36:37]
	s_cbranch_scc0 .LBB0_523
	s_and_b64 vcc, exec, s[26:27]
	s_cbranch_vccz .LBB0_526
	s_barrier
	s_setprio 3

.LBB0_617:
	ds_read_b128 v[146:149], v159
	ds_read_b128 v[150:153], v159 offset:1024
	ds_read_b128 v[164:167], v159 offset:2048
	ds_read_b128 v[168:171], v159 offset:3072
	ds_read_b128 v[172:175], v160
	ds_read_b128 v[176:179], v160 offset:1024
	ds_read_b128 v[180:183], v160 offset:2048
	ds_read_b128 v[184:187], v160 offset:3072
	s_add_u32 s58, s56, 0xfff80080
	s_addc_u32 s59, s57, -1
	s_cmp_eq_u32 s55, 28
	s_cselect_b32 s61, s35, s59
	s_cselect_b32 s60, s46, s58
	s_cselect_b32 s59, s31, s51
	s_cselect_b32 s58, s47, s50
	v_lshl_add_u64 v[154:155], s[56:57], 0, v[140:141]
	s_add_i32 m0, s45, 0xc000
	ds_read_b128 v[188:191], v161
	ds_read_b128 v[192:195], v161 offset:1024
	ds_read_b128 v[196:199], v161 offset:2048
	ds_read_b128 v[200:203], v161 offset:3072
	ds_read_b128 v[204:207], v161 offset:4096
	ds_read_b128 v[208:211], v161 offset:5120
	ds_read_b128 v[212:215], v161 offset:6144
	ds_read_b128 v[216:219], v161 offset:7168
	global_load_lds_dwordx4 v[154:155], off
	v_lshl_add_u64 v[154:155], s[56:57], 0, v[138:139]
	s_add_i32 m0, s45, 0xe000
	s_nop 0
	global_load_lds_dwordx4 v[154:155], off
	s_waitcnt vmcnt(8)
	s_waitcnt lgkmcnt(0)
	s_setprio 0
	s_barrier
	v_mfma_f32_16x16x32_bf16 v[124:127], v[146:149], v[188:191], v[124:127]
	v_mfma_f32_16x16x32_bf16 v[120:123], v[164:167], v[188:191], v[120:123]
	v_mfma_f32_16x16x32_bf16 v[108:111], v[146:149], v[196:199], v[108:111]
	v_mfma_f32_16x16x32_bf16 v[104:107], v[164:167], v[196:199], v[104:107]
	v_mfma_f32_16x16x32_bf16 v[92:95], v[146:149], v[204:207], v[92:95]
	v_mfma_f32_16x16x32_bf16 v[88:91], v[164:167], v[204:207], v[88:91]
	v_mfma_f32_16x16x32_bf16 v[76:79], v[146:149], v[212:215], v[76:79]
	v_mfma_f32_16x16x32_bf16 v[72:75], v[164:167], v[212:215], v[72:75]
	v_mfma_f32_16x16x32_bf16 v[124:127], v[150:153], v[192:195], v[124:127]
	v_mfma_f32_16x16x32_bf16 v[120:123], v[168:171], v[192:195], v[120:123]
	v_mfma_f32_16x16x32_bf16 v[108:111], v[150:153], v[200:203], v[108:111]
	v_mfma_f32_16x16x32_bf16 v[104:107], v[168:171], v[200:203], v[104:107]
	v_mfma_f32_16x16x32_bf16 v[92:95], v[150:153], v[208:211], v[92:95]
	v_mfma_f32_16x16x32_bf16 v[88:91], v[168:171], v[208:211], v[88:91]
	v_mfma_f32_16x16x32_bf16 v[76:79], v[150:153], v[216:219], v[76:79]
	v_mfma_f32_16x16x32_bf16 v[72:75], v[168:171], v[216:219], v[72:75]
	v_mfma_f32_16x16x32_bf16 v[116:119], v[172:175], v[188:191], v[116:119]
	v_mfma_f32_16x16x32_bf16 v[112:115], v[180:183], v[188:191], v[112:115]
	v_mfma_f32_16x16x32_bf16 v[100:103], v[172:175], v[196:199], v[100:103]
	v_mfma_f32_16x16x32_bf16 v[96:99], v[180:183], v[196:199], v[96:99]
	v_mfma_f32_16x16x32_bf16 v[84:87], v[172:175], v[204:207], v[84:87]
	v_mfma_f32_16x16x32_bf16 v[80:83], v[180:183], v[204:207], v[80:83]
	v_mfma_f32_16x16x32_bf16 v[68:71], v[172:175], v[212:215], v[68:71]
	v_mfma_f32_16x16x32_bf16 v[64:67], v[180:183], v[212:215], v[64:67]
	v_mfma_f32_16x16x32_bf16 v[116:119], v[176:179], v[192:195], v[116:119]
	v_mfma_f32_16x16x32_bf16 v[112:115], v[184:187], v[192:195], v[112:115]
	v_mfma_f32_16x16x32_bf16 v[100:103], v[176:179], v[200:203], v[100:103]
	v_mfma_f32_16x16x32_bf16 v[96:99], v[184:187], v[200:203], v[96:99]
	v_mfma_f32_16x16x32_bf16 v[84:87], v[176:179], v[208:211], v[84:87]
	v_mfma_f32_16x16x32_bf16 v[80:83], v[184:187], v[208:211], v[80:83]
	v_mfma_f32_16x16x32_bf16 v[68:71], v[176:179], v[216:219], v[68:71]
	v_mfma_f32_16x16x32_bf16 v[64:67], v[184:187], v[216:219], v[64:67]
	s_barrier
	s_setprio 1
	s_add_i32 s72, s66, s44
	v_lshl_add_u64 v[154:155], s[58:59], 0, v[130:131]
	s_mov_b32 m0, s72
	ds_read_b128 v[188:191], v161 offset:16384
	ds_read_b128 v[192:195], v161 offset:17408
	ds_read_b128 v[196:199], v161 offset:18432
	ds_read_b128 v[200:203], v161 offset:19456
	ds_read_b128 v[204:207], v161 offset:20480
	ds_read_b128 v[208:211], v161 offset:21504
	ds_read_b128 v[212:215], v161 offset:22528
	ds_read_b128 v[216:219], v161 offset:23552
	global_load_lds_dwordx4 v[154:155], off
	s_add_i32 m0, s72, 0x2000
	s_add_u32 s80, s58, 0x80000
	v_lshl_add_u64 v[220:221], s[58:59], 0, v[134:135]
	s_addc_u32 s81, s59, 0
	s_add_i32 s72, s67, s44
	global_load_lds_dwordx4 v[220:221], off
	v_lshl_add_u64 v[222:223], s[80:81], 0, v[130:131]
	s_mov_b32 m0, s72
	v_lshl_add_u64 v[224:225], s[60:61], 0, v[132:133]
	global_load_lds_dwordx4 v[222:223], off
	v_lshl_add_u64 v[222:223], s[80:81], 0, v[134:135]
	s_add_i32 m0, s72, 0x2000
	s_nop 0
	global_load_lds_dwordx4 v[222:223], off
	v_lshl_add_u64 v[222:223], s[60:61], 0, v[128:129]
	s_mov_b32 m0, s45
	s_nop 0
	global_load_lds_dwordx4 v[222:223], off
	s_mov_b32 m0, s48
	s_nop 0
	global_load_lds_dwordx4 v[224:225], off
	s_waitcnt vmcnt(8)
	s_waitcnt lgkmcnt(0)
	s_setprio 0
	s_barrier
	v_mfma_f32_16x16x32_bf16 v[60:63], v[146:149], v[188:191], v[60:63]
	v_mfma_f32_16x16x32_bf16 v[56:59], v[164:167], v[188:191], v[56:59]
	v_mfma_f32_16x16x32_bf16 v[44:47], v[146:149], v[196:199], v[44:47]
	v_mfma_f32_16x16x32_bf16 v[40:43], v[164:167], v[196:199], v[40:43]
	v_mfma_f32_16x16x32_bf16 v[28:31], v[146:149], v[204:207], v[28:31]
	v_mfma_f32_16x16x32_bf16 v[24:27], v[164:167], v[204:207], v[24:27]
	v_mfma_f32_16x16x32_bf16 v[12:15], v[146:149], v[212:215], v[12:15]
	v_mfma_f32_16x16x32_bf16 v[8:11], v[164:167], v[212:215], v[8:11]
	v_mfma_f32_16x16x32_bf16 v[60:63], v[150:153], v[192:195], v[60:63]
	v_mfma_f32_16x16x32_bf16 v[56:59], v[168:171], v[192:195], v[56:59]
	v_mfma_f32_16x16x32_bf16 v[44:47], v[150:153], v[200:203], v[44:47]
	v_mfma_f32_16x16x32_bf16 v[40:43], v[168:171], v[200:203], v[40:43]
	v_mfma_f32_16x16x32_bf16 v[28:31], v[150:153], v[208:211], v[28:31]
	v_mfma_f32_16x16x32_bf16 v[24:27], v[168:171], v[208:211], v[24:27]
	v_mfma_f32_16x16x32_bf16 v[12:15], v[150:153], v[216:219], v[12:15]
	v_mfma_f32_16x16x32_bf16 v[8:11], v[168:171], v[216:219], v[8:11]
	v_mfma_f32_16x16x32_bf16 v[52:55], v[172:175], v[188:191], v[52:55]
	v_mfma_f32_16x16x32_bf16 v[48:51], v[180:183], v[188:191], v[48:51]
	v_mfma_f32_16x16x32_bf16 v[36:39], v[172:175], v[196:199], v[36:39]
	v_mfma_f32_16x16x32_bf16 v[32:35], v[180:183], v[196:199], v[32:35]
	v_mfma_f32_16x16x32_bf16 v[20:23], v[172:175], v[204:207], v[20:23]
	v_mfma_f32_16x16x32_bf16 v[16:19], v[180:183], v[204:207], v[16:19]
	v_mfma_f32_16x16x32_bf16 v[4:7], v[172:175], v[212:215], v[4:7]
	v_mfma_f32_16x16x32_bf16 v[0:3], v[180:183], v[212:215], v[0:3]
	v_mfma_f32_16x16x32_bf16 v[52:55], v[176:179], v[192:195], v[52:55]
	v_mfma_f32_16x16x32_bf16 v[48:51], v[184:187], v[192:195], v[48:51]
	v_mfma_f32_16x16x32_bf16 v[36:39], v[176:179], v[200:203], v[36:39]
	v_mfma_f32_16x16x32_bf16 v[32:35], v[184:187], v[200:203], v[32:35]
	v_mfma_f32_16x16x32_bf16 v[20:23], v[176:179], v[208:211], v[20:23]
	v_mfma_f32_16x16x32_bf16 v[16:19], v[184:187], v[208:211], v[16:19]
	v_mfma_f32_16x16x32_bf16 v[4:7], v[176:179], v[216:219], v[4:7]
	v_mfma_f32_16x16x32_bf16 v[0:3], v[184:187], v[216:219], v[0:3]
	s_barrier
	s_setprio 1
	s_add_i32 s72, 0, 0x18000
	s_add_i32 s78, 0, 0x1c000
	v_add_u32_e32 v168, s72, v157
	v_add_u32_e32 v184, s78, v157
	ds_read_b128 v[146:149], v168
	ds_read_b128 v[150:153], v168 offset:1024
	ds_read_b128 v[164:167], v168 offset:2048
	ds_read_b128 v[168:171], v168 offset:3072
	ds_read_b128 v[172:175], v184
	ds_read_b128 v[176:179], v184 offset:1024
	ds_read_b128 v[180:183], v184 offset:2048
	ds_read_b128 v[184:187], v184 offset:3072
	s_add_u32 s60, s60, 0x80000
	s_addc_u32 s61, s61, 0
	s_mov_b32 m0, s49
	v_lshl_add_u64 v[226:227], s[60:61], 0, v[128:129]
	ds_read_b128 v[188:191], v161 offset:32768
	ds_read_b128 v[192:195], v161 offset:33792
	ds_read_b128 v[196:199], v161 offset:34816
	ds_read_b128 v[200:203], v161 offset:35840
	ds_read_b128 v[204:207], v161 offset:36864
	ds_read_b128 v[208:211], v161 offset:37888
	ds_read_b128 v[212:215], v161 offset:38912
	ds_read_b128 v[216:219], v161 offset:39936
	global_load_lds_dwordx4 v[226:227], off
	v_lshl_add_u64 v[226:227], s[60:61], 0, v[132:133]
	s_mov_b32 m0, s62
	s_nop 0
	global_load_lds_dwordx4 v[226:227], off
	s_waitcnt vmcnt(8)
	s_waitcnt lgkmcnt(0)
	s_setprio 0
	s_barrier
	v_mfma_f32_16x16x32_bf16 v[124:127], v[146:149], v[188:191], v[124:127]
	v_mfma_f32_16x16x32_bf16 v[120:123], v[164:167], v[188:191], v[120:123]
	v_mfma_f32_16x16x32_bf16 v[108:111], v[146:149], v[196:199], v[108:111]
	v_mfma_f32_16x16x32_bf16 v[104:107], v[164:167], v[196:199], v[104:107]
	v_mfma_f32_16x16x32_bf16 v[92:95], v[146:149], v[204:207], v[92:95]
	v_mfma_f32_16x16x32_bf16 v[88:91], v[164:167], v[204:207], v[88:91]
	v_mfma_f32_16x16x32_bf16 v[76:79], v[146:149], v[212:215], v[76:79]
	v_mfma_f32_16x16x32_bf16 v[72:75], v[164:167], v[212:215], v[72:75]
	v_mfma_f32_16x16x32_bf16 v[124:127], v[150:153], v[192:195], v[124:127]
	v_mfma_f32_16x16x32_bf16 v[120:123], v[168:171], v[192:195], v[120:123]
	v_mfma_f32_16x16x32_bf16 v[108:111], v[150:153], v[200:203], v[108:111]
	v_mfma_f32_16x16x32_bf16 v[104:107], v[168:171], v[200:203], v[104:107]
	v_mfma_f32_16x16x32_bf16 v[92:95], v[150:153], v[208:211], v[92:95]
	v_mfma_f32_16x16x32_bf16 v[88:91], v[168:171], v[208:211], v[88:91]
	v_mfma_f32_16x16x32_bf16 v[76:79], v[150:153], v[216:219], v[76:79]
	v_mfma_f32_16x16x32_bf16 v[72:75], v[168:171], v[216:219], v[72:75]
	v_mfma_f32_16x16x32_bf16 v[116:119], v[172:175], v[188:191], v[116:119]
	v_mfma_f32_16x16x32_bf16 v[112:115], v[180:183], v[188:191], v[112:115]
	v_mfma_f32_16x16x32_bf16 v[100:103], v[172:175], v[196:199], v[100:103]
	v_mfma_f32_16x16x32_bf16 v[96:99], v[180:183], v[196:199], v[96:99]
	v_mfma_f32_16x16x32_bf16 v[84:87], v[172:175], v[204:207], v[84:87]
	v_mfma_f32_16x16x32_bf16 v[80:83], v[180:183], v[204:207], v[80:83]
	v_mfma_f32_16x16x32_bf16 v[68:71], v[172:175], v[212:215], v[68:71]
	v_mfma_f32_16x16x32_bf16 v[64:67], v[180:183], v[212:215], v[64:67]
	v_mfma_f32_16x16x32_bf16 v[116:119], v[176:179], v[192:195], v[116:119]
	v_mfma_f32_16x16x32_bf16 v[112:115], v[184:187], v[192:195], v[112:115]
	v_mfma_f32_16x16x32_bf16 v[100:103], v[176:179], v[200:203], v[100:103]
	v_mfma_f32_16x16x32_bf16 v[96:99], v[184:187], v[200:203], v[96:99]
	v_mfma_f32_16x16x32_bf16 v[84:87], v[176:179], v[208:211], v[84:87]
	v_mfma_f32_16x16x32_bf16 v[80:83], v[184:187], v[208:211], v[80:83]
	v_mfma_f32_16x16x32_bf16 v[68:71], v[176:179], v[216:219], v[68:71]
	v_mfma_f32_16x16x32_bf16 v[64:67], v[184:187], v[216:219], v[64:67]
	s_barrier
	s_setprio 1
	s_add_i32 s60, s72, s44
	v_lshl_add_u64 v[154:155], v[154:155], 0, s[24:25]
	s_mov_b32 m0, s60
	ds_read_b128 v[188:191], v161 offset:49152
	ds_read_b128 v[192:195], v161 offset:50176
	ds_read_b128 v[196:199], v161 offset:51200
	ds_read_b128 v[200:203], v161 offset:52224
	ds_read_b128 v[204:207], v161 offset:53248
	ds_read_b128 v[208:211], v161 offset:54272
	ds_read_b128 v[212:215], v161 offset:55296
	ds_read_b128 v[216:219], v161 offset:56320
	global_load_lds_dwordx4 v[154:155], off
	s_add_i32 m0, s60, 0x2000
	s_add_u32 s58, s58, 0x80080
	v_lshl_add_u64 v[154:155], v[220:221], 0, s[24:25]
	s_addc_u32 s59, s59, 0
	s_add_i32 s60, s78, s44
	global_load_lds_dwordx4 v[154:155], off
	v_lshl_add_u64 v[154:155], s[58:59], 0, v[130:131]
	s_mov_b32 m0, s60
	s_nop 0
	global_load_lds_dwordx4 v[154:155], off
	v_lshl_add_u64 v[154:155], s[58:59], 0, v[134:135]
	s_add_i32 m0, s60, 0x2000
	s_nop 0
	global_load_lds_dwordx4 v[154:155], off
	v_lshl_add_u64 v[154:155], v[222:223], 0, s[24:25]
	s_mov_b32 m0, s64
	s_nop 0
	global_load_lds_dwordx4 v[154:155], off
	v_lshl_add_u64 v[154:155], v[224:225], 0, s[24:25]
	s_mov_b32 m0, s65
	s_nop 0
	global_load_lds_dwordx4 v[154:155], off
	s_waitcnt vmcnt(8)
	s_waitcnt lgkmcnt(0)
	s_setprio 0
	s_barrier
	v_mfma_f32_16x16x32_bf16 v[60:63], v[146:149], v[188:191], v[60:63]
	v_mfma_f32_16x16x32_bf16 v[56:59], v[164:167], v[188:191], v[56:59]
	v_mfma_f32_16x16x32_bf16 v[44:47], v[146:149], v[196:199], v[44:47]
	v_mfma_f32_16x16x32_bf16 v[40:43], v[164:167], v[196:199], v[40:43]
	v_mfma_f32_16x16x32_bf16 v[28:31], v[146:149], v[204:207], v[28:31]
	v_mfma_f32_16x16x32_bf16 v[24:27], v[164:167], v[204:207], v[24:27]
	v_mfma_f32_16x16x32_bf16 v[12:15], v[146:149], v[212:215], v[12:15]
	v_mfma_f32_16x16x32_bf16 v[8:11], v[164:167], v[212:215], v[8:11]
	v_mfma_f32_16x16x32_bf16 v[60:63], v[150:153], v[192:195], v[60:63]
	v_mfma_f32_16x16x32_bf16 v[56:59], v[168:171], v[192:195], v[56:59]
	v_mfma_f32_16x16x32_bf16 v[44:47], v[150:153], v[200:203], v[44:47]
	v_mfma_f32_16x16x32_bf16 v[40:43], v[168:171], v[200:203], v[40:43]
	v_mfma_f32_16x16x32_bf16 v[28:31], v[150:153], v[208:211], v[28:31]
	v_mfma_f32_16x16x32_bf16 v[24:27], v[168:171], v[208:211], v[24:27]
	v_mfma_f32_16x16x32_bf16 v[12:15], v[150:153], v[216:219], v[12:15]
	v_mfma_f32_16x16x32_bf16 v[8:11], v[168:171], v[216:219], v[8:11]
	v_mfma_f32_16x16x32_bf16 v[52:55], v[172:175], v[188:191], v[52:55]
	v_mfma_f32_16x16x32_bf16 v[48:51], v[180:183], v[188:191], v[48:51]
	v_mfma_f32_16x16x32_bf16 v[36:39], v[172:175], v[196:199], v[36:39]
	v_mfma_f32_16x16x32_bf16 v[32:35], v[180:183], v[196:199], v[32:35]
	v_mfma_f32_16x16x32_bf16 v[20:23], v[172:175], v[204:207], v[20:23]
	v_mfma_f32_16x16x32_bf16 v[16:19], v[180:183], v[204:207], v[16:19]
	v_mfma_f32_16x16x32_bf16 v[4:7], v[172:175], v[212:215], v[4:7]
	v_mfma_f32_16x16x32_bf16 v[0:3], v[180:183], v[212:215], v[0:3]
	v_mfma_f32_16x16x32_bf16 v[52:55], v[176:179], v[192:195], v[52:55]
	v_mfma_f32_16x16x32_bf16 v[48:51], v[184:187], v[192:195], v[48:51]
	v_mfma_f32_16x16x32_bf16 v[36:39], v[176:179], v[200:203], v[36:39]
	v_mfma_f32_16x16x32_bf16 v[32:35], v[184:187], v[200:203], v[32:35]
	v_mfma_f32_16x16x32_bf16 v[20:23], v[176:179], v[208:211], v[20:23]
	v_mfma_f32_16x16x32_bf16 v[16:19], v[184:187], v[208:211], v[16:19]
	v_mfma_f32_16x16x32_bf16 v[4:7], v[176:179], v[216:219], v[4:7]
	v_mfma_f32_16x16x32_bf16 v[0:3], v[184:187], v[216:219], v[0:3]
	s_barrier
	s_setprio 1
	s_add_i32 s55, s55, 2
	s_add_u32 s50, s50, 0x100
	s_addc_u32 s51, s51, 0
	s_add_u32 s56, s56, 0x100
	s_addc_u32 s57, s57, 0
	s_cmp_gt_u32 s55, 29
	s_cbranch_scc0 .LBB0_617
	s_and_b64 vcc, exec, s[26:27]
	s_cbranch_vccz .LBB0_620
	s_barrier
	s_setprio 3

.LBB0_708:
	ds_read_b128 v[0:3], v145
	ds_read_b128 v[4:7], v145 offset:1024
	ds_read_b128 v[8:11], v145 offset:2048
	ds_read_b128 v[12:15], v145 offset:3072
	ds_read_b128 v[16:19], v146
	ds_read_b128 v[20:23], v146 offset:1024
	ds_read_b128 v[24:27], v146 offset:2048
	ds_read_b128 v[28:31], v146 offset:3072
	s_ashr_i32 s37, s36, 31
	s_lshl_b64 s[52:53], s[36:37], 17
	s_add_u32 s52, s6, s52
	s_addc_u32 s53, s7, s53
	s_and_b64 s[54:55], s[8:9], exec
	s_cselect_b32 s65, s53, s59
	s_cselect_b32 s64, s52, s58
	s_ashr_i32 s35, s34, 31
	s_lshl_b64 s[54:55], s[34:35], 17
	s_add_u32 s54, s44, s54
	s_addc_u32 s55, s45, s55
	s_and_b64 s[62:63], s[8:9], exec
	s_cselect_b32 s63, s55, s61
	s_cselect_b32 s62, s54, s60
	s_add_u32 s86, s58, 0x10080
	s_addc_u32 s87, s59, 0
	s_mov_b32 m0, s72
	v_lshl_add_u64 v[64:65], s[86:87], 0, v[128:129]
	ds_read_b128 v[32:35], v147
	ds_read_b128 v[36:39], v147 offset:1024
	ds_read_b128 v[40:43], v147 offset:2048
	ds_read_b128 v[44:47], v147 offset:3072
	ds_read_b128 v[48:51], v147 offset:4096
	ds_read_b128 v[52:55], v147 offset:5120
	ds_read_b128 v[56:59], v147 offset:6144
	ds_read_b128 v[60:63], v147 offset:7168
	global_load_lds_dwordx4 v[64:65], off
	v_lshl_add_u64 v[64:65], s[86:87], 0, v[132:133]
	s_mov_b32 m0, s80
	s_nop 0
	global_load_lds_dwordx4 v[64:65], off
	s_waitcnt vmcnt(8)
	s_waitcnt lgkmcnt(0)
	s_setprio 0
	s_barrier
	v_mfma_f32_16x16x32_bf16 v[64:67], v[0:3], v[32:35], 0
	v_mfma_f32_16x16x32_bf16 v[68:71], v[8:11], v[32:35], 0
	v_mfma_f32_16x16x32_bf16 v[72:75], v[0:3], v[40:43], 0
	v_mfma_f32_16x16x32_bf16 v[76:79], v[8:11], v[40:43], 0
	v_mfma_f32_16x16x32_bf16 v[80:83], v[0:3], v[48:51], 0
	v_mfma_f32_16x16x32_bf16 v[84:87], v[8:11], v[48:51], 0
	v_mfma_f32_16x16x32_bf16 v[88:91], v[0:3], v[56:59], 0
	v_mfma_f32_16x16x32_bf16 v[92:95], v[8:11], v[56:59], 0
	v_mfma_f32_16x16x32_bf16 v[64:67], v[4:7], v[36:39], v[64:67]
	v_mfma_f32_16x16x32_bf16 v[68:71], v[12:15], v[36:39], v[68:71]
	v_mfma_f32_16x16x32_bf16 v[72:75], v[4:7], v[44:47], v[72:75]
	v_mfma_f32_16x16x32_bf16 v[76:79], v[12:15], v[44:47], v[76:79]
	v_mfma_f32_16x16x32_bf16 v[80:83], v[4:7], v[52:55], v[80:83]
	v_mfma_f32_16x16x32_bf16 v[84:87], v[12:15], v[52:55], v[84:87]
	v_mfma_f32_16x16x32_bf16 v[88:91], v[4:7], v[60:63], v[88:91]
	v_mfma_f32_16x16x32_bf16 v[92:95], v[12:15], v[60:63], v[92:95]
	v_mfma_f32_16x16x32_bf16 v[96:99], v[16:19], v[32:35], 0
	v_mfma_f32_16x16x32_bf16 v[32:35], v[24:27], v[32:35], 0
	v_mfma_f32_16x16x32_bf16 v[96:99], v[20:23], v[36:39], v[96:99]
	v_mfma_f32_16x16x32_bf16 v[32:35], v[28:31], v[36:39], v[32:35]
	v_mfma_f32_16x16x32_bf16 v[36:39], v[16:19], v[40:43], 0
	v_mfma_f32_16x16x32_bf16 v[40:43], v[24:27], v[40:43], 0
	v_mfma_f32_16x16x32_bf16 v[36:39], v[20:23], v[44:47], v[36:39]
	v_mfma_f32_16x16x32_bf16 v[40:43], v[28:31], v[44:47], v[40:43]
	v_mfma_f32_16x16x32_bf16 v[44:47], v[16:19], v[48:51], 0
	v_mfma_f32_16x16x32_bf16 v[48:51], v[24:27], v[48:51], 0
	v_mfma_f32_16x16x32_bf16 v[44:47], v[20:23], v[52:55], v[44:47]
	v_mfma_f32_16x16x32_bf16 v[48:51], v[28:31], v[52:55], v[48:51]
	v_mfma_f32_16x16x32_bf16 v[52:55], v[16:19], v[56:59], 0
	v_mfma_f32_16x16x32_bf16 v[56:59], v[24:27], v[56:59], 0
	v_mfma_f32_16x16x32_bf16 v[52:55], v[20:23], v[60:63], v[52:55]
	v_mfma_f32_16x16x32_bf16 v[56:59], v[28:31], v[60:63], v[56:59]
	s_barrier
	s_setprio 1
	s_add_i32 s85, s70, s48
	v_lshl_add_u64 v[140:141], s[60:61], 0, v[130:131]
	s_add_i32 s35, s85, 0x2000
	v_lshl_add_u64 v[148:149], v[140:141], 0, s[20:21]
	s_mov_b32 m0, s85
	v_lshl_add_u64 v[212:213], s[60:61], 0, v[134:135]
	s_add_u32 s86, s60, 0x10100
	ds_read_b128 v[60:63], v147 offset:16384
	ds_read_b128 v[100:103], v147 offset:17408
	ds_read_b128 v[104:107], v147 offset:18432
	ds_read_b128 v[108:111], v147 offset:19456
	ds_read_b128 v[112:115], v147 offset:20480
	ds_read_b128 v[116:119], v147 offset:21504
	ds_read_b128 v[120:123], v147 offset:22528
	ds_read_b128 v[124:127], v147 offset:23552
	global_load_lds_dwordx4 v[148:149], off
	v_lshl_add_u64 v[148:149], v[212:213], 0, s[20:21]
	s_mov_b32 m0, s35
	s_addc_u32 s87, s61, 0
	s_add_i32 s37, s71, s48
	global_load_lds_dwordx4 v[148:149], off
	v_lshl_add_u64 v[148:149], s[86:87], 0, v[130:131]
	s_mov_b32 m0, s37
	s_add_i32 s47, s37, 0x2000
	global_load_lds_dwordx4 v[148:149], off
	v_lshl_add_u64 v[148:149], s[86:87], 0, v[134:135]
	s_mov_b32 m0, s47
	v_lshl_add_u64 v[214:215], s[58:59], 0, v[128:129]
	global_load_lds_dwordx4 v[148:149], off
	v_lshl_add_u64 v[148:149], v[214:215], 0, s[20:21]
	s_mov_b32 m0, s49
	v_lshl_add_u64 v[216:217], s[58:59], 0, v[132:133]
	global_load_lds_dwordx4 v[148:149], off
	v_lshl_add_u64 v[148:149], v[216:217], 0, s[20:21]
	s_mov_b32 m0, s50
	s_nop 0
	global_load_lds_dwordx4 v[148:149], off
	s_waitcnt vmcnt(8)
	s_waitcnt lgkmcnt(0)
	s_setprio 0
	s_barrier
	v_mfma_f32_16x16x32_bf16 v[148:151], v[0:3], v[60:63], 0
	v_mfma_f32_16x16x32_bf16 v[156:159], v[0:3], v[104:107], 0
	v_mfma_f32_16x16x32_bf16 v[164:167], v[0:3], v[112:115], 0
	v_mfma_f32_16x16x32_bf16 v[0:3], v[0:3], v[120:123], 0
	v_mfma_f32_16x16x32_bf16 v[148:151], v[4:7], v[100:103], v[148:151]
	v_mfma_f32_16x16x32_bf16 v[156:159], v[4:7], v[108:111], v[156:159]
	v_mfma_f32_16x16x32_bf16 v[164:167], v[4:7], v[116:119], v[164:167]
	v_mfma_f32_16x16x32_bf16 v[0:3], v[4:7], v[124:127], v[0:3]
	v_mfma_f32_16x16x32_bf16 v[4:7], v[8:11], v[120:123], 0
	v_mfma_f32_16x16x32_bf16 v[152:155], v[8:11], v[60:63], 0
	v_mfma_f32_16x16x32_bf16 v[160:163], v[8:11], v[104:107], 0
	v_mfma_f32_16x16x32_bf16 v[168:171], v[8:11], v[112:115], 0
	v_mfma_f32_16x16x32_bf16 v[4:7], v[12:15], v[124:127], v[4:7]
	v_mfma_f32_16x16x32_bf16 v[152:155], v[12:15], v[100:103], v[152:155]
	v_mfma_f32_16x16x32_bf16 v[160:163], v[12:15], v[108:111], v[160:163]
	v_mfma_f32_16x16x32_bf16 v[168:171], v[12:15], v[116:119], v[168:171]
	v_mfma_f32_16x16x32_bf16 v[8:11], v[16:19], v[60:63], 0
	v_mfma_f32_16x16x32_bf16 v[12:15], v[24:27], v[60:63], 0
	v_mfma_f32_16x16x32_bf16 v[8:11], v[20:23], v[100:103], v[8:11]
	v_mfma_f32_16x16x32_bf16 v[12:15], v[28:31], v[100:103], v[12:15]
	v_mfma_f32_16x16x32_bf16 v[60:63], v[16:19], v[104:107], 0
	v_mfma_f32_16x16x32_bf16 v[100:103], v[24:27], v[104:107], 0
	v_mfma_f32_16x16x32_bf16 v[104:107], v[16:19], v[112:115], 0
	v_mfma_f32_16x16x32_bf16 v[16:19], v[16:19], v[120:123], 0
	v_mfma_f32_16x16x32_bf16 v[60:63], v[20:23], v[108:111], v[60:63]
	v_mfma_f32_16x16x32_bf16 v[100:103], v[28:31], v[108:111], v[100:103]
	v_mfma_f32_16x16x32_bf16 v[104:107], v[20:23], v[116:119], v[104:107]
	v_mfma_f32_16x16x32_bf16 v[108:111], v[24:27], v[112:115], 0
	v_mfma_f32_16x16x32_bf16 v[16:19], v[20:23], v[124:127], v[16:19]
	v_mfma_f32_16x16x32_bf16 v[20:23], v[24:27], v[120:123], 0
	v_mfma_f32_16x16x32_bf16 v[108:111], v[28:31], v[116:119], v[108:111]
	v_mfma_f32_16x16x32_bf16 v[20:23], v[28:31], v[124:127], v[20:23]
	s_barrier
	s_setprio 1
	s_add_i32 s78, 0, 0x18000
	s_add_i32 s79, 0, 0x1c000
	v_add_u32_e32 v224, s78, v143
	v_add_u32_e32 v232, s79, v143
	ds_read_b128 v[24:27], v224
	ds_read_b128 v[28:31], v224 offset:1024
	ds_read_b128 v[112:115], v224 offset:2048
	ds_read_b128 v[116:119], v224 offset:3072
	ds_read_b128 v[120:123], v232
	ds_read_b128 v[124:127], v232 offset:1024
	ds_read_b128 v[172:175], v232 offset:2048
	ds_read_b128 v[176:179], v232 offset:3072
	s_add_u32 s86, s58, 0x10100
	s_addc_u32 s87, s59, 0
	s_mov_b32 m0, s51
	v_lshl_add_u64 v[218:219], s[86:87], 0, v[128:129]
	ds_read_b128 v[180:183], v147 offset:32768
	ds_read_b128 v[184:187], v147 offset:33792
	ds_read_b128 v[188:191], v147 offset:34816
	ds_read_b128 v[192:195], v147 offset:35840
	ds_read_b128 v[196:199], v147 offset:36864
	ds_read_b128 v[200:203], v147 offset:37888
	ds_read_b128 v[204:207], v147 offset:38912
	ds_read_b128 v[208:211], v147 offset:39936
	global_load_lds_dwordx4 v[218:219], off
	v_lshl_add_u64 v[218:219], s[86:87], 0, v[132:133]
	s_mov_b32 m0, s57
	s_nop 0
	global_load_lds_dwordx4 v[218:219], off
	s_waitcnt vmcnt(8)
	s_waitcnt lgkmcnt(0)
	s_setprio 0
	s_barrier
	v_mfma_f32_16x16x32_bf16 v[64:67], v[24:27], v[180:183], v[64:67]
	v_mfma_f32_16x16x32_bf16 v[68:71], v[112:115], v[180:183], v[68:71]
	v_mfma_f32_16x16x32_bf16 v[72:75], v[24:27], v[188:191], v[72:75]
	v_mfma_f32_16x16x32_bf16 v[76:79], v[112:115], v[188:191], v[76:79]
	v_mfma_f32_16x16x32_bf16 v[80:83], v[24:27], v[196:199], v[80:83]
	v_mfma_f32_16x16x32_bf16 v[84:87], v[112:115], v[196:199], v[84:87]
	v_mfma_f32_16x16x32_bf16 v[88:91], v[24:27], v[204:207], v[88:91]
	v_mfma_f32_16x16x32_bf16 v[92:95], v[112:115], v[204:207], v[92:95]
	v_mfma_f32_16x16x32_bf16 v[64:67], v[28:31], v[184:187], v[64:67]
	v_mfma_f32_16x16x32_bf16 v[68:71], v[116:119], v[184:187], v[68:71]
	v_mfma_f32_16x16x32_bf16 v[72:75], v[28:31], v[192:195], v[72:75]
	v_mfma_f32_16x16x32_bf16 v[76:79], v[116:119], v[192:195], v[76:79]
	v_mfma_f32_16x16x32_bf16 v[80:83], v[28:31], v[200:203], v[80:83]
	v_mfma_f32_16x16x32_bf16 v[84:87], v[116:119], v[200:203], v[84:87]
	v_mfma_f32_16x16x32_bf16 v[88:91], v[28:31], v[208:211], v[88:91]
	v_mfma_f32_16x16x32_bf16 v[92:95], v[116:119], v[208:211], v[92:95]
	v_mfma_f32_16x16x32_bf16 v[96:99], v[120:123], v[180:183], v[96:99]
	v_mfma_f32_16x16x32_bf16 v[32:35], v[172:175], v[180:183], v[32:35]
	v_mfma_f32_16x16x32_bf16 v[36:39], v[120:123], v[188:191], v[36:39]
	v_mfma_f32_16x16x32_bf16 v[40:43], v[172:175], v[188:191], v[40:43]
	v_mfma_f32_16x16x32_bf16 v[44:47], v[120:123], v[196:199], v[44:47]
	v_mfma_f32_16x16x32_bf16 v[48:51], v[172:175], v[196:199], v[48:51]
	v_mfma_f32_16x16x32_bf16 v[52:55], v[120:123], v[204:207], v[52:55]
	v_mfma_f32_16x16x32_bf16 v[56:59], v[172:175], v[204:207], v[56:59]
	v_mfma_f32_16x16x32_bf16 v[96:99], v[124:127], v[184:187], v[96:99]
	v_mfma_f32_16x16x32_bf16 v[32:35], v[176:179], v[184:187], v[32:35]
	v_mfma_f32_16x16x32_bf16 v[36:39], v[124:127], v[192:195], v[36:39]
	v_mfma_f32_16x16x32_bf16 v[40:43], v[176:179], v[192:195], v[40:43]
	v_mfma_f32_16x16x32_bf16 v[44:47], v[124:127], v[200:203], v[44:47]
	v_mfma_f32_16x16x32_bf16 v[48:51], v[176:179], v[200:203], v[48:51]
	v_mfma_f32_16x16x32_bf16 v[52:55], v[124:127], v[208:211], v[52:55]
	v_mfma_f32_16x16x32_bf16 v[56:59], v[176:179], v[208:211], v[56:59]
	s_barrier
	s_setprio 1
	s_add_i32 s87, s78, s48
	s_add_i32 s86, s87, 0x2000
	v_lshl_add_u64 v[140:141], v[140:141], 0, s[22:23]
	s_mov_b32 m0, s87
	s_add_u32 s88, s60, 0x10180
	ds_read_b128 v[180:183], v147 offset:49152
	ds_read_b128 v[184:187], v147 offset:50176
	ds_read_b128 v[188:191], v147 offset:51200
	ds_read_b128 v[192:195], v147 offset:52224
	ds_read_b128 v[196:199], v147 offset:53248
	ds_read_b128 v[200:203], v147 offset:54272
	ds_read_b128 v[204:207], v147 offset:55296
	ds_read_b128 v[208:211], v147 offset:56320
	global_load_lds_dwordx4 v[140:141], off
	v_lshl_add_u64 v[140:141], v[212:213], 0, s[22:23]
	s_mov_b32 m0, s86
	s_addc_u32 s89, s61, 0
	s_add_i32 s60, s79, s48
	global_load_lds_dwordx4 v[140:141], off
	v_lshl_add_u64 v[140:141], s[88:89], 0, v[130:131]
	s_mov_b32 m0, s60
	s_add_i32 s61, s60, 0x2000
	global_load_lds_dwordx4 v[140:141], off
	v_lshl_add_u64 v[140:141], s[88:89], 0, v[134:135]
	s_mov_b32 m0, s61
	s_nop 0
	global_load_lds_dwordx4 v[140:141], off
	v_lshl_add_u64 v[140:141], v[214:215], 0, s[22:23]
	s_mov_b32 m0, s66
	s_nop 0
	global_load_lds_dwordx4 v[140:141], off
	v_lshl_add_u64 v[140:141], v[216:217], 0, s[22:23]
	s_mov_b32 m0, s67
	s_nop 0
	global_load_lds_dwordx4 v[140:141], off
	s_waitcnt vmcnt(8)
	s_waitcnt lgkmcnt(0)
	s_setprio 0
	s_barrier
	v_mfma_f32_16x16x32_bf16 v[0:3], v[24:27], v[204:207], v[0:3]
	v_mfma_f32_16x16x32_bf16 v[4:7], v[112:115], v[204:207], v[4:7]
	v_mfma_f32_16x16x32_bf16 v[148:151], v[24:27], v[180:183], v[148:151]
	v_mfma_f32_16x16x32_bf16 v[152:155], v[112:115], v[180:183], v[152:155]
	v_mfma_f32_16x16x32_bf16 v[156:159], v[24:27], v[188:191], v[156:159]
	v_mfma_f32_16x16x32_bf16 v[160:163], v[112:115], v[188:191], v[160:163]
	v_mfma_f32_16x16x32_bf16 v[164:167], v[24:27], v[196:199], v[164:167]
	v_mfma_f32_16x16x32_bf16 v[168:171], v[112:115], v[196:199], v[168:171]
	v_mfma_f32_16x16x32_bf16 v[0:3], v[28:31], v[208:211], v[0:3]
	v_mfma_f32_16x16x32_bf16 v[4:7], v[116:119], v[208:211], v[4:7]
	v_mfma_f32_16x16x32_bf16 v[148:151], v[28:31], v[184:187], v[148:151]
	v_mfma_f32_16x16x32_bf16 v[152:155], v[116:119], v[184:187], v[152:155]
	v_mfma_f32_16x16x32_bf16 v[156:159], v[28:31], v[192:195], v[156:159]
	v_mfma_f32_16x16x32_bf16 v[160:163], v[116:119], v[192:195], v[160:163]
	v_mfma_f32_16x16x32_bf16 v[164:167], v[28:31], v[200:203], v[164:167]
	v_mfma_f32_16x16x32_bf16 v[168:171], v[116:119], v[200:203], v[168:171]
	v_mfma_f32_16x16x32_bf16 v[8:11], v[120:123], v[180:183], v[8:11]
	v_mfma_f32_16x16x32_bf16 v[12:15], v[172:175], v[180:183], v[12:15]
	v_mfma_f32_16x16x32_bf16 v[24:27], v[120:123], v[188:191], v[60:63]
	v_mfma_f32_16x16x32_bf16 v[28:31], v[172:175], v[188:191], v[100:103]
	v_mfma_f32_16x16x32_bf16 v[60:63], v[120:123], v[196:199], v[104:107]
	v_mfma_f32_16x16x32_bf16 v[100:103], v[172:175], v[196:199], v[108:111]
	v_mfma_f32_16x16x32_bf16 v[16:19], v[120:123], v[204:207], v[16:19]
	v_mfma_f32_16x16x32_bf16 v[20:23], v[172:175], v[204:207], v[20:23]
	v_mfma_f32_16x16x32_bf16 v[8:11], v[124:127], v[184:187], v[8:11]
	v_mfma_f32_16x16x32_bf16 v[12:15], v[176:179], v[184:187], v[12:15]
	v_mfma_f32_16x16x32_bf16 v[24:27], v[124:127], v[192:195], v[24:27]
	v_mfma_f32_16x16x32_bf16 v[28:31], v[176:179], v[192:195], v[28:31]
	v_mfma_f32_16x16x32_bf16 v[60:63], v[124:127], v[200:203], v[60:63]
	v_mfma_f32_16x16x32_bf16 v[100:103], v[176:179], v[200:203], v[100:103]
	v_mfma_f32_16x16x32_bf16 v[16:19], v[124:127], v[208:211], v[16:19]
	v_mfma_f32_16x16x32_bf16 v[20:23], v[176:179], v[208:211], v[20:23]
	s_barrier
	s_setprio 1
	ds_read_b128 v[104:107], v145
	ds_read_b128 v[108:111], v145 offset:1024
	ds_read_b128 v[112:115], v145 offset:2048
	ds_read_b128 v[116:119], v145 offset:3072
	ds_read_b128 v[120:123], v146
	ds_read_b128 v[124:127], v146 offset:1024
	ds_read_b128 v[172:175], v146 offset:2048
	ds_read_b128 v[176:179], v146 offset:3072
	s_add_u32 s58, s58, 0x10180
	s_addc_u32 s59, s59, 0
	s_mov_b32 m0, s72
	v_lshl_add_u64 v[140:141], s[58:59], 0, v[128:129]
	ds_read_b128 v[180:183], v147
	ds_read_b128 v[184:187], v147 offset:1024
	ds_read_b128 v[188:191], v147 offset:2048
	ds_read_b128 v[192:195], v147 offset:3072
	ds_read_b128 v[196:199], v147 offset:4096
	ds_read_b128 v[200:203], v147 offset:5120
	ds_read_b128 v[204:207], v147 offset:6144
	ds_read_b128 v[208:211], v147 offset:7168
	global_load_lds_dwordx4 v[140:141], off
	v_lshl_add_u64 v[140:141], s[58:59], 0, v[132:133]
	s_mov_b32 m0, s80
	s_nop 0
	global_load_lds_dwordx4 v[140:141], off
	s_waitcnt vmcnt(8)
	s_waitcnt lgkmcnt(0)
	s_setprio 0
	s_barrier
	v_mfma_f32_16x16x32_bf16 v[88:91], v[104:107], v[204:207], v[88:91]
	v_mfma_f32_16x16x32_bf16 v[64:67], v[104:107], v[180:183], v[64:67]
	v_mfma_f32_16x16x32_bf16 v[68:71], v[112:115], v[180:183], v[68:71]
	v_mfma_f32_16x16x32_bf16 v[72:75], v[104:107], v[188:191], v[72:75]
	v_mfma_f32_16x16x32_bf16 v[76:79], v[112:115], v[188:191], v[76:79]
	v_mfma_f32_16x16x32_bf16 v[80:83], v[104:107], v[196:199], v[80:83]
	v_mfma_f32_16x16x32_bf16 v[84:87], v[112:115], v[196:199], v[84:87]
	v_mfma_f32_16x16x32_bf16 v[212:215], v[108:111], v[208:211], v[88:91]
	v_mfma_f32_16x16x32_bf16 v[88:91], v[112:115], v[204:207], v[92:95]
	v_mfma_f32_16x16x32_bf16 v[64:67], v[108:111], v[184:187], v[64:67]
	v_mfma_f32_16x16x32_bf16 v[68:71], v[116:119], v[184:187], v[68:71]
	v_mfma_f32_16x16x32_bf16 v[72:75], v[108:111], v[192:195], v[72:75]
	v_mfma_f32_16x16x32_bf16 v[76:79], v[116:119], v[192:195], v[76:79]
	v_mfma_f32_16x16x32_bf16 v[80:83], v[108:111], v[200:203], v[80:83]
	v_mfma_f32_16x16x32_bf16 v[84:87], v[116:119], v[200:203], v[84:87]
	v_mfma_f32_16x16x32_bf16 v[92:95], v[116:119], v[208:211], v[88:91]
	v_mfma_f32_16x16x32_bf16 v[48:51], v[172:175], v[196:199], v[48:51]
	v_mfma_f32_16x16x32_bf16 v[88:91], v[120:123], v[180:183], v[96:99]
	v_mfma_f32_16x16x32_bf16 v[32:35], v[172:175], v[180:183], v[32:35]
	v_mfma_f32_16x16x32_bf16 v[36:39], v[120:123], v[188:191], v[36:39]
	v_mfma_f32_16x16x32_bf16 v[40:43], v[172:175], v[188:191], v[40:43]
	v_mfma_f32_16x16x32_bf16 v[44:47], v[120:123], v[196:199], v[44:47]
	v_mfma_f32_16x16x32_bf16 v[180:183], v[176:179], v[200:203], v[48:51]
	v_mfma_f32_16x16x32_bf16 v[48:51], v[120:123], v[204:207], v[52:55]
	v_mfma_f32_16x16x32_bf16 v[32:35], v[176:179], v[184:187], v[32:35]
	v_mfma_f32_16x16x32_bf16 v[36:39], v[124:127], v[192:195], v[36:39]
	v_mfma_f32_16x16x32_bf16 v[40:43], v[176:179], v[192:195], v[40:43]
	v_mfma_f32_16x16x32_bf16 v[44:47], v[124:127], v[200:203], v[44:47]
	v_mfma_f32_16x16x32_bf16 v[52:55], v[124:127], v[208:211], v[48:51]
	v_mfma_f32_16x16x32_bf16 v[48:51], v[172:175], v[204:207], v[56:59]
	v_mfma_f32_16x16x32_bf16 v[216:219], v[124:127], v[184:187], v[88:91]
	v_mfma_f32_16x16x32_bf16 v[184:187], v[176:179], v[208:211], v[48:51]
	s_barrier
	s_setprio 1
	s_mov_b32 m0, s85
	v_lshl_add_u64 v[140:141], s[62:63], 0, v[130:131]
	s_add_u32 s58, s62, 0x10000
	s_nop 0
	ds_read_b128 v[48:51], v147 offset:16384
	ds_read_b128 v[56:59], v147 offset:17408
	ds_read_b128 v[88:91], v147 offset:18432
	ds_read_b128 v[96:99], v147 offset:19456
	ds_read_b128 v[188:191], v147 offset:20480
	ds_read_b128 v[192:195], v147 offset:21504
	ds_read_b128 v[196:199], v147 offset:22528
	ds_read_b128 v[200:203], v147 offset:23552
	global_load_lds_dwordx4 v[140:141], off
	v_lshl_add_u64 v[252:253], s[62:63], 0, v[134:135]
	s_mov_b32 m0, s35
	s_addc_u32 s59, s63, 0
	global_load_lds_dwordx4 v[252:253], off
	v_lshl_add_u64 v[204:205], s[58:59], 0, v[130:131]
	s_mov_b32 m0, s37
	v_lshl_add_u64 v[136:137], s[64:65], 0, v[128:129]
	global_load_lds_dwordx4 v[204:205], off
	v_lshl_add_u64 v[204:205], s[58:59], 0, v[134:135]
	s_mov_b32 m0, s47
	v_lshl_add_u64 v[138:139], s[64:65], 0, v[132:133]
	global_load_lds_dwordx4 v[204:205], off
	s_mov_b32 m0, s49
	s_nop 0
	global_load_lds_dwordx4 v[136:137], off
	s_mov_b32 m0, s50
	s_nop 0
	global_load_lds_dwordx4 v[138:139], off
	s_waitcnt vmcnt(8)
	s_waitcnt lgkmcnt(0)
	s_setprio 0
	s_barrier
	v_mfma_f32_16x16x32_bf16 v[0:3], v[104:107], v[196:199], v[0:3]
	v_mfma_f32_16x16x32_bf16 v[4:7], v[112:115], v[196:199], v[4:7]
	v_mfma_f32_16x16x32_bf16 v[148:151], v[104:107], v[48:51], v[148:151]
	v_mfma_f32_16x16x32_bf16 v[152:155], v[112:115], v[48:51], v[152:155]
	v_mfma_f32_16x16x32_bf16 v[156:159], v[104:107], v[88:91], v[156:159]
	v_mfma_f32_16x16x32_bf16 v[160:163], v[112:115], v[88:91], v[160:163]
	v_mfma_f32_16x16x32_bf16 v[164:167], v[104:107], v[188:191], v[164:167]
	v_mfma_f32_16x16x32_bf16 v[168:171], v[112:115], v[188:191], v[168:171]
	v_mfma_f32_16x16x32_bf16 v[0:3], v[108:111], v[200:203], v[0:3]
	v_mfma_f32_16x16x32_bf16 v[4:7], v[116:119], v[200:203], v[4:7]
	v_mfma_f32_16x16x32_bf16 v[148:151], v[108:111], v[56:59], v[148:151]
	v_mfma_f32_16x16x32_bf16 v[152:155], v[116:119], v[56:59], v[152:155]
	v_mfma_f32_16x16x32_bf16 v[156:159], v[108:111], v[96:99], v[156:159]
	v_mfma_f32_16x16x32_bf16 v[160:163], v[116:119], v[96:99], v[160:163]
	v_mfma_f32_16x16x32_bf16 v[164:167], v[108:111], v[192:195], v[164:167]
	v_mfma_f32_16x16x32_bf16 v[168:171], v[116:119], v[192:195], v[168:171]
	v_mfma_f32_16x16x32_bf16 v[12:15], v[172:175], v[48:51], v[12:15]
	v_mfma_f32_16x16x32_bf16 v[204:207], v[176:179], v[56:59], v[12:15]
	v_mfma_f32_16x16x32_bf16 v[12:15], v[120:123], v[88:91], v[24:27]
	v_mfma_f32_16x16x32_bf16 v[24:27], v[124:127], v[96:99], v[12:15]
	v_mfma_f32_16x16x32_bf16 v[12:15], v[172:175], v[88:91], v[28:31]
	v_mfma_f32_16x16x32_bf16 v[208:211], v[176:179], v[96:99], v[12:15]
	v_mfma_f32_16x16x32_bf16 v[12:15], v[120:123], v[188:191], v[60:63]
	v_mfma_f32_16x16x32_bf16 v[220:223], v[124:127], v[192:195], v[12:15]
	v_mfma_f32_16x16x32_bf16 v[12:15], v[172:175], v[188:191], v[100:103]
	v_mfma_f32_16x16x32_bf16 v[8:11], v[120:123], v[48:51], v[8:11]
	v_mfma_f32_16x16x32_bf16 v[188:191], v[176:179], v[192:195], v[12:15]
	v_mfma_f32_16x16x32_bf16 v[12:15], v[120:123], v[196:199], v[16:19]
	v_mfma_f32_16x16x32_bf16 v[8:11], v[124:127], v[56:59], v[8:11]
	v_mfma_f32_16x16x32_bf16 v[192:195], v[124:127], v[200:203], v[12:15]
	v_mfma_f32_16x16x32_bf16 v[12:15], v[172:175], v[196:199], v[20:23]
	v_mfma_f32_16x16x32_bf16 v[172:175], v[176:179], v[200:203], v[12:15]
	s_barrier
	s_setprio 1
	s_nop 4
	ds_read_b128 v[12:15], v224
	ds_read_b128 v[16:19], v224 offset:1024
	ds_read_b128 v[176:179], v224 offset:2048
	ds_read_b128 v[196:199], v224 offset:3072
	ds_read_b128 v[200:203], v232
	ds_read_b128 v[224:227], v232 offset:1024
	ds_read_b128 v[228:231], v232 offset:2048
	ds_read_b128 v[232:235], v232 offset:3072
	s_add_u32 s58, s64, 0x10000
	s_addc_u32 s59, s65, 0
	s_mov_b32 m0, s51
	v_lshl_add_u64 v[48:49], s[58:59], 0, v[128:129]
	ds_read_b128 v[20:23], v147 offset:32768
	ds_read_b128 v[28:31], v147 offset:33792
	ds_read_b128 v[60:63], v147 offset:34816
	ds_read_b128 v[100:103], v147 offset:35840
	ds_read_b128 v[236:239], v147 offset:36864
	ds_read_b128 v[240:243], v147 offset:37888
	ds_read_b128 v[244:247], v147 offset:38912
	ds_read_b128 v[248:251], v147 offset:39936
	global_load_lds_dwordx4 v[48:49], off
	v_lshl_add_u64 v[48:49], s[58:59], 0, v[132:133]
	s_mov_b32 m0, s57
	s_nop 0
	global_load_lds_dwordx4 v[48:49], off
	s_waitcnt vmcnt(8)
	s_waitcnt lgkmcnt(0)
	s_setprio 0
	s_barrier
	v_mfma_f32_16x16x32_bf16 v[48:51], v[12:15], v[20:23], v[64:67]
	v_mfma_f32_16x16x32_bf16 v[120:123], v[16:19], v[28:31], v[48:51]
	v_mfma_f32_16x16x32_bf16 v[48:51], v[176:179], v[20:23], v[68:71]
	v_mfma_f32_16x16x32_bf16 v[112:115], v[196:199], v[28:31], v[48:51]
	v_mfma_f32_16x16x32_bf16 v[48:51], v[12:15], v[60:63], v[72:75]
	v_mfma_f32_16x16x32_bf16 v[104:107], v[16:19], v[100:103], v[48:51]
	v_mfma_f32_16x16x32_bf16 v[48:51], v[176:179], v[60:63], v[76:79]
	v_mfma_f32_16x16x32_bf16 v[96:99], v[196:199], v[100:103], v[48:51]
	v_mfma_f32_16x16x32_bf16 v[48:51], v[12:15], v[236:239], v[80:83]
	v_mfma_f32_16x16x32_bf16 v[88:91], v[16:19], v[240:243], v[48:51]
	v_mfma_f32_16x16x32_bf16 v[48:51], v[176:179], v[236:239], v[84:87]
	v_mfma_f32_16x16x32_bf16 v[80:83], v[196:199], v[240:243], v[48:51]
	v_mfma_f32_16x16x32_bf16 v[48:51], v[12:15], v[244:247], v[212:215]
	v_mfma_f32_16x16x32_bf16 v[56:59], v[16:19], v[248:251], v[48:51]
	v_mfma_f32_16x16x32_bf16 v[48:51], v[176:179], v[244:247], v[92:95]
	v_mfma_f32_16x16x32_bf16 v[48:51], v[196:199], v[248:251], v[48:51]
	v_mfma_f32_16x16x32_bf16 v[64:67], v[200:203], v[20:23], v[216:219]
	v_mfma_f32_16x16x32_bf16 v[20:23], v[228:231], v[20:23], v[32:35]
	v_mfma_f32_16x16x32_bf16 v[116:119], v[232:235], v[28:31], v[20:23]
	v_mfma_f32_16x16x32_bf16 v[20:23], v[200:203], v[60:63], v[36:39]
	v_mfma_f32_16x16x32_bf16 v[108:111], v[224:227], v[100:103], v[20:23]
	v_mfma_f32_16x16x32_bf16 v[20:23], v[228:231], v[60:63], v[40:43]
	v_mfma_f32_16x16x32_bf16 v[100:103], v[232:235], v[100:103], v[20:23]
	v_mfma_f32_16x16x32_bf16 v[20:23], v[200:203], v[236:239], v[44:47]
	v_mfma_f32_16x16x32_bf16 v[92:95], v[224:227], v[240:243], v[20:23]
	v_mfma_f32_16x16x32_bf16 v[20:23], v[228:231], v[236:239], v[180:183]
	v_mfma_f32_16x16x32_bf16 v[84:87], v[232:235], v[240:243], v[20:23]
	v_mfma_f32_16x16x32_bf16 v[20:23], v[200:203], v[244:247], v[52:55]
	v_mfma_f32_16x16x32_bf16 v[60:63], v[224:227], v[248:251], v[20:23]
	v_mfma_f32_16x16x32_bf16 v[20:23], v[228:231], v[244:247], v[184:187]
	v_mfma_f32_16x16x32_bf16 v[124:127], v[224:227], v[28:31], v[64:67]
	v_mfma_f32_16x16x32_bf16 v[52:55], v[232:235], v[248:251], v[20:23]
	s_barrier
	s_setprio 1
	s_mov_b32 m0, s87
	s_nop 2
	v_lshl_add_u64 v[20:21], v[140:141], 0, s[14:15]
	s_add_u32 s58, s62, 0x10080
	ds_read_b128 v[32:35], v147 offset:49152
	ds_read_b128 v[40:43], v147 offset:50176
	ds_read_b128 v[180:183], v147 offset:51200
	ds_read_b128 v[184:187], v147 offset:52224
	ds_read_b128 v[212:215], v147 offset:53248
	ds_read_b128 v[216:219], v147 offset:54272
	ds_read_b128 v[236:239], v147 offset:55296
	ds_read_b128 v[240:243], v147 offset:56320
	global_load_lds_dwordx4 v[20:21], off
	v_lshl_add_u64 v[20:21], v[252:253], 0, s[14:15]
	s_mov_b32 m0, s86
	s_addc_u32 s59, s63, 0
	global_load_lds_dwordx4 v[20:21], off
	v_lshl_add_u64 v[20:21], s[58:59], 0, v[130:131]
	s_mov_b32 m0, s60
	s_nop 0
	global_load_lds_dwordx4 v[20:21], off
	v_lshl_add_u64 v[20:21], s[58:59], 0, v[134:135]
	s_mov_b32 m0, s61
	s_nop 0
	global_load_lds_dwordx4 v[20:21], off
	v_lshl_add_u64 v[20:21], v[136:137], 0, s[14:15]
	s_mov_b32 m0, s66
	s_nop 0
	global_load_lds_dwordx4 v[20:21], off
	v_lshl_add_u64 v[20:21], v[138:139], 0, s[14:15]
	s_mov_b32 m0, s67
	s_nop 0
	global_load_lds_dwordx4 v[20:21], off
	s_waitcnt vmcnt(8)
	s_waitcnt lgkmcnt(0)
	s_setprio 0
	s_barrier
	v_mfma_f32_16x16x32_bf16 v[20:23], v[12:15], v[32:35], v[148:151]
	v_mfma_f32_16x16x32_bf16 v[76:79], v[16:19], v[40:43], v[20:23]
	v_mfma_f32_16x16x32_bf16 v[20:23], v[176:179], v[32:35], v[152:155]
	v_mfma_f32_16x16x32_bf16 v[68:71], v[196:199], v[40:43], v[20:23]
	v_mfma_f32_16x16x32_bf16 v[20:23], v[12:15], v[180:183], v[156:159]
	v_mfma_f32_16x16x32_bf16 v[44:47], v[16:19], v[184:187], v[20:23]
	v_mfma_f32_16x16x32_bf16 v[20:23], v[176:179], v[180:183], v[160:163]
	v_mfma_f32_16x16x32_bf16 v[36:39], v[196:199], v[184:187], v[20:23]
	v_mfma_f32_16x16x32_bf16 v[20:23], v[12:15], v[212:215], v[164:167]
	v_mfma_f32_16x16x32_bf16 v[0:3], v[12:15], v[236:239], v[0:3]
	v_mfma_f32_16x16x32_bf16 v[28:31], v[16:19], v[216:219], v[20:23]
	v_mfma_f32_16x16x32_bf16 v[20:23], v[176:179], v[212:215], v[168:171]
	v_mfma_f32_16x16x32_bf16 v[12:15], v[16:19], v[240:243], v[0:3]
	v_mfma_f32_16x16x32_bf16 v[0:3], v[176:179], v[236:239], v[4:7]
	v_mfma_f32_16x16x32_bf16 v[20:23], v[196:199], v[216:219], v[20:23]
	v_mfma_f32_16x16x32_bf16 v[4:7], v[196:199], v[240:243], v[0:3]
	v_mfma_f32_16x16x32_bf16 v[0:3], v[200:203], v[32:35], v[8:11]
	v_mfma_f32_16x16x32_bf16 v[72:75], v[224:227], v[40:43], v[0:3]
	v_mfma_f32_16x16x32_bf16 v[0:3], v[228:231], v[32:35], v[204:207]
	v_mfma_f32_16x16x32_bf16 v[64:67], v[232:235], v[40:43], v[0:3]
	v_mfma_f32_16x16x32_bf16 v[0:3], v[200:203], v[180:183], v[24:27]
	v_mfma_f32_16x16x32_bf16 v[40:43], v[224:227], v[184:187], v[0:3]
	v_mfma_f32_16x16x32_bf16 v[0:3], v[228:231], v[180:183], v[208:211]
	v_mfma_f32_16x16x32_bf16 v[32:35], v[232:235], v[184:187], v[0:3]
	v_mfma_f32_16x16x32_bf16 v[0:3], v[200:203], v[212:215], v[220:223]
	v_mfma_f32_16x16x32_bf16 v[24:27], v[224:227], v[216:219], v[0:3]
	v_mfma_f32_16x16x32_bf16 v[0:3], v[228:231], v[212:215], v[188:191]
	v_mfma_f32_16x16x32_bf16 v[16:19], v[232:235], v[216:219], v[0:3]
	v_mfma_f32_16x16x32_bf16 v[0:3], v[200:203], v[236:239], v[192:195]
	v_mfma_f32_16x16x32_bf16 v[8:11], v[224:227], v[240:243], v[0:3]
	v_mfma_f32_16x16x32_bf16 v[0:3], v[228:231], v[236:239], v[172:175]
	v_mfma_f32_16x16x32_bf16 v[0:3], v[232:235], v[240:243], v[0:3]
	s_barrier
	s_setprio 1
	s_andn2_b64 vcc, exec, s[16:17]
	s_cbranch_vccnz .LBB0_710
	s_barrier
	s_setprio 3

.LBB0_731:
	ds_read_b128 v[146:149], v153
	ds_read_b128 v[158:161], v153 offset:1024
	ds_read_b128 v[162:165], v153 offset:2048
	ds_read_b128 v[166:169], v153 offset:3072
	ds_read_b128 v[170:173], v154
	ds_read_b128 v[174:177], v154 offset:1024
	ds_read_b128 v[178:181], v154 offset:2048
	ds_read_b128 v[182:185], v154 offset:3072
	s_add_u32 s34, s30, 0xfff80080
	s_addc_u32 s35, s31, -1
	s_cmp_eq_u32 s61, 28
	s_cselect_b32 s37, s21, s35
	s_cselect_b32 s36, s46, s34
	s_cselect_b32 s35, s19, s60
	s_cselect_b32 s34, s47, s59
	v_lshl_add_u64 v[218:219], s[30:31], 0, v[140:141]
	s_add_i32 m0, s27, 0xc000
	ds_read_b128 v[186:189], v155
	ds_read_b128 v[190:193], v155 offset:1024
	ds_read_b128 v[194:197], v155 offset:2048
	ds_read_b128 v[198:201], v155 offset:3072
	ds_read_b128 v[202:205], v155 offset:4096
	ds_read_b128 v[206:209], v155 offset:5120
	ds_read_b128 v[210:213], v155 offset:6144
	ds_read_b128 v[214:217], v155 offset:7168
	global_load_lds_dwordx4 v[218:219], off
	v_lshl_add_u64 v[218:219], s[30:31], 0, v[138:139]
	s_add_i32 m0, s27, 0xe000
	s_nop 0
	global_load_lds_dwordx4 v[218:219], off
	s_waitcnt vmcnt(8)
	s_waitcnt lgkmcnt(0)
	s_setprio 0
	s_barrier
	v_mfma_f32_16x16x32_bf16 v[124:127], v[146:149], v[186:189], v[124:127]
	v_mfma_f32_16x16x32_bf16 v[120:123], v[162:165], v[186:189], v[120:123]
	v_mfma_f32_16x16x32_bf16 v[108:111], v[146:149], v[194:197], v[108:111]
	v_mfma_f32_16x16x32_bf16 v[104:107], v[162:165], v[194:197], v[104:107]
	v_mfma_f32_16x16x32_bf16 v[92:95], v[146:149], v[202:205], v[92:95]
	v_mfma_f32_16x16x32_bf16 v[88:91], v[162:165], v[202:205], v[88:91]
	v_mfma_f32_16x16x32_bf16 v[76:79], v[146:149], v[210:213], v[76:79]
	v_mfma_f32_16x16x32_bf16 v[72:75], v[162:165], v[210:213], v[72:75]
	v_mfma_f32_16x16x32_bf16 v[124:127], v[158:161], v[190:193], v[124:127]
	v_mfma_f32_16x16x32_bf16 v[120:123], v[166:169], v[190:193], v[120:123]
	v_mfma_f32_16x16x32_bf16 v[108:111], v[158:161], v[198:201], v[108:111]
	v_mfma_f32_16x16x32_bf16 v[104:107], v[166:169], v[198:201], v[104:107]
	v_mfma_f32_16x16x32_bf16 v[92:95], v[158:161], v[206:209], v[92:95]
	v_mfma_f32_16x16x32_bf16 v[88:91], v[166:169], v[206:209], v[88:91]
	v_mfma_f32_16x16x32_bf16 v[76:79], v[158:161], v[214:217], v[76:79]
	v_mfma_f32_16x16x32_bf16 v[72:75], v[166:169], v[214:217], v[72:75]
	v_mfma_f32_16x16x32_bf16 v[116:119], v[170:173], v[186:189], v[116:119]
	v_mfma_f32_16x16x32_bf16 v[112:115], v[178:181], v[186:189], v[112:115]
	v_mfma_f32_16x16x32_bf16 v[100:103], v[170:173], v[194:197], v[100:103]
	v_mfma_f32_16x16x32_bf16 v[96:99], v[178:181], v[194:197], v[96:99]
	v_mfma_f32_16x16x32_bf16 v[84:87], v[170:173], v[202:205], v[84:87]
	v_mfma_f32_16x16x32_bf16 v[80:83], v[178:181], v[202:205], v[80:83]
	v_mfma_f32_16x16x32_bf16 v[68:71], v[170:173], v[210:213], v[68:71]
	v_mfma_f32_16x16x32_bf16 v[64:67], v[178:181], v[210:213], v[64:67]
	v_mfma_f32_16x16x32_bf16 v[116:119], v[174:177], v[190:193], v[116:119]
	v_mfma_f32_16x16x32_bf16 v[112:115], v[182:185], v[190:193], v[112:115]
	v_mfma_f32_16x16x32_bf16 v[100:103], v[174:177], v[198:201], v[100:103]
	v_mfma_f32_16x16x32_bf16 v[96:99], v[182:185], v[198:201], v[96:99]
	v_mfma_f32_16x16x32_bf16 v[84:87], v[174:177], v[206:209], v[84:87]
	v_mfma_f32_16x16x32_bf16 v[80:83], v[182:185], v[206:209], v[80:83]
	v_mfma_f32_16x16x32_bf16 v[68:71], v[174:177], v[214:217], v[68:71]
	v_mfma_f32_16x16x32_bf16 v[64:67], v[182:185], v[214:217], v[64:67]
	s_barrier
	s_setprio 1
	s_add_i32 s62, s55, s48
	v_lshl_add_u64 v[218:219], s[34:35], 0, v[130:131]
	s_mov_b32 m0, s62
	ds_read_b128 v[186:189], v155 offset:16384
	ds_read_b128 v[190:193], v155 offset:17408
	ds_read_b128 v[194:197], v155 offset:18432
	ds_read_b128 v[198:201], v155 offset:19456
	ds_read_b128 v[202:205], v155 offset:20480
	ds_read_b128 v[206:209], v155 offset:21504
	ds_read_b128 v[210:213], v155 offset:22528
	ds_read_b128 v[214:217], v155 offset:23552
	global_load_lds_dwordx4 v[218:219], off
	s_add_i32 m0, s62, 0x2000
	s_add_u32 s62, s34, 0x80000
	v_lshl_add_u64 v[220:221], s[34:35], 0, v[134:135]
	s_addc_u32 s63, s35, 0
	s_add_i32 s64, s56, s48
	global_load_lds_dwordx4 v[220:221], off
	v_lshl_add_u64 v[222:223], s[62:63], 0, v[130:131]
	s_mov_b32 m0, s64
	v_lshl_add_u64 v[224:225], s[36:37], 0, v[132:133]
	global_load_lds_dwordx4 v[222:223], off
	v_lshl_add_u64 v[222:223], s[62:63], 0, v[134:135]
	s_add_i32 m0, s64, 0x2000
	s_nop 0
	global_load_lds_dwordx4 v[222:223], off
	v_lshl_add_u64 v[222:223], s[36:37], 0, v[128:129]
	s_mov_b32 m0, s27
	s_nop 0
	global_load_lds_dwordx4 v[222:223], off
	s_mov_b32 m0, s49
	s_nop 0
	global_load_lds_dwordx4 v[224:225], off
	s_waitcnt vmcnt(8)
	s_waitcnt lgkmcnt(0)
	s_setprio 0
	s_barrier
	v_mfma_f32_16x16x32_bf16 v[60:63], v[146:149], v[186:189], v[60:63]
	v_mfma_f32_16x16x32_bf16 v[56:59], v[162:165], v[186:189], v[56:59]
	v_mfma_f32_16x16x32_bf16 v[44:47], v[146:149], v[194:197], v[44:47]
	v_mfma_f32_16x16x32_bf16 v[40:43], v[162:165], v[194:197], v[40:43]
	v_mfma_f32_16x16x32_bf16 v[28:31], v[146:149], v[202:205], v[28:31]
	v_mfma_f32_16x16x32_bf16 v[24:27], v[162:165], v[202:205], v[24:27]
	v_mfma_f32_16x16x32_bf16 v[12:15], v[146:149], v[210:213], v[12:15]
	v_mfma_f32_16x16x32_bf16 v[8:11], v[162:165], v[210:213], v[8:11]
	v_mfma_f32_16x16x32_bf16 v[60:63], v[158:161], v[190:193], v[60:63]
	v_mfma_f32_16x16x32_bf16 v[56:59], v[166:169], v[190:193], v[56:59]
	v_mfma_f32_16x16x32_bf16 v[44:47], v[158:161], v[198:201], v[44:47]
	v_mfma_f32_16x16x32_bf16 v[40:43], v[166:169], v[198:201], v[40:43]
	v_mfma_f32_16x16x32_bf16 v[28:31], v[158:161], v[206:209], v[28:31]
	v_mfma_f32_16x16x32_bf16 v[24:27], v[166:169], v[206:209], v[24:27]
	v_mfma_f32_16x16x32_bf16 v[12:15], v[158:161], v[214:217], v[12:15]
	v_mfma_f32_16x16x32_bf16 v[8:11], v[166:169], v[214:217], v[8:11]
	v_mfma_f32_16x16x32_bf16 v[52:55], v[170:173], v[186:189], v[52:55]
	v_mfma_f32_16x16x32_bf16 v[48:51], v[178:181], v[186:189], v[48:51]
	v_mfma_f32_16x16x32_bf16 v[36:39], v[170:173], v[194:197], v[36:39]
	v_mfma_f32_16x16x32_bf16 v[32:35], v[178:181], v[194:197], v[32:35]
	v_mfma_f32_16x16x32_bf16 v[20:23], v[170:173], v[202:205], v[20:23]
	v_mfma_f32_16x16x32_bf16 v[16:19], v[178:181], v[202:205], v[16:19]
	v_mfma_f32_16x16x32_bf16 v[4:7], v[170:173], v[210:213], v[4:7]
	v_mfma_f32_16x16x32_bf16 v[0:3], v[178:181], v[210:213], v[0:3]
	v_mfma_f32_16x16x32_bf16 v[52:55], v[174:177], v[190:193], v[52:55]
	v_mfma_f32_16x16x32_bf16 v[48:51], v[182:185], v[190:193], v[48:51]
	v_mfma_f32_16x16x32_bf16 v[36:39], v[174:177], v[198:201], v[36:39]
	v_mfma_f32_16x16x32_bf16 v[32:35], v[182:185], v[198:201], v[32:35]
	v_mfma_f32_16x16x32_bf16 v[20:23], v[174:177], v[206:209], v[20:23]
	v_mfma_f32_16x16x32_bf16 v[16:19], v[182:185], v[206:209], v[16:19]
	v_mfma_f32_16x16x32_bf16 v[4:7], v[174:177], v[214:217], v[4:7]
	v_mfma_f32_16x16x32_bf16 v[0:3], v[182:185], v[214:217], v[0:3]
	s_barrier
	s_setprio 1
	s_add_i32 s62, 0, 0x18000
	s_add_i32 s63, 0, 0x1c000
	v_add_u32_e32 v166, s62, v151
	v_add_u32_e32 v182, s63, v151
	ds_read_b128 v[146:149], v166
	ds_read_b128 v[158:161], v166 offset:1024
	ds_read_b128 v[162:165], v166 offset:2048
	ds_read_b128 v[166:169], v166 offset:3072
	ds_read_b128 v[170:173], v182
	ds_read_b128 v[174:177], v182 offset:1024
	ds_read_b128 v[178:181], v182 offset:2048
	ds_read_b128 v[182:185], v182 offset:3072
	s_add_u32 s36, s36, 0x80000
	s_addc_u32 s37, s37, 0
	s_mov_b32 m0, s50
	v_lshl_add_u64 v[226:227], s[36:37], 0, v[128:129]
	ds_read_b128 v[186:189], v155 offset:32768
	ds_read_b128 v[190:193], v155 offset:33792
	ds_read_b128 v[194:197], v155 offset:34816
	ds_read_b128 v[198:201], v155 offset:35840
	ds_read_b128 v[202:205], v155 offset:36864
	ds_read_b128 v[206:209], v155 offset:37888
	ds_read_b128 v[210:213], v155 offset:38912
	ds_read_b128 v[214:217], v155 offset:39936
	global_load_lds_dwordx4 v[226:227], off
	v_lshl_add_u64 v[226:227], s[36:37], 0, v[132:133]
	s_mov_b32 m0, s51
	s_nop 0
	global_load_lds_dwordx4 v[226:227], off
	s_waitcnt vmcnt(8)
	s_waitcnt lgkmcnt(0)
	s_setprio 0
	s_barrier
	v_mfma_f32_16x16x32_bf16 v[124:127], v[146:149], v[186:189], v[124:127]
	v_mfma_f32_16x16x32_bf16 v[120:123], v[162:165], v[186:189], v[120:123]
	v_mfma_f32_16x16x32_bf16 v[108:111], v[146:149], v[194:197], v[108:111]
	v_mfma_f32_16x16x32_bf16 v[104:107], v[162:165], v[194:197], v[104:107]
	v_mfma_f32_16x16x32_bf16 v[92:95], v[146:149], v[202:205], v[92:95]
	v_mfma_f32_16x16x32_bf16 v[88:91], v[162:165], v[202:205], v[88:91]
	v_mfma_f32_16x16x32_bf16 v[76:79], v[146:149], v[210:213], v[76:79]
	v_mfma_f32_16x16x32_bf16 v[72:75], v[162:165], v[210:213], v[72:75]
	v_mfma_f32_16x16x32_bf16 v[124:127], v[158:161], v[190:193], v[124:127]
	v_mfma_f32_16x16x32_bf16 v[120:123], v[166:169], v[190:193], v[120:123]
	v_mfma_f32_16x16x32_bf16 v[108:111], v[158:161], v[198:201], v[108:111]
	v_mfma_f32_16x16x32_bf16 v[104:107], v[166:169], v[198:201], v[104:107]
	v_mfma_f32_16x16x32_bf16 v[92:95], v[158:161], v[206:209], v[92:95]
	v_mfma_f32_16x16x32_bf16 v[88:91], v[166:169], v[206:209], v[88:91]
	v_mfma_f32_16x16x32_bf16 v[76:79], v[158:161], v[214:217], v[76:79]
	v_mfma_f32_16x16x32_bf16 v[72:75], v[166:169], v[214:217], v[72:75]
	v_mfma_f32_16x16x32_bf16 v[116:119], v[170:173], v[186:189], v[116:119]
	v_mfma_f32_16x16x32_bf16 v[112:115], v[178:181], v[186:189], v[112:115]
	v_mfma_f32_16x16x32_bf16 v[100:103], v[170:173], v[194:197], v[100:103]
	v_mfma_f32_16x16x32_bf16 v[96:99], v[178:181], v[194:197], v[96:99]
	v_mfma_f32_16x16x32_bf16 v[84:87], v[170:173], v[202:205], v[84:87]
	v_mfma_f32_16x16x32_bf16 v[80:83], v[178:181], v[202:205], v[80:83]
	v_mfma_f32_16x16x32_bf16 v[68:71], v[170:173], v[210:213], v[68:71]
	v_mfma_f32_16x16x32_bf16 v[64:67], v[178:181], v[210:213], v[64:67]
	v_mfma_f32_16x16x32_bf16 v[116:119], v[174:177], v[190:193], v[116:119]
	v_mfma_f32_16x16x32_bf16 v[112:115], v[182:185], v[190:193], v[112:115]
	v_mfma_f32_16x16x32_bf16 v[100:103], v[174:177], v[198:201], v[100:103]
	v_mfma_f32_16x16x32_bf16 v[96:99], v[182:185], v[198:201], v[96:99]
	v_mfma_f32_16x16x32_bf16 v[84:87], v[174:177], v[206:209], v[84:87]
	v_mfma_f32_16x16x32_bf16 v[80:83], v[182:185], v[206:209], v[80:83]
	v_mfma_f32_16x16x32_bf16 v[68:71], v[174:177], v[214:217], v[68:71]
	v_mfma_f32_16x16x32_bf16 v[64:67], v[182:185], v[214:217], v[64:67]
	s_barrier
	s_setprio 1
	s_add_i32 s36, s62, s48
	v_lshl_add_u64 v[218:219], v[218:219], 0, s[14:15]
	s_mov_b32 m0, s36
	ds_read_b128 v[186:189], v155 offset:49152
	ds_read_b128 v[190:193], v155 offset:50176
	ds_read_b128 v[194:197], v155 offset:51200
	ds_read_b128 v[198:201], v155 offset:52224
	ds_read_b128 v[202:205], v155 offset:53248
	ds_read_b128 v[206:209], v155 offset:54272
	ds_read_b128 v[210:213], v155 offset:55296
	ds_read_b128 v[214:217], v155 offset:56320
	global_load_lds_dwordx4 v[218:219], off
	s_add_i32 m0, s36, 0x2000
	s_add_u32 s34, s34, 0x80080
	v_lshl_add_u64 v[218:219], v[220:221], 0, s[14:15]
	s_addc_u32 s35, s35, 0
	s_add_i32 s36, s63, s48
	global_load_lds_dwordx4 v[218:219], off
	v_lshl_add_u64 v[218:219], s[34:35], 0, v[130:131]
	s_mov_b32 m0, s36
	s_nop 0
	global_load_lds_dwordx4 v[218:219], off
	v_lshl_add_u64 v[218:219], s[34:35], 0, v[134:135]
	s_add_i32 m0, s36, 0x2000
	s_nop 0
	global_load_lds_dwordx4 v[218:219], off
	v_lshl_add_u64 v[218:219], v[222:223], 0, s[14:15]
	s_mov_b32 m0, s53
	s_nop 0
	global_load_lds_dwordx4 v[218:219], off
	v_lshl_add_u64 v[218:219], v[224:225], 0, s[14:15]
	s_mov_b32 m0, s54
	s_nop 0
	global_load_lds_dwordx4 v[218:219], off
	s_waitcnt vmcnt(8)
	s_waitcnt lgkmcnt(0)
	s_setprio 0
	s_barrier
	v_mfma_f32_16x16x32_bf16 v[60:63], v[146:149], v[186:189], v[60:63]
	v_mfma_f32_16x16x32_bf16 v[56:59], v[162:165], v[186:189], v[56:59]
	v_mfma_f32_16x16x32_bf16 v[44:47], v[146:149], v[194:197], v[44:47]
	v_mfma_f32_16x16x32_bf16 v[40:43], v[162:165], v[194:197], v[40:43]
	v_mfma_f32_16x16x32_bf16 v[28:31], v[146:149], v[202:205], v[28:31]
	v_mfma_f32_16x16x32_bf16 v[24:27], v[162:165], v[202:205], v[24:27]
	v_mfma_f32_16x16x32_bf16 v[12:15], v[146:149], v[210:213], v[12:15]
	v_mfma_f32_16x16x32_bf16 v[8:11], v[162:165], v[210:213], v[8:11]
	v_mfma_f32_16x16x32_bf16 v[60:63], v[158:161], v[190:193], v[60:63]
	v_mfma_f32_16x16x32_bf16 v[56:59], v[166:169], v[190:193], v[56:59]
	v_mfma_f32_16x16x32_bf16 v[44:47], v[158:161], v[198:201], v[44:47]
	v_mfma_f32_16x16x32_bf16 v[40:43], v[166:169], v[198:201], v[40:43]
	v_mfma_f32_16x16x32_bf16 v[28:31], v[158:161], v[206:209], v[28:31]
	v_mfma_f32_16x16x32_bf16 v[24:27], v[166:169], v[206:209], v[24:27]
	v_mfma_f32_16x16x32_bf16 v[12:15], v[158:161], v[214:217], v[12:15]
	v_mfma_f32_16x16x32_bf16 v[8:11], v[166:169], v[214:217], v[8:11]
	v_mfma_f32_16x16x32_bf16 v[52:55], v[170:173], v[186:189], v[52:55]
	v_mfma_f32_16x16x32_bf16 v[48:51], v[178:181], v[186:189], v[48:51]
	v_mfma_f32_16x16x32_bf16 v[36:39], v[170:173], v[194:197], v[36:39]
	v_mfma_f32_16x16x32_bf16 v[32:35], v[178:181], v[194:197], v[32:35]
	v_mfma_f32_16x16x32_bf16 v[20:23], v[170:173], v[202:205], v[20:23]
	v_mfma_f32_16x16x32_bf16 v[16:19], v[178:181], v[202:205], v[16:19]
	v_mfma_f32_16x16x32_bf16 v[4:7], v[170:173], v[210:213], v[4:7]
	v_mfma_f32_16x16x32_bf16 v[0:3], v[178:181], v[210:213], v[0:3]
	v_mfma_f32_16x16x32_bf16 v[52:55], v[174:177], v[190:193], v[52:55]
	v_mfma_f32_16x16x32_bf16 v[48:51], v[182:185], v[190:193], v[48:51]
	v_mfma_f32_16x16x32_bf16 v[36:39], v[174:177], v[198:201], v[36:39]
	v_mfma_f32_16x16x32_bf16 v[32:35], v[182:185], v[198:201], v[32:35]
	v_mfma_f32_16x16x32_bf16 v[20:23], v[174:177], v[206:209], v[20:23]
	v_mfma_f32_16x16x32_bf16 v[16:19], v[182:185], v[206:209], v[16:19]
	v_mfma_f32_16x16x32_bf16 v[4:7], v[174:177], v[214:217], v[4:7]
	v_mfma_f32_16x16x32_bf16 v[0:3], v[182:185], v[214:217], v[0:3]
	s_barrier
	s_setprio 1
	s_add_i32 s61, s61, 2
	s_add_u32 s59, s59, 0x100
	s_addc_u32 s60, s60, 0
	s_add_u32 s30, s30, 0x100
	s_addc_u32 s31, s31, 0
	s_cmp_gt_u32 s61, 29
	s_cbranch_scc0 .LBB0_731
	s_and_b64 vcc, exec, s[16:17]
	s_cbranch_vccz .LBB0_734
	s_barrier
	s_setprio 3

.LBB0_952:
	ds_read_b128 v[144:147], v151
	ds_read_b128 v[156:159], v151 offset:1024
	ds_read_b128 v[160:163], v151 offset:2048
	ds_read_b128 v[164:167], v151 offset:3072
	ds_read_b128 v[168:171], v152
	ds_read_b128 v[172:175], v152 offset:1024
	ds_read_b128 v[176:179], v152 offset:2048
	ds_read_b128 v[180:183], v152 offset:3072
	s_add_u32 s54, s52, 0xfff80080
	s_addc_u32 s55, s53, -1
	s_cmp_eq_u32 s68, 28
	s_cselect_b32 s57, s27, s55
	s_cselect_b32 s56, s37, s54
	s_cselect_b32 s55, s25, s67
	s_cselect_b32 s54, s46, s47
	v_lshl_add_u64 v[216:217], s[52:53], 0, v[138:139]
	s_add_i32 m0, s59, 0xc000
	ds_read_b128 v[184:187], v153
	ds_read_b128 v[188:191], v153 offset:1024
	ds_read_b128 v[192:195], v153 offset:2048
	ds_read_b128 v[196:199], v153 offset:3072
	ds_read_b128 v[200:203], v153 offset:4096
	ds_read_b128 v[204:207], v153 offset:5120
	ds_read_b128 v[208:211], v153 offset:6144
	ds_read_b128 v[212:215], v153 offset:7168
	global_load_lds_dwordx4 v[216:217], off
	v_lshl_add_u64 v[216:217], s[52:53], 0, v[136:137]
	s_add_i32 m0, s59, 0xe000
	s_nop 0
	global_load_lds_dwordx4 v[216:217], off
	s_waitcnt vmcnt(8)
	s_waitcnt lgkmcnt(0)
	s_setprio 0
	s_barrier
	v_mfma_f32_16x16x32_bf16 v[116:119], v[144:147], v[184:187], v[116:119]
	v_mfma_f32_16x16x32_bf16 v[112:115], v[160:163], v[184:187], v[112:115]
	v_mfma_f32_16x16x32_bf16 v[104:107], v[144:147], v[192:195], v[104:107]
	v_mfma_f32_16x16x32_bf16 v[96:99], v[160:163], v[192:195], v[96:99]
	v_mfma_f32_16x16x32_bf16 v[88:91], v[144:147], v[200:203], v[88:91]
	v_mfma_f32_16x16x32_bf16 v[80:83], v[160:163], v[200:203], v[80:83]
	v_mfma_f32_16x16x32_bf16 v[72:75], v[144:147], v[208:211], v[72:75]
	v_mfma_f32_16x16x32_bf16 v[64:67], v[160:163], v[208:211], v[64:67]
	v_mfma_f32_16x16x32_bf16 v[116:119], v[156:159], v[188:191], v[116:119]
	v_mfma_f32_16x16x32_bf16 v[112:115], v[164:167], v[188:191], v[112:115]
	v_mfma_f32_16x16x32_bf16 v[104:107], v[156:159], v[196:199], v[104:107]
	v_mfma_f32_16x16x32_bf16 v[96:99], v[164:167], v[196:199], v[96:99]
	v_mfma_f32_16x16x32_bf16 v[88:91], v[156:159], v[204:207], v[88:91]
	v_mfma_f32_16x16x32_bf16 v[80:83], v[164:167], v[204:207], v[80:83]
	v_mfma_f32_16x16x32_bf16 v[72:75], v[156:159], v[212:215], v[72:75]
	v_mfma_f32_16x16x32_bf16 v[64:67], v[164:167], v[212:215], v[64:67]
	v_mfma_f32_16x16x32_bf16 v[124:127], v[168:171], v[184:187], v[124:127]
	v_mfma_f32_16x16x32_bf16 v[120:123], v[176:179], v[184:187], v[120:123]
	v_mfma_f32_16x16x32_bf16 v[108:111], v[168:171], v[192:195], v[108:111]
	v_mfma_f32_16x16x32_bf16 v[100:103], v[176:179], v[192:195], v[100:103]
	v_mfma_f32_16x16x32_bf16 v[92:95], v[168:171], v[200:203], v[92:95]
	v_mfma_f32_16x16x32_bf16 v[84:87], v[176:179], v[200:203], v[84:87]
	v_mfma_f32_16x16x32_bf16 v[76:79], v[168:171], v[208:211], v[76:79]
	v_mfma_f32_16x16x32_bf16 v[68:71], v[176:179], v[208:211], v[68:71]
	v_mfma_f32_16x16x32_bf16 v[124:127], v[172:175], v[188:191], v[124:127]
	v_mfma_f32_16x16x32_bf16 v[120:123], v[180:183], v[188:191], v[120:123]
	v_mfma_f32_16x16x32_bf16 v[108:111], v[172:175], v[196:199], v[108:111]
	v_mfma_f32_16x16x32_bf16 v[100:103], v[180:183], v[196:199], v[100:103]
	v_mfma_f32_16x16x32_bf16 v[92:95], v[172:175], v[204:207], v[92:95]
	v_mfma_f32_16x16x32_bf16 v[84:87], v[180:183], v[204:207], v[84:87]
	v_mfma_f32_16x16x32_bf16 v[76:79], v[172:175], v[212:215], v[76:79]
	v_mfma_f32_16x16x32_bf16 v[68:71], v[180:183], v[212:215], v[68:71]
	s_barrier
	s_setprio 1
	s_add_i32 s69, s64, s58
	v_lshl_add_u64 v[216:217], s[54:55], 0, v[130:131]
	s_mov_b32 m0, s69
	ds_read_b128 v[184:187], v153 offset:16384
	ds_read_b128 v[188:191], v153 offset:17408
	ds_read_b128 v[192:195], v153 offset:18432
	ds_read_b128 v[196:199], v153 offset:19456
	ds_read_b128 v[200:203], v153 offset:20480
	ds_read_b128 v[204:207], v153 offset:21504
	ds_read_b128 v[208:211], v153 offset:22528
	ds_read_b128 v[212:215], v153 offset:23552
	global_load_lds_dwordx4 v[216:217], off
	s_add_i32 m0, s69, 0x2000
	s_add_u32 s70, s54, 0x80000
	v_lshl_add_u64 v[218:219], s[54:55], 0, v[134:135]
	s_addc_u32 s71, s55, 0
	s_add_i32 s69, s65, s58
	global_load_lds_dwordx4 v[218:219], off
	v_lshl_add_u64 v[220:221], s[70:71], 0, v[130:131]
	s_mov_b32 m0, s69
	v_lshl_add_u64 v[222:223], s[56:57], 0, v[132:133]
	global_load_lds_dwordx4 v[220:221], off
	v_lshl_add_u64 v[220:221], s[70:71], 0, v[134:135]
	s_add_i32 m0, s69, 0x2000
	s_nop 0
	global_load_lds_dwordx4 v[220:221], off
	v_lshl_add_u64 v[220:221], s[56:57], 0, v[128:129]
	s_mov_b32 m0, s59
	s_nop 0
	global_load_lds_dwordx4 v[220:221], off
	s_mov_b32 m0, s50
	s_nop 0
	global_load_lds_dwordx4 v[222:223], off
	s_waitcnt vmcnt(8)
	s_waitcnt lgkmcnt(0)
	s_setprio 0
	s_barrier
	v_mfma_f32_16x16x32_bf16 v[56:59], v[144:147], v[184:187], v[56:59]
	v_mfma_f32_16x16x32_bf16 v[48:51], v[160:163], v[184:187], v[48:51]
	v_mfma_f32_16x16x32_bf16 v[40:43], v[144:147], v[192:195], v[40:43]
	v_mfma_f32_16x16x32_bf16 v[32:35], v[160:163], v[192:195], v[32:35]
	v_mfma_f32_16x16x32_bf16 v[24:27], v[144:147], v[200:203], v[24:27]
	v_mfma_f32_16x16x32_bf16 v[16:19], v[160:163], v[200:203], v[16:19]
	v_mfma_f32_16x16x32_bf16 v[8:11], v[144:147], v[208:211], v[8:11]
	v_mfma_f32_16x16x32_bf16 v[0:3], v[160:163], v[208:211], v[0:3]
	v_mfma_f32_16x16x32_bf16 v[56:59], v[156:159], v[188:191], v[56:59]
	v_mfma_f32_16x16x32_bf16 v[48:51], v[164:167], v[188:191], v[48:51]
	v_mfma_f32_16x16x32_bf16 v[40:43], v[156:159], v[196:199], v[40:43]
	v_mfma_f32_16x16x32_bf16 v[32:35], v[164:167], v[196:199], v[32:35]
	v_mfma_f32_16x16x32_bf16 v[24:27], v[156:159], v[204:207], v[24:27]
	v_mfma_f32_16x16x32_bf16 v[16:19], v[164:167], v[204:207], v[16:19]
	v_mfma_f32_16x16x32_bf16 v[8:11], v[156:159], v[212:215], v[8:11]
	v_mfma_f32_16x16x32_bf16 v[0:3], v[164:167], v[212:215], v[0:3]
	v_mfma_f32_16x16x32_bf16 v[60:63], v[168:171], v[184:187], v[60:63]
	v_mfma_f32_16x16x32_bf16 v[52:55], v[176:179], v[184:187], v[52:55]
	v_mfma_f32_16x16x32_bf16 v[44:47], v[168:171], v[192:195], v[44:47]
	v_mfma_f32_16x16x32_bf16 v[36:39], v[176:179], v[192:195], v[36:39]
	v_mfma_f32_16x16x32_bf16 v[28:31], v[168:171], v[200:203], v[28:31]
	v_mfma_f32_16x16x32_bf16 v[20:23], v[176:179], v[200:203], v[20:23]
	v_mfma_f32_16x16x32_bf16 v[12:15], v[168:171], v[208:211], v[12:15]
	v_mfma_f32_16x16x32_bf16 v[4:7], v[176:179], v[208:211], v[4:7]
	v_mfma_f32_16x16x32_bf16 v[60:63], v[172:175], v[188:191], v[60:63]
	v_mfma_f32_16x16x32_bf16 v[52:55], v[180:183], v[188:191], v[52:55]
	v_mfma_f32_16x16x32_bf16 v[44:47], v[172:175], v[196:199], v[44:47]
	v_mfma_f32_16x16x32_bf16 v[36:39], v[180:183], v[196:199], v[36:39]
	v_mfma_f32_16x16x32_bf16 v[28:31], v[172:175], v[204:207], v[28:31]
	v_mfma_f32_16x16x32_bf16 v[20:23], v[180:183], v[204:207], v[20:23]
	v_mfma_f32_16x16x32_bf16 v[12:15], v[172:175], v[212:215], v[12:15]
	v_mfma_f32_16x16x32_bf16 v[4:7], v[180:183], v[212:215], v[4:7]
	s_barrier
	s_setprio 1
	s_add_i32 s69, 0, 0x18000
	v_add_u32_e32 v155, s69, v149
	s_add_i32 s70, 0, 0x1c000
	ds_read_b128 v[144:147], v155
	ds_read_b128 v[156:159], v155 offset:1024
	ds_read_b128 v[160:163], v155 offset:2048
	ds_read_b128 v[164:167], v155 offset:3072
	v_add_u32_e32 v155, s70, v149
	ds_read_b128 v[168:171], v155
	ds_read_b128 v[172:175], v155 offset:1024
	ds_read_b128 v[176:179], v155 offset:2048
	ds_read_b128 v[180:183], v155 offset:3072
	s_add_u32 s56, s56, 0x80000
	s_addc_u32 s57, s57, 0
	s_mov_b32 m0, s51
	v_lshl_add_u64 v[224:225], s[56:57], 0, v[128:129]
	ds_read_b128 v[184:187], v153 offset:32768
	ds_read_b128 v[188:191], v153 offset:33792
	ds_read_b128 v[192:195], v153 offset:34816
	ds_read_b128 v[196:199], v153 offset:35840
	ds_read_b128 v[200:203], v153 offset:36864
	ds_read_b128 v[204:207], v153 offset:37888
	ds_read_b128 v[208:211], v153 offset:38912
	ds_read_b128 v[212:215], v153 offset:39936
	global_load_lds_dwordx4 v[224:225], off
	v_lshl_add_u64 v[224:225], s[56:57], 0, v[132:133]
	s_mov_b32 m0, s60
	s_nop 0
	global_load_lds_dwordx4 v[224:225], off
	s_waitcnt vmcnt(8)
	s_waitcnt lgkmcnt(0)
	s_setprio 0
	s_barrier
	v_mfma_f32_16x16x32_bf16 v[116:119], v[144:147], v[184:187], v[116:119]
	v_mfma_f32_16x16x32_bf16 v[112:115], v[160:163], v[184:187], v[112:115]
	v_mfma_f32_16x16x32_bf16 v[104:107], v[144:147], v[192:195], v[104:107]
	v_mfma_f32_16x16x32_bf16 v[96:99], v[160:163], v[192:195], v[96:99]
	v_mfma_f32_16x16x32_bf16 v[88:91], v[144:147], v[200:203], v[88:91]
	v_mfma_f32_16x16x32_bf16 v[80:83], v[160:163], v[200:203], v[80:83]
	v_mfma_f32_16x16x32_bf16 v[72:75], v[144:147], v[208:211], v[72:75]
	v_mfma_f32_16x16x32_bf16 v[64:67], v[160:163], v[208:211], v[64:67]
	v_mfma_f32_16x16x32_bf16 v[116:119], v[156:159], v[188:191], v[116:119]
	v_mfma_f32_16x16x32_bf16 v[112:115], v[164:167], v[188:191], v[112:115]
	v_mfma_f32_16x16x32_bf16 v[104:107], v[156:159], v[196:199], v[104:107]
	v_mfma_f32_16x16x32_bf16 v[96:99], v[164:167], v[196:199], v[96:99]
	v_mfma_f32_16x16x32_bf16 v[88:91], v[156:159], v[204:207], v[88:91]
	v_mfma_f32_16x16x32_bf16 v[80:83], v[164:167], v[204:207], v[80:83]
	v_mfma_f32_16x16x32_bf16 v[72:75], v[156:159], v[212:215], v[72:75]
	v_mfma_f32_16x16x32_bf16 v[64:67], v[164:167], v[212:215], v[64:67]
	v_mfma_f32_16x16x32_bf16 v[124:127], v[168:171], v[184:187], v[124:127]
	v_mfma_f32_16x16x32_bf16 v[120:123], v[176:179], v[184:187], v[120:123]
	v_mfma_f32_16x16x32_bf16 v[108:111], v[168:171], v[192:195], v[108:111]
	v_mfma_f32_16x16x32_bf16 v[100:103], v[176:179], v[192:195], v[100:103]
	v_mfma_f32_16x16x32_bf16 v[92:95], v[168:171], v[200:203], v[92:95]
	v_mfma_f32_16x16x32_bf16 v[84:87], v[176:179], v[200:203], v[84:87]
	v_mfma_f32_16x16x32_bf16 v[76:79], v[168:171], v[208:211], v[76:79]
	v_mfma_f32_16x16x32_bf16 v[68:71], v[176:179], v[208:211], v[68:71]
	v_mfma_f32_16x16x32_bf16 v[124:127], v[172:175], v[188:191], v[124:127]
	v_mfma_f32_16x16x32_bf16 v[120:123], v[180:183], v[188:191], v[120:123]
	v_mfma_f32_16x16x32_bf16 v[108:111], v[172:175], v[196:199], v[108:111]
	v_mfma_f32_16x16x32_bf16 v[100:103], v[180:183], v[196:199], v[100:103]
	v_mfma_f32_16x16x32_bf16 v[92:95], v[172:175], v[204:207], v[92:95]
	v_mfma_f32_16x16x32_bf16 v[84:87], v[180:183], v[204:207], v[84:87]
	v_mfma_f32_16x16x32_bf16 v[76:79], v[172:175], v[212:215], v[76:79]
	v_mfma_f32_16x16x32_bf16 v[68:71], v[180:183], v[212:215], v[68:71]
	s_barrier
	s_setprio 1
	s_add_i32 s56, s69, s58
	v_lshl_add_u64 v[216:217], v[216:217], 0, s[20:21]
	s_mov_b32 m0, s56
	ds_read_b128 v[184:187], v153 offset:49152
	ds_read_b128 v[188:191], v153 offset:50176
	ds_read_b128 v[192:195], v153 offset:51200
	ds_read_b128 v[196:199], v153 offset:52224
	ds_read_b128 v[200:203], v153 offset:53248
	ds_read_b128 v[204:207], v153 offset:54272
	ds_read_b128 v[208:211], v153 offset:55296
	ds_read_b128 v[212:215], v153 offset:56320
	global_load_lds_dwordx4 v[216:217], off
	s_add_i32 m0, s56, 0x2000
	s_add_u32 s54, s54, 0x80080
	v_lshl_add_u64 v[216:217], v[218:219], 0, s[20:21]
	s_addc_u32 s55, s55, 0
	s_add_i32 s56, s70, s58
	global_load_lds_dwordx4 v[216:217], off
	v_lshl_add_u64 v[216:217], s[54:55], 0, v[130:131]
	s_mov_b32 m0, s56
	s_nop 0
	global_load_lds_dwordx4 v[216:217], off
	v_lshl_add_u64 v[216:217], s[54:55], 0, v[134:135]
	s_add_i32 m0, s56, 0x2000
	s_nop 0
	global_load_lds_dwordx4 v[216:217], off
	v_lshl_add_u64 v[216:217], v[220:221], 0, s[20:21]
	s_mov_b32 m0, s62
	s_nop 0
	global_load_lds_dwordx4 v[216:217], off
	v_lshl_add_u64 v[216:217], v[222:223], 0, s[20:21]
	s_mov_b32 m0, s63
	s_nop 0
	global_load_lds_dwordx4 v[216:217], off
	s_waitcnt vmcnt(8)
	s_waitcnt lgkmcnt(0)
	s_setprio 0
	s_barrier
	v_mfma_f32_16x16x32_bf16 v[56:59], v[144:147], v[184:187], v[56:59]
	v_mfma_f32_16x16x32_bf16 v[48:51], v[160:163], v[184:187], v[48:51]
	v_mfma_f32_16x16x32_bf16 v[40:43], v[144:147], v[192:195], v[40:43]
	v_mfma_f32_16x16x32_bf16 v[32:35], v[160:163], v[192:195], v[32:35]
	v_mfma_f32_16x16x32_bf16 v[24:27], v[144:147], v[200:203], v[24:27]
	v_mfma_f32_16x16x32_bf16 v[16:19], v[160:163], v[200:203], v[16:19]
	v_mfma_f32_16x16x32_bf16 v[8:11], v[144:147], v[208:211], v[8:11]
	v_mfma_f32_16x16x32_bf16 v[0:3], v[160:163], v[208:211], v[0:3]
	v_mfma_f32_16x16x32_bf16 v[56:59], v[156:159], v[188:191], v[56:59]
	v_mfma_f32_16x16x32_bf16 v[48:51], v[164:167], v[188:191], v[48:51]
	v_mfma_f32_16x16x32_bf16 v[40:43], v[156:159], v[196:199], v[40:43]
	v_mfma_f32_16x16x32_bf16 v[32:35], v[164:167], v[196:199], v[32:35]
	v_mfma_f32_16x16x32_bf16 v[24:27], v[156:159], v[204:207], v[24:27]
	v_mfma_f32_16x16x32_bf16 v[16:19], v[164:167], v[204:207], v[16:19]
	v_mfma_f32_16x16x32_bf16 v[8:11], v[156:159], v[212:215], v[8:11]
	v_mfma_f32_16x16x32_bf16 v[0:3], v[164:167], v[212:215], v[0:3]
	v_mfma_f32_16x16x32_bf16 v[60:63], v[168:171], v[184:187], v[60:63]
	v_mfma_f32_16x16x32_bf16 v[52:55], v[176:179], v[184:187], v[52:55]
	v_mfma_f32_16x16x32_bf16 v[44:47], v[168:171], v[192:195], v[44:47]
	v_mfma_f32_16x16x32_bf16 v[36:39], v[176:179], v[192:195], v[36:39]
	v_mfma_f32_16x16x32_bf16 v[28:31], v[168:171], v[200:203], v[28:31]
	v_mfma_f32_16x16x32_bf16 v[20:23], v[176:179], v[200:203], v[20:23]
	v_mfma_f32_16x16x32_bf16 v[12:15], v[168:171], v[208:211], v[12:15]
	v_mfma_f32_16x16x32_bf16 v[4:7], v[176:179], v[208:211], v[4:7]
	v_mfma_f32_16x16x32_bf16 v[60:63], v[172:175], v[188:191], v[60:63]
	v_mfma_f32_16x16x32_bf16 v[52:55], v[180:183], v[188:191], v[52:55]
	v_mfma_f32_16x16x32_bf16 v[44:47], v[172:175], v[196:199], v[44:47]
	v_mfma_f32_16x16x32_bf16 v[36:39], v[180:183], v[196:199], v[36:39]
	v_mfma_f32_16x16x32_bf16 v[28:31], v[172:175], v[204:207], v[28:31]
	v_mfma_f32_16x16x32_bf16 v[20:23], v[180:183], v[204:207], v[20:23]
	v_mfma_f32_16x16x32_bf16 v[12:15], v[172:175], v[212:215], v[12:15]
	v_mfma_f32_16x16x32_bf16 v[4:7], v[180:183], v[212:215], v[4:7]
	s_barrier
	s_setprio 1
	s_add_i32 s68, s68, 2
	s_add_u32 s47, s47, 0x100
	s_addc_u32 s67, s67, 0
	s_add_u32 s52, s52, 0x100
	s_addc_u32 s53, s53, 0
	s_cmp_gt_u32 s68, 29
	s_cbranch_scc0 .LBB0_952
	s_and_b64 vcc, exec, s[22:23]
	s_cbranch_vccz .LBB0_955
	s_barrier
	s_setprio 3

.LBB0_1053:
	s_and_b64 vcc, exec, s[16:17]
	s_cbranch_vccz .LBB0_1055
	s_barrier
	s_setprio 3

.LBB0_1137:
	ds_read_b128 v[144:147], v151
	ds_read_b128 v[156:159], v151 offset:1024
	ds_read_b128 v[160:163], v151 offset:2048
	ds_read_b128 v[164:167], v151 offset:3072
	ds_read_b128 v[168:171], v152
	ds_read_b128 v[172:175], v152 offset:1024
	ds_read_b128 v[176:179], v152 offset:2048
	ds_read_b128 v[180:183], v152 offset:3072
	s_add_u32 s34, s30, 0x100
	s_addc_u32 s35, s31, 0
	s_cmpk_eq_i32 s66, 0x54
	s_cselect_b32 s49, s11, s35
	s_cselect_b32 s48, s10, s34
	s_cselect_b32 s37, s27, s47
	s_cselect_b32 s36, s26, s46
	v_lshl_add_u64 v[216:217], s[30:31], 0, v[138:139]
	s_add_i32 m0, s53, 0xc000
	ds_read_b128 v[184:187], v153
	ds_read_b128 v[188:191], v153 offset:1024
	ds_read_b128 v[192:195], v153 offset:2048
	ds_read_b128 v[196:199], v153 offset:3072
	ds_read_b128 v[200:203], v153 offset:4096
	ds_read_b128 v[204:207], v153 offset:5120
	ds_read_b128 v[208:211], v153 offset:6144
	ds_read_b128 v[212:215], v153 offset:7168
	global_load_lds_dwordx4 v[216:217], off
	v_lshl_add_u64 v[216:217], s[30:31], 0, v[136:137]
	s_add_i32 m0, s53, 0xe000
	s_nop 0
	global_load_lds_dwordx4 v[216:217], off
	s_waitcnt vmcnt(8)
	s_waitcnt lgkmcnt(0)
	s_setprio 0
	s_barrier
	v_mfma_f32_16x16x32_bf16 v[124:127], v[144:147], v[184:187], v[124:127]
	v_mfma_f32_16x16x32_bf16 v[120:123], v[160:163], v[184:187], v[120:123]
	v_mfma_f32_16x16x32_bf16 v[108:111], v[144:147], v[192:195], v[108:111]
	v_mfma_f32_16x16x32_bf16 v[104:107], v[160:163], v[192:195], v[104:107]
	v_mfma_f32_16x16x32_bf16 v[92:95], v[144:147], v[200:203], v[92:95]
	v_mfma_f32_16x16x32_bf16 v[88:91], v[160:163], v[200:203], v[88:91]
	v_mfma_f32_16x16x32_bf16 v[76:79], v[144:147], v[208:211], v[76:79]
	v_mfma_f32_16x16x32_bf16 v[72:75], v[160:163], v[208:211], v[72:75]
	v_mfma_f32_16x16x32_bf16 v[124:127], v[156:159], v[188:191], v[124:127]
	v_mfma_f32_16x16x32_bf16 v[120:123], v[164:167], v[188:191], v[120:123]
	v_mfma_f32_16x16x32_bf16 v[108:111], v[156:159], v[196:199], v[108:111]
	v_mfma_f32_16x16x32_bf16 v[104:107], v[164:167], v[196:199], v[104:107]
	v_mfma_f32_16x16x32_bf16 v[92:95], v[156:159], v[204:207], v[92:95]
	v_mfma_f32_16x16x32_bf16 v[88:91], v[164:167], v[204:207], v[88:91]
	v_mfma_f32_16x16x32_bf16 v[76:79], v[156:159], v[212:215], v[76:79]
	v_mfma_f32_16x16x32_bf16 v[72:75], v[164:167], v[212:215], v[72:75]
	v_mfma_f32_16x16x32_bf16 v[116:119], v[168:171], v[184:187], v[116:119]
	v_mfma_f32_16x16x32_bf16 v[112:115], v[176:179], v[184:187], v[112:115]
	v_mfma_f32_16x16x32_bf16 v[100:103], v[168:171], v[192:195], v[100:103]
	v_mfma_f32_16x16x32_bf16 v[96:99], v[176:179], v[192:195], v[96:99]
	v_mfma_f32_16x16x32_bf16 v[84:87], v[168:171], v[200:203], v[84:87]
	v_mfma_f32_16x16x32_bf16 v[80:83], v[176:179], v[200:203], v[80:83]
	v_mfma_f32_16x16x32_bf16 v[68:71], v[168:171], v[208:211], v[68:71]
	v_mfma_f32_16x16x32_bf16 v[64:67], v[176:179], v[208:211], v[64:67]
	v_mfma_f32_16x16x32_bf16 v[116:119], v[172:175], v[188:191], v[116:119]
	v_mfma_f32_16x16x32_bf16 v[112:115], v[180:183], v[188:191], v[112:115]
	v_mfma_f32_16x16x32_bf16 v[100:103], v[172:175], v[196:199], v[100:103]
	v_mfma_f32_16x16x32_bf16 v[96:99], v[180:183], v[196:199], v[96:99]
	v_mfma_f32_16x16x32_bf16 v[84:87], v[172:175], v[204:207], v[84:87]
	v_mfma_f32_16x16x32_bf16 v[80:83], v[180:183], v[204:207], v[80:83]
	v_mfma_f32_16x16x32_bf16 v[68:71], v[172:175], v[212:215], v[68:71]
	v_mfma_f32_16x16x32_bf16 v[64:67], v[180:183], v[212:215], v[64:67]
	s_barrier
	s_setprio 1
	s_add_i32 s30, s60, s52
	v_lshl_add_u64 v[216:217], s[36:37], 0, v[130:131]
	s_mov_b32 m0, s30
	ds_read_b128 v[184:187], v153 offset:16384
	ds_read_b128 v[188:191], v153 offset:17408
	ds_read_b128 v[192:195], v153 offset:18432
	ds_read_b128 v[196:199], v153 offset:19456
	ds_read_b128 v[200:203], v153 offset:20480
	ds_read_b128 v[204:207], v153 offset:21504
	ds_read_b128 v[208:211], v153 offset:22528
	ds_read_b128 v[212:215], v153 offset:23552
	global_load_lds_dwordx4 v[216:217], off
	s_add_i32 m0, s30, 0x2000
	s_add_u32 s30, s36, 0x160000
	v_lshl_add_u64 v[218:219], s[36:37], 0, v[134:135]
	s_addc_u32 s31, s37, 0
	s_add_i32 s67, s61, s52
	global_load_lds_dwordx4 v[218:219], off
	v_lshl_add_u64 v[220:221], s[30:31], 0, v[130:131]
	s_mov_b32 m0, s67
	v_lshl_add_u64 v[222:223], s[48:49], 0, v[132:133]
	global_load_lds_dwordx4 v[220:221], off
	v_lshl_add_u64 v[220:221], s[30:31], 0, v[134:135]
	s_add_i32 m0, s67, 0x2000
	s_nop 0
	global_load_lds_dwordx4 v[220:221], off
	v_lshl_add_u64 v[220:221], s[48:49], 0, v[128:129]
	s_mov_b32 m0, s53
	s_nop 0
	global_load_lds_dwordx4 v[220:221], off
	s_mov_b32 m0, s54
	s_nop 0
	global_load_lds_dwordx4 v[222:223], off
	s_waitcnt vmcnt(8)
	s_waitcnt lgkmcnt(0)
	s_setprio 0
	s_barrier
	v_mfma_f32_16x16x32_bf16 v[60:63], v[144:147], v[184:187], v[60:63]
	v_mfma_f32_16x16x32_bf16 v[56:59], v[160:163], v[184:187], v[56:59]
	v_mfma_f32_16x16x32_bf16 v[44:47], v[144:147], v[192:195], v[44:47]
	v_mfma_f32_16x16x32_bf16 v[40:43], v[160:163], v[192:195], v[40:43]
	v_mfma_f32_16x16x32_bf16 v[28:31], v[144:147], v[200:203], v[28:31]
	v_mfma_f32_16x16x32_bf16 v[24:27], v[160:163], v[200:203], v[24:27]
	v_mfma_f32_16x16x32_bf16 v[12:15], v[144:147], v[208:211], v[12:15]
	v_mfma_f32_16x16x32_bf16 v[8:11], v[160:163], v[208:211], v[8:11]
	v_mfma_f32_16x16x32_bf16 v[60:63], v[156:159], v[188:191], v[60:63]
	v_mfma_f32_16x16x32_bf16 v[56:59], v[164:167], v[188:191], v[56:59]
	v_mfma_f32_16x16x32_bf16 v[44:47], v[156:159], v[196:199], v[44:47]
	v_mfma_f32_16x16x32_bf16 v[40:43], v[164:167], v[196:199], v[40:43]
	v_mfma_f32_16x16x32_bf16 v[28:31], v[156:159], v[204:207], v[28:31]
	v_mfma_f32_16x16x32_bf16 v[24:27], v[164:167], v[204:207], v[24:27]
	v_mfma_f32_16x16x32_bf16 v[12:15], v[156:159], v[212:215], v[12:15]
	v_mfma_f32_16x16x32_bf16 v[8:11], v[164:167], v[212:215], v[8:11]
	v_mfma_f32_16x16x32_bf16 v[52:55], v[168:171], v[184:187], v[52:55]
	v_mfma_f32_16x16x32_bf16 v[48:51], v[176:179], v[184:187], v[48:51]
	v_mfma_f32_16x16x32_bf16 v[36:39], v[168:171], v[192:195], v[36:39]
	v_mfma_f32_16x16x32_bf16 v[32:35], v[176:179], v[192:195], v[32:35]
	v_mfma_f32_16x16x32_bf16 v[20:23], v[168:171], v[200:203], v[20:23]
	v_mfma_f32_16x16x32_bf16 v[16:19], v[176:179], v[200:203], v[16:19]
	v_mfma_f32_16x16x32_bf16 v[4:7], v[168:171], v[208:211], v[4:7]
	v_mfma_f32_16x16x32_bf16 v[0:3], v[176:179], v[208:211], v[0:3]
	v_mfma_f32_16x16x32_bf16 v[52:55], v[172:175], v[188:191], v[52:55]
	v_mfma_f32_16x16x32_bf16 v[48:51], v[180:183], v[188:191], v[48:51]
	v_mfma_f32_16x16x32_bf16 v[36:39], v[172:175], v[196:199], v[36:39]
	v_mfma_f32_16x16x32_bf16 v[32:35], v[180:183], v[196:199], v[32:35]
	v_mfma_f32_16x16x32_bf16 v[20:23], v[172:175], v[204:207], v[20:23]
	v_mfma_f32_16x16x32_bf16 v[16:19], v[180:183], v[204:207], v[16:19]
	v_mfma_f32_16x16x32_bf16 v[4:7], v[172:175], v[212:215], v[4:7]
	v_mfma_f32_16x16x32_bf16 v[0:3], v[180:183], v[212:215], v[0:3]
	s_barrier
	s_setprio 1
	s_add_i32 s67, 0, 0x18000
	v_add_u32_e32 v155, s67, v149
	s_add_i32 s68, 0, 0x1c000
	ds_read_b128 v[144:147], v155
	ds_read_b128 v[156:159], v155 offset:1024
	ds_read_b128 v[160:163], v155 offset:2048
	ds_read_b128 v[164:167], v155 offset:3072
	v_add_u32_e32 v155, s68, v149
	ds_read_b128 v[168:171], v155
	ds_read_b128 v[172:175], v155 offset:1024
	ds_read_b128 v[176:179], v155 offset:2048
	ds_read_b128 v[180:183], v155 offset:3072
	s_add_u32 s30, s48, 0x160000
	s_addc_u32 s31, s49, 0
	s_mov_b32 m0, s55
	v_lshl_add_u64 v[224:225], s[30:31], 0, v[128:129]
	ds_read_b128 v[184:187], v153 offset:32768
	ds_read_b128 v[188:191], v153 offset:33792
	ds_read_b128 v[192:195], v153 offset:34816
	ds_read_b128 v[196:199], v153 offset:35840
	ds_read_b128 v[200:203], v153 offset:36864
	ds_read_b128 v[204:207], v153 offset:37888
	ds_read_b128 v[208:211], v153 offset:38912
	ds_read_b128 v[212:215], v153 offset:39936
	global_load_lds_dwordx4 v[224:225], off
	v_lshl_add_u64 v[224:225], s[30:31], 0, v[132:133]
	s_mov_b32 m0, s56
	s_nop 0
	global_load_lds_dwordx4 v[224:225], off
	s_waitcnt vmcnt(8)
	s_waitcnt lgkmcnt(0)
	s_setprio 0
	s_barrier
	v_mfma_f32_16x16x32_bf16 v[124:127], v[144:147], v[184:187], v[124:127]
	v_mfma_f32_16x16x32_bf16 v[120:123], v[160:163], v[184:187], v[120:123]
	v_mfma_f32_16x16x32_bf16 v[108:111], v[144:147], v[192:195], v[108:111]
	v_mfma_f32_16x16x32_bf16 v[104:107], v[160:163], v[192:195], v[104:107]
	v_mfma_f32_16x16x32_bf16 v[92:95], v[144:147], v[200:203], v[92:95]
	v_mfma_f32_16x16x32_bf16 v[88:91], v[160:163], v[200:203], v[88:91]
	v_mfma_f32_16x16x32_bf16 v[76:79], v[144:147], v[208:211], v[76:79]
	v_mfma_f32_16x16x32_bf16 v[72:75], v[160:163], v[208:211], v[72:75]
	v_mfma_f32_16x16x32_bf16 v[124:127], v[156:159], v[188:191], v[124:127]
	v_mfma_f32_16x16x32_bf16 v[120:123], v[164:167], v[188:191], v[120:123]
	v_mfma_f32_16x16x32_bf16 v[108:111], v[156:159], v[196:199], v[108:111]
	v_mfma_f32_16x16x32_bf16 v[104:107], v[164:167], v[196:199], v[104:107]
	v_mfma_f32_16x16x32_bf16 v[92:95], v[156:159], v[204:207], v[92:95]
	v_mfma_f32_16x16x32_bf16 v[88:91], v[164:167], v[204:207], v[88:91]
	v_mfma_f32_16x16x32_bf16 v[76:79], v[156:159], v[212:215], v[76:79]
	v_mfma_f32_16x16x32_bf16 v[72:75], v[164:167], v[212:215], v[72:75]
	v_mfma_f32_16x16x32_bf16 v[116:119], v[168:171], v[184:187], v[116:119]
	v_mfma_f32_16x16x32_bf16 v[112:115], v[176:179], v[184:187], v[112:115]
	v_mfma_f32_16x16x32_bf16 v[100:103], v[168:171], v[192:195], v[100:103]
	v_mfma_f32_16x16x32_bf16 v[96:99], v[176:179], v[192:195], v[96:99]
	v_mfma_f32_16x16x32_bf16 v[84:87], v[168:171], v[200:203], v[84:87]
	v_mfma_f32_16x16x32_bf16 v[80:83], v[176:179], v[200:203], v[80:83]
	v_mfma_f32_16x16x32_bf16 v[68:71], v[168:171], v[208:211], v[68:71]
	v_mfma_f32_16x16x32_bf16 v[64:67], v[176:179], v[208:211], v[64:67]
	v_mfma_f32_16x16x32_bf16 v[116:119], v[172:175], v[188:191], v[116:119]
	v_mfma_f32_16x16x32_bf16 v[112:115], v[180:183], v[188:191], v[112:115]
	v_mfma_f32_16x16x32_bf16 v[100:103], v[172:175], v[196:199], v[100:103]
	v_mfma_f32_16x16x32_bf16 v[96:99], v[180:183], v[196:199], v[96:99]
	v_mfma_f32_16x16x32_bf16 v[84:87], v[172:175], v[204:207], v[84:87]
	v_mfma_f32_16x16x32_bf16 v[80:83], v[180:183], v[204:207], v[80:83]
	v_mfma_f32_16x16x32_bf16 v[68:71], v[172:175], v[212:215], v[68:71]
	v_mfma_f32_16x16x32_bf16 v[64:67], v[180:183], v[212:215], v[64:67]
	s_barrier
	s_setprio 1
	s_add_i32 s30, s67, s52
	v_lshl_add_u64 v[216:217], v[216:217], 0, s[22:23]
	s_mov_b32 m0, s30
	ds_read_b128 v[184:187], v153 offset:49152
	ds_read_b128 v[188:191], v153 offset:50176
	ds_read_b128 v[192:195], v153 offset:51200
	ds_read_b128 v[196:199], v153 offset:52224
	ds_read_b128 v[200:203], v153 offset:53248
	ds_read_b128 v[204:207], v153 offset:54272
	ds_read_b128 v[208:211], v153 offset:55296
	ds_read_b128 v[212:215], v153 offset:56320
	global_load_lds_dwordx4 v[216:217], off
	s_add_i32 m0, s30, 0x2000
	s_add_u32 s30, s36, 0x160080
	v_lshl_add_u64 v[216:217], v[218:219], 0, s[22:23]
	s_addc_u32 s31, s37, 0
	s_add_i32 s36, s68, s52
	global_load_lds_dwordx4 v[216:217], off
	v_lshl_add_u64 v[216:217], s[30:31], 0, v[130:131]
	s_mov_b32 m0, s36
	s_nop 0
	global_load_lds_dwordx4 v[216:217], off
	v_lshl_add_u64 v[216:217], s[30:31], 0, v[134:135]
	s_add_i32 m0, s36, 0x2000
	s_nop 0
	global_load_lds_dwordx4 v[216:217], off
	v_lshl_add_u64 v[216:217], v[220:221], 0, s[22:23]
	s_mov_b32 m0, s58
	s_nop 0
	global_load_lds_dwordx4 v[216:217], off
	v_lshl_add_u64 v[216:217], v[222:223], 0, s[22:23]
	s_mov_b32 m0, s59
	s_nop 0
	global_load_lds_dwordx4 v[216:217], off
	s_waitcnt vmcnt(8)
	s_waitcnt lgkmcnt(0)
	s_setprio 0
	s_barrier
	v_mfma_f32_16x16x32_bf16 v[60:63], v[144:147], v[184:187], v[60:63]
	v_mfma_f32_16x16x32_bf16 v[56:59], v[160:163], v[184:187], v[56:59]
	v_mfma_f32_16x16x32_bf16 v[44:47], v[144:147], v[192:195], v[44:47]
	v_mfma_f32_16x16x32_bf16 v[40:43], v[160:163], v[192:195], v[40:43]
	v_mfma_f32_16x16x32_bf16 v[28:31], v[144:147], v[200:203], v[28:31]
	v_mfma_f32_16x16x32_bf16 v[24:27], v[160:163], v[200:203], v[24:27]
	v_mfma_f32_16x16x32_bf16 v[12:15], v[144:147], v[208:211], v[12:15]
	v_mfma_f32_16x16x32_bf16 v[8:11], v[160:163], v[208:211], v[8:11]
	v_mfma_f32_16x16x32_bf16 v[60:63], v[156:159], v[188:191], v[60:63]
	v_mfma_f32_16x16x32_bf16 v[56:59], v[164:167], v[188:191], v[56:59]
	v_mfma_f32_16x16x32_bf16 v[44:47], v[156:159], v[196:199], v[44:47]
	v_mfma_f32_16x16x32_bf16 v[40:43], v[164:167], v[196:199], v[40:43]
	v_mfma_f32_16x16x32_bf16 v[28:31], v[156:159], v[204:207], v[28:31]
	v_mfma_f32_16x16x32_bf16 v[24:27], v[164:167], v[204:207], v[24:27]
	v_mfma_f32_16x16x32_bf16 v[12:15], v[156:159], v[212:215], v[12:15]
	v_mfma_f32_16x16x32_bf16 v[8:11], v[164:167], v[212:215], v[8:11]
	v_mfma_f32_16x16x32_bf16 v[52:55], v[168:171], v[184:187], v[52:55]
	v_mfma_f32_16x16x32_bf16 v[48:51], v[176:179], v[184:187], v[48:51]
	v_mfma_f32_16x16x32_bf16 v[36:39], v[168:171], v[192:195], v[36:39]
	v_mfma_f32_16x16x32_bf16 v[32:35], v[176:179], v[192:195], v[32:35]
	v_mfma_f32_16x16x32_bf16 v[20:23], v[168:171], v[200:203], v[20:23]
	v_mfma_f32_16x16x32_bf16 v[16:19], v[176:179], v[200:203], v[16:19]
	v_mfma_f32_16x16x32_bf16 v[4:7], v[168:171], v[208:211], v[4:7]
	v_mfma_f32_16x16x32_bf16 v[0:3], v[176:179], v[208:211], v[0:3]
	v_mfma_f32_16x16x32_bf16 v[52:55], v[172:175], v[188:191], v[52:55]
	v_mfma_f32_16x16x32_bf16 v[48:51], v[180:183], v[188:191], v[48:51]
	v_mfma_f32_16x16x32_bf16 v[36:39], v[172:175], v[196:199], v[36:39]
	v_mfma_f32_16x16x32_bf16 v[32:35], v[180:183], v[196:199], v[32:35]
	v_mfma_f32_16x16x32_bf16 v[20:23], v[172:175], v[204:207], v[20:23]
	v_mfma_f32_16x16x32_bf16 v[16:19], v[180:183], v[204:207], v[16:19]
	v_mfma_f32_16x16x32_bf16 v[4:7], v[172:175], v[212:215], v[4:7]
	v_mfma_f32_16x16x32_bf16 v[0:3], v[180:183], v[212:215], v[0:3]
	s_barrier
	s_setprio 1
	s_add_i32 s66, s66, 2
	s_add_u32 s46, s46, 0x100
	s_addc_u32 s47, s47, 0
	s_cmpk_gt_u32 s66, 0x55
	s_mov_b64 s[30:31], s[34:35]
	s_cbranch_scc0 .LBB0_1137
	s_and_b64 vcc, exec, s[24:25]
	s_cbranch_vccz .LBB0_1140
	s_barrier
	s_setprio 3
